# proj, merge and moe_up GEMM mainloops rewritten with v_mfma_f32_16x16x32_bf16 (bf16 operands, f32 accumulate), fragment ring prefetch, saddr LDS-DMA, matching 16x16 accumulator staging
# speedup vs baseline: 1.0361x; 1.0215x over previous
.LBB0_426:
	s_xor_b64 s[4:5], s[10:11], -1
	s_and_b64 s[8:9], s[10:11], exec
	s_mov_b32 s8, 0x2608e000
	s_cselect_b32 s8, s8, 0x2788e000
	s_add_u32 s8, s2, s8
	s_addc_u32 s9, s3, 0
	s_and_b64 s[10:11], s[10:11], exec
	s_mov_b32 s10, 0x3810000
	s_cselect_b32 s10, s10, 0x4010000
	v_mov_b32_e32 v2, v195
	s_add_u32 s10, s12, s10
	s_addc_u32 s11, s13, 0
	v_readfirstlane_b32 s14, v2
	s_lshl_b32 s14, s14, 4
	s_and_b32 s26, s14, 0xfffffc00
	v_lshl_add_u64 v[0:1], s[8:9], 0, v[134:135]
	s_mov_b32 s14, m0
	s_mov_b32 m0, s26
	s_nop 0
	global_load_lds_dwordx4 v[0:1], off
	s_mov_b32 m0, s14
	s_add_i32 s24, s26, 0x8000
	v_lshl_add_u64 v[0:1], s[10:11], 0, v[136:137]
	s_mov_b32 s14, m0
	s_mov_b32 m0, s24
	s_nop 0
	global_load_lds_dwordx4 v[0:1], off
	s_mov_b32 m0, s14
	v_lshl_add_u64 v[0:1], s[8:9], 0, v[138:139]
	s_add_i32 s25, s26, 0x2000
	s_mov_b32 s14, m0
	s_mov_b32 m0, s25
	s_nop 0
	global_load_lds_dwordx4 v[0:1], off
	s_mov_b32 m0, s14
	v_lshl_add_u64 v[0:1], s[10:11], 0, v[140:141]
	s_add_i32 s27, s26, 0xa000
	s_mov_b32 s14, m0
	s_mov_b32 m0, s27
	s_nop 0
	global_load_lds_dwordx4 v[0:1], off
	s_mov_b32 m0, s14
	v_lshl_add_u64 v[0:1], s[8:9], 0, v[142:143]
	s_add_i32 s28, s26, 0x4000
	s_mov_b32 s14, m0
	s_mov_b32 m0, s28
	s_nop 0
	global_load_lds_dwordx4 v[0:1], off
	s_mov_b32 m0, s14
	v_lshl_add_u64 v[0:1], s[10:11], 0, v[144:145]
	s_add_i32 s29, s26, 0xc000
	s_mov_b32 s14, m0
	s_mov_b32 m0, s29
	s_nop 0
	global_load_lds_dwordx4 v[0:1], off
	s_mov_b32 m0, s14
	v_lshl_add_u64 v[0:1], s[8:9], 0, v[146:147]
	s_add_i32 s30, s26, 0x6000
	s_mov_b32 s14, m0
	s_mov_b32 m0, s30
	s_nop 0
	global_load_lds_dwordx4 v[0:1], off
	s_mov_b32 m0, s14
	v_lshl_add_u64 v[0:1], s[10:11], 0, v[148:149]
	s_add_i32 s31, s26, 0xe000
	s_mov_b32 s14, m0
	s_mov_b32 m0, s31
	s_nop 0
	global_load_lds_dwordx4 v[0:1], off
	s_mov_b32 m0, s14
	v_and_b32_e32 v4, 31, v2
	v_lshrrev_b32_e32 v0, 1, v2
	s_mov_b32 s14, 0x1ffff80
	v_and_or_b32 v0, v0, s14, v4
	s_add_i32 s15, s26, 0x10000
	s_add_i32 s14, s26, 0x18000
	s_add_u32 s22, s8, 0x80
	v_lshrrev_b32_e32 v3, 5, v2
	v_bfe_u32 v1, v2, 1, 3
	s_addc_u32 s23, s9, 0
	v_lshlrev_b32_e32 v153, 7, v0
	v_bitop3_b32 v0, v3, v1, 1 bitop3:0x6c
	s_add_u32 s36, s10, 0x80
	s_waitcnt vmcnt(0)
	s_barrier
	s_mov_b32 s14, m0
	v_and_b32_e32 v4, 15, v195
	v_lshrrev_b32_e32 v5, 8, v195
	v_lshl_add_u32 v5, v5, 7, v4
	v_lshlrev_b32_e32 v5, 7, v5
	v_bfe_u32 v6, v195, 4, 2
	v_bfe_u32 v7, v195, 1, 3
	v_xor_b32_e32 v6, v6, v7
	v_lshlrev_b32_e32 v6, 4, v6
	v_or_b32_e32 v168, v5, v6
	v_xor_b32_e32 v169, 64, v168
	v_bfe_u32 v7, v195, 6, 2
	v_lshl_add_u32 v7, v7, 6, v4
	v_lshlrev_b32_e32 v7, 7, v7
	v_or_b32_e32 v192, v7, v6
	v_xor_b32_e32 v204, 64, v192
	s_add_u32 s8, s8, 0x80
	s_addc_u32 s9, s9, 0
	s_add_u32 s10, s10, 0x80
	s_addc_u32 s11, s11, 0
	ds_read_b128 v[172:175], v192 offset:32768
	ds_read_b128 v[176:179], v192 offset:34816
	ds_read_b128 v[180:183], v192 offset:36864
	ds_read_b128 v[184:187], v192 offset:38912
	ds_read_b128 v[152:155], v168
	ds_read_b128 v[156:159], v168 offset:2048
	ds_read_b128 v[160:163], v168 offset:4096
	s_add_u32 m0, s26, 0x10000
	s_nop 0
	global_load_lds_dwordx4 v134, s[8:9]
	s_add_u32 m0, s26, 0x18000
	s_nop 0
	global_load_lds_dwordx4 v136, s[10:11]
	s_add_u32 m0, s26, 0x12000
	s_nop 0
	global_load_lds_dwordx4 v138, s[8:9]
	s_add_u32 m0, s26, 0x1a000
	s_nop 0
	global_load_lds_dwordx4 v140, s[10:11]
	s_add_u32 m0, s26, 0x14000
	s_nop 0
	global_load_lds_dwordx4 v142, s[8:9]
	s_add_u32 m0, s26, 0x1c000
	s_nop 0
	global_load_lds_dwordx4 v144, s[10:11]
	s_add_u32 m0, s26, 0x16000
	s_nop 0
	global_load_lds_dwordx4 v146, s[8:9]
	s_add_u32 m0, s26, 0x1e000
	s_nop 0
	global_load_lds_dwordx4 v148, s[10:11]
	s_add_u32 s8, s8, 0x80
	s_addc_u32 s9, s9, 0
	s_add_u32 s10, s10, 0x80
	s_addc_u32 s11, s11, 0
	s_waitcnt lgkmcnt(2)
	v_mfma_f32_16x16x32_bf16 v[0:3], v[152:155], v[172:175], 0
	ds_read_b128 v[164:167], v168 offset:6144
	v_mfma_f32_16x16x32_bf16 v[4:7], v[152:155], v[176:179], 0
	ds_read_b128 v[196:199], v204 offset:32768
	v_mfma_f32_16x16x32_bf16 v[8:11], v[152:155], v[180:183], 0
	v_mfma_f32_16x16x32_bf16 v[12:15], v[152:155], v[184:187], 0
	s_waitcnt lgkmcnt(3)
	v_mfma_f32_16x16x32_bf16 v[16:19], v[156:159], v[172:175], 0
	ds_read_b128 v[152:155], v168 offset:8192
	v_mfma_f32_16x16x32_bf16 v[20:23], v[156:159], v[176:179], 0
	ds_read_b128 v[200:203], v204 offset:34816
	v_mfma_f32_16x16x32_bf16 v[24:27], v[156:159], v[180:183], 0
	v_mfma_f32_16x16x32_bf16 v[28:31], v[156:159], v[184:187], 0
	s_waitcnt lgkmcnt(4)
	v_mfma_f32_16x16x32_bf16 v[32:35], v[160:163], v[172:175], 0
	ds_read_b128 v[156:159], v168 offset:10240
	v_mfma_f32_16x16x32_bf16 v[36:39], v[160:163], v[176:179], 0
	ds_read_b128 v[212:215], v204 offset:36864
	v_mfma_f32_16x16x32_bf16 v[40:43], v[160:163], v[180:183], 0
	v_mfma_f32_16x16x32_bf16 v[44:47], v[160:163], v[184:187], 0
	s_waitcnt lgkmcnt(5)
	v_mfma_f32_16x16x32_bf16 v[48:51], v[164:167], v[172:175], 0
	ds_read_b128 v[160:163], v168 offset:12288
	v_mfma_f32_16x16x32_bf16 v[52:55], v[164:167], v[176:179], 0
	ds_read_b128 v[216:219], v204 offset:38912
	v_mfma_f32_16x16x32_bf16 v[56:59], v[164:167], v[180:183], 0
	v_mfma_f32_16x16x32_bf16 v[60:63], v[164:167], v[184:187], 0
	s_waitcnt lgkmcnt(5)
	v_mfma_f32_16x16x32_bf16 v[64:67], v[152:155], v[172:175], 0
	ds_read_b128 v[164:167], v168 offset:14336
	v_mfma_f32_16x16x32_bf16 v[68:71], v[152:155], v[176:179], 0
	v_mfma_f32_16x16x32_bf16 v[72:75], v[152:155], v[180:183], 0
	v_mfma_f32_16x16x32_bf16 v[76:79], v[152:155], v[184:187], 0
	s_waitcnt lgkmcnt(4)
	v_mfma_f32_16x16x32_bf16 v[80:83], v[156:159], v[172:175], 0
	ds_read_b128 v[152:155], v169
	v_mfma_f32_16x16x32_bf16 v[84:87], v[156:159], v[176:179], 0
	v_mfma_f32_16x16x32_bf16 v[88:91], v[156:159], v[180:183], 0
	v_mfma_f32_16x16x32_bf16 v[92:95], v[156:159], v[184:187], 0
	s_waitcnt lgkmcnt(3)
	v_mfma_f32_16x16x32_bf16 v[96:99], v[160:163], v[172:175], 0
	ds_read_b128 v[156:159], v169 offset:2048
	v_mfma_f32_16x16x32_bf16 v[100:103], v[160:163], v[176:179], 0
	v_mfma_f32_16x16x32_bf16 v[104:107], v[160:163], v[180:183], 0
	v_mfma_f32_16x16x32_bf16 v[108:111], v[160:163], v[184:187], 0
	s_waitcnt lgkmcnt(2)
	v_mfma_f32_16x16x32_bf16 v[112:115], v[164:167], v[172:175], 0
	ds_read_b128 v[160:163], v169 offset:4096
	v_mfma_f32_16x16x32_bf16 v[116:119], v[164:167], v[176:179], 0
	v_mfma_f32_16x16x32_bf16 v[120:123], v[164:167], v[180:183], 0
	v_mfma_f32_16x16x32_bf16 v[124:127], v[164:167], v[184:187], 0
	s_waitcnt lgkmcnt(2)
	v_mfma_f32_16x16x32_bf16 v[0:3], v[152:155], v[196:199], v[0:3]
	ds_read_b128 v[164:167], v169 offset:6144
	v_mfma_f32_16x16x32_bf16 v[4:7], v[152:155], v[200:203], v[4:7]
	v_mfma_f32_16x16x32_bf16 v[8:11], v[152:155], v[212:215], v[8:11]
	v_mfma_f32_16x16x32_bf16 v[12:15], v[152:155], v[216:219], v[12:15]
	s_waitcnt lgkmcnt(2)
	v_mfma_f32_16x16x32_bf16 v[16:19], v[156:159], v[196:199], v[16:19]
	ds_read_b128 v[152:155], v169 offset:8192
	v_mfma_f32_16x16x32_bf16 v[20:23], v[156:159], v[200:203], v[20:23]
	v_mfma_f32_16x16x32_bf16 v[24:27], v[156:159], v[212:215], v[24:27]
	v_mfma_f32_16x16x32_bf16 v[28:31], v[156:159], v[216:219], v[28:31]
	s_waitcnt lgkmcnt(2)
	v_mfma_f32_16x16x32_bf16 v[32:35], v[160:163], v[196:199], v[32:35]
	ds_read_b128 v[156:159], v169 offset:10240
	v_mfma_f32_16x16x32_bf16 v[36:39], v[160:163], v[200:203], v[36:39]
	v_mfma_f32_16x16x32_bf16 v[40:43], v[160:163], v[212:215], v[40:43]
	v_mfma_f32_16x16x32_bf16 v[44:47], v[160:163], v[216:219], v[44:47]
	s_waitcnt lgkmcnt(2)
	v_mfma_f32_16x16x32_bf16 v[48:51], v[164:167], v[196:199], v[48:51]
	ds_read_b128 v[160:163], v169 offset:12288
	v_mfma_f32_16x16x32_bf16 v[52:55], v[164:167], v[200:203], v[52:55]
	v_mfma_f32_16x16x32_bf16 v[56:59], v[164:167], v[212:215], v[56:59]
	v_mfma_f32_16x16x32_bf16 v[60:63], v[164:167], v[216:219], v[60:63]
	s_waitcnt lgkmcnt(2)
	v_mfma_f32_16x16x32_bf16 v[64:67], v[152:155], v[196:199], v[64:67]
	ds_read_b128 v[164:167], v169 offset:14336
	v_mfma_f32_16x16x32_bf16 v[68:71], v[152:155], v[200:203], v[68:71]
	v_mfma_f32_16x16x32_bf16 v[72:75], v[152:155], v[212:215], v[72:75]
	v_mfma_f32_16x16x32_bf16 v[76:79], v[152:155], v[216:219], v[76:79]
	s_waitcnt lgkmcnt(2)
	v_mfma_f32_16x16x32_bf16 v[80:83], v[156:159], v[196:199], v[80:83]
	v_mfma_f32_16x16x32_bf16 v[84:87], v[156:159], v[200:203], v[84:87]
	v_mfma_f32_16x16x32_bf16 v[88:91], v[156:159], v[212:215], v[88:91]
	v_mfma_f32_16x16x32_bf16 v[92:95], v[156:159], v[216:219], v[92:95]
	s_waitcnt lgkmcnt(0)
	s_waitcnt vmcnt(0)
	s_barrier
	v_xor_b32_e32 v168, 0x10000, v168
	v_xor_b32_e32 v169, 0x10000, v169
	v_xor_b32_e32 v192, 0x10000, v192
	v_xor_b32_e32 v204, 0x10000, v204
	v_mfma_f32_16x16x32_bf16 v[96:99], v[160:163], v[196:199], v[96:99]
	ds_read_b128 v[152:155], v168
	ds_read_b128 v[156:159], v168 offset:2048
	s_mov_b32 m0, s26
	v_mfma_f32_16x16x32_bf16 v[100:103], v[160:163], v[200:203], v[100:103]
	global_load_lds_dwordx4 v134, s[8:9]
	v_mfma_f32_16x16x32_bf16 v[104:107], v[160:163], v[212:215], v[104:107]
	ds_read_b128 v[172:175], v192 offset:32768
	ds_read_b128 v[176:179], v192 offset:34816
	s_add_u32 m0, s26, 0x8000
	v_mfma_f32_16x16x32_bf16 v[108:111], v[160:163], v[216:219], v[108:111]
	global_load_lds_dwordx4 v136, s[10:11]
	v_mfma_f32_16x16x32_bf16 v[112:115], v[164:167], v[196:199], v[112:115]
	ds_read_b128 v[160:163], v168 offset:4096
	s_add_u32 m0, s26, 0x2000
	v_mfma_f32_16x16x32_bf16 v[116:119], v[164:167], v[200:203], v[116:119]
	global_load_lds_dwordx4 v138, s[8:9]
	ds_read_b128 v[180:183], v192 offset:36864
	ds_read_b128 v[184:187], v192 offset:38912
	v_mfma_f32_16x16x32_bf16 v[120:123], v[164:167], v[212:215], v[120:123]
	s_add_u32 m0, s26, 0xa000
	v_mfma_f32_16x16x32_bf16 v[124:127], v[164:167], v[216:219], v[124:127]
	global_load_lds_dwordx4 v140, s[10:11]
	s_waitcnt lgkmcnt(4)
	v_mfma_f32_16x16x32_bf16 v[0:3], v[152:155], v[172:175], v[0:3]
	ds_read_b128 v[164:167], v168 offset:6144
	s_waitcnt lgkmcnt(4)
	v_mfma_f32_16x16x32_bf16 v[4:7], v[152:155], v[176:179], v[4:7]
	ds_read_b128 v[196:199], v204 offset:32768
	s_waitcnt lgkmcnt(3)
	v_mfma_f32_16x16x32_bf16 v[8:11], v[152:155], v[180:183], v[8:11]
	s_waitcnt lgkmcnt(2)
	v_mfma_f32_16x16x32_bf16 v[12:15], v[152:155], v[184:187], v[12:15]
	v_mfma_f32_16x16x32_bf16 v[16:19], v[156:159], v[172:175], v[16:19]
	ds_read_b128 v[152:155], v168 offset:8192
	v_mfma_f32_16x16x32_bf16 v[20:23], v[156:159], v[176:179], v[20:23]
	ds_read_b128 v[200:203], v204 offset:34816
	v_mfma_f32_16x16x32_bf16 v[24:27], v[156:159], v[180:183], v[24:27]
	v_mfma_f32_16x16x32_bf16 v[28:31], v[156:159], v[184:187], v[28:31]
	v_mfma_f32_16x16x32_bf16 v[32:35], v[160:163], v[172:175], v[32:35]
	ds_read_b128 v[156:159], v168 offset:10240
	v_mfma_f32_16x16x32_bf16 v[36:39], v[160:163], v[176:179], v[36:39]
	ds_read_b128 v[212:215], v204 offset:36864
	v_mfma_f32_16x16x32_bf16 v[40:43], v[160:163], v[180:183], v[40:43]
	s_add_u32 m0, s26, 0x4000
	v_mfma_f32_16x16x32_bf16 v[44:47], v[160:163], v[184:187], v[44:47]
	global_load_lds_dwordx4 v142, s[8:9]
	s_waitcnt lgkmcnt(5)
	v_mfma_f32_16x16x32_bf16 v[48:51], v[164:167], v[172:175], v[48:51]
	ds_read_b128 v[160:163], v168 offset:12288
	v_mfma_f32_16x16x32_bf16 v[52:55], v[164:167], v[176:179], v[52:55]
	ds_read_b128 v[216:219], v204 offset:38912
	v_mfma_f32_16x16x32_bf16 v[56:59], v[164:167], v[180:183], v[56:59]
	s_add_u32 m0, s26, 0xc000
	v_mfma_f32_16x16x32_bf16 v[60:63], v[164:167], v[184:187], v[60:63]
	global_load_lds_dwordx4 v144, s[10:11]
	s_waitcnt lgkmcnt(5)
	v_mfma_f32_16x16x32_bf16 v[64:67], v[152:155], v[172:175], v[64:67]
	ds_read_b128 v[164:167], v168 offset:14336
	v_mfma_f32_16x16x32_bf16 v[68:71], v[152:155], v[176:179], v[68:71]
	v_mfma_f32_16x16x32_bf16 v[72:75], v[152:155], v[180:183], v[72:75]
	s_add_u32 m0, s26, 0x6000
	v_mfma_f32_16x16x32_bf16 v[76:79], v[152:155], v[184:187], v[76:79]
	global_load_lds_dwordx4 v146, s[8:9]
	s_waitcnt lgkmcnt(4)
	v_mfma_f32_16x16x32_bf16 v[80:83], v[156:159], v[172:175], v[80:83]
	ds_read_b128 v[152:155], v169
	v_mfma_f32_16x16x32_bf16 v[84:87], v[156:159], v[176:179], v[84:87]
	v_mfma_f32_16x16x32_bf16 v[88:91], v[156:159], v[180:183], v[88:91]
	s_add_u32 m0, s26, 0xe000
	v_mfma_f32_16x16x32_bf16 v[92:95], v[156:159], v[184:187], v[92:95]
	global_load_lds_dwordx4 v148, s[10:11]
	s_add_u32 s8, s8, 0x80
	s_addc_u32 s9, s9, 0
	s_add_u32 s10, s10, 0x80
	s_addc_u32 s11, s11, 0
	s_waitcnt lgkmcnt(3)
	v_mfma_f32_16x16x32_bf16 v[96:99], v[160:163], v[172:175], v[96:99]
	ds_read_b128 v[156:159], v169 offset:2048
	v_mfma_f32_16x16x32_bf16 v[100:103], v[160:163], v[176:179], v[100:103]
	v_mfma_f32_16x16x32_bf16 v[104:107], v[160:163], v[180:183], v[104:107]
	v_mfma_f32_16x16x32_bf16 v[108:111], v[160:163], v[184:187], v[108:111]
	s_waitcnt lgkmcnt(2)
	v_mfma_f32_16x16x32_bf16 v[112:115], v[164:167], v[172:175], v[112:115]
	ds_read_b128 v[160:163], v169 offset:4096
	v_mfma_f32_16x16x32_bf16 v[116:119], v[164:167], v[176:179], v[116:119]
	v_mfma_f32_16x16x32_bf16 v[120:123], v[164:167], v[180:183], v[120:123]
	v_mfma_f32_16x16x32_bf16 v[124:127], v[164:167], v[184:187], v[124:127]
	s_waitcnt lgkmcnt(2)
	v_mfma_f32_16x16x32_bf16 v[0:3], v[152:155], v[196:199], v[0:3]
	ds_read_b128 v[164:167], v169 offset:6144
	v_mfma_f32_16x16x32_bf16 v[4:7], v[152:155], v[200:203], v[4:7]
	v_mfma_f32_16x16x32_bf16 v[8:11], v[152:155], v[212:215], v[8:11]
	v_mfma_f32_16x16x32_bf16 v[12:15], v[152:155], v[216:219], v[12:15]
	s_waitcnt lgkmcnt(2)
	v_mfma_f32_16x16x32_bf16 v[16:19], v[156:159], v[196:199], v[16:19]
	ds_read_b128 v[152:155], v169 offset:8192
	v_mfma_f32_16x16x32_bf16 v[20:23], v[156:159], v[200:203], v[20:23]
	v_mfma_f32_16x16x32_bf16 v[24:27], v[156:159], v[212:215], v[24:27]
	v_mfma_f32_16x16x32_bf16 v[28:31], v[156:159], v[216:219], v[28:31]
	s_waitcnt lgkmcnt(2)
	v_mfma_f32_16x16x32_bf16 v[32:35], v[160:163], v[196:199], v[32:35]
	ds_read_b128 v[156:159], v169 offset:10240
	v_mfma_f32_16x16x32_bf16 v[36:39], v[160:163], v[200:203], v[36:39]
	v_mfma_f32_16x16x32_bf16 v[40:43], v[160:163], v[212:215], v[40:43]
	v_mfma_f32_16x16x32_bf16 v[44:47], v[160:163], v[216:219], v[44:47]
	s_waitcnt lgkmcnt(2)
	v_mfma_f32_16x16x32_bf16 v[48:51], v[164:167], v[196:199], v[48:51]
	ds_read_b128 v[160:163], v169 offset:12288
	v_mfma_f32_16x16x32_bf16 v[52:55], v[164:167], v[200:203], v[52:55]
	v_mfma_f32_16x16x32_bf16 v[56:59], v[164:167], v[212:215], v[56:59]
	v_mfma_f32_16x16x32_bf16 v[60:63], v[164:167], v[216:219], v[60:63]
	s_waitcnt lgkmcnt(2)
	v_mfma_f32_16x16x32_bf16 v[64:67], v[152:155], v[196:199], v[64:67]
	ds_read_b128 v[164:167], v169 offset:14336
	v_mfma_f32_16x16x32_bf16 v[68:71], v[152:155], v[200:203], v[68:71]
	v_mfma_f32_16x16x32_bf16 v[72:75], v[152:155], v[212:215], v[72:75]
	v_mfma_f32_16x16x32_bf16 v[76:79], v[152:155], v[216:219], v[76:79]
	s_waitcnt lgkmcnt(2)
	v_mfma_f32_16x16x32_bf16 v[80:83], v[156:159], v[196:199], v[80:83]
	v_mfma_f32_16x16x32_bf16 v[84:87], v[156:159], v[200:203], v[84:87]
	v_mfma_f32_16x16x32_bf16 v[88:91], v[156:159], v[212:215], v[88:91]
	v_mfma_f32_16x16x32_bf16 v[92:95], v[156:159], v[216:219], v[92:95]
	s_waitcnt lgkmcnt(0)
	s_waitcnt vmcnt(0)
	s_barrier
	v_xor_b32_e32 v168, 0x10000, v168
	v_xor_b32_e32 v169, 0x10000, v169
	v_xor_b32_e32 v192, 0x10000, v192
	v_xor_b32_e32 v204, 0x10000, v204
	v_mfma_f32_16x16x32_bf16 v[96:99], v[160:163], v[196:199], v[96:99]
	ds_read_b128 v[152:155], v168
	ds_read_b128 v[156:159], v168 offset:2048
	s_add_u32 m0, s26, 0x10000
	v_mfma_f32_16x16x32_bf16 v[100:103], v[160:163], v[200:203], v[100:103]
	global_load_lds_dwordx4 v134, s[8:9]
	v_mfma_f32_16x16x32_bf16 v[104:107], v[160:163], v[212:215], v[104:107]
	ds_read_b128 v[172:175], v192 offset:32768
	ds_read_b128 v[176:179], v192 offset:34816
	s_add_u32 m0, s26, 0x18000
	v_mfma_f32_16x16x32_bf16 v[108:111], v[160:163], v[216:219], v[108:111]
	global_load_lds_dwordx4 v136, s[10:11]
	v_mfma_f32_16x16x32_bf16 v[112:115], v[164:167], v[196:199], v[112:115]
	ds_read_b128 v[160:163], v168 offset:4096
	s_add_u32 m0, s26, 0x12000
	v_mfma_f32_16x16x32_bf16 v[116:119], v[164:167], v[200:203], v[116:119]
	global_load_lds_dwordx4 v138, s[8:9]
	ds_read_b128 v[180:183], v192 offset:36864
	ds_read_b128 v[184:187], v192 offset:38912
	v_mfma_f32_16x16x32_bf16 v[120:123], v[164:167], v[212:215], v[120:123]
	s_add_u32 m0, s26, 0x1a000
	v_mfma_f32_16x16x32_bf16 v[124:127], v[164:167], v[216:219], v[124:127]
	global_load_lds_dwordx4 v140, s[10:11]
	s_waitcnt lgkmcnt(4)
	v_mfma_f32_16x16x32_bf16 v[0:3], v[152:155], v[172:175], v[0:3]
	ds_read_b128 v[164:167], v168 offset:6144
	s_waitcnt lgkmcnt(4)
	v_mfma_f32_16x16x32_bf16 v[4:7], v[152:155], v[176:179], v[4:7]
	ds_read_b128 v[196:199], v204 offset:32768
	s_waitcnt lgkmcnt(3)
	v_mfma_f32_16x16x32_bf16 v[8:11], v[152:155], v[180:183], v[8:11]
	s_waitcnt lgkmcnt(2)
	v_mfma_f32_16x16x32_bf16 v[12:15], v[152:155], v[184:187], v[12:15]
	v_mfma_f32_16x16x32_bf16 v[16:19], v[156:159], v[172:175], v[16:19]
	ds_read_b128 v[152:155], v168 offset:8192
	v_mfma_f32_16x16x32_bf16 v[20:23], v[156:159], v[176:179], v[20:23]
	ds_read_b128 v[200:203], v204 offset:34816
	v_mfma_f32_16x16x32_bf16 v[24:27], v[156:159], v[180:183], v[24:27]
	v_mfma_f32_16x16x32_bf16 v[28:31], v[156:159], v[184:187], v[28:31]
	v_mfma_f32_16x16x32_bf16 v[32:35], v[160:163], v[172:175], v[32:35]
	ds_read_b128 v[156:159], v168 offset:10240
	v_mfma_f32_16x16x32_bf16 v[36:39], v[160:163], v[176:179], v[36:39]
	ds_read_b128 v[212:215], v204 offset:36864
	v_mfma_f32_16x16x32_bf16 v[40:43], v[160:163], v[180:183], v[40:43]
	s_add_u32 m0, s26, 0x14000
	v_mfma_f32_16x16x32_bf16 v[44:47], v[160:163], v[184:187], v[44:47]
	global_load_lds_dwordx4 v142, s[8:9]
	s_waitcnt lgkmcnt(5)
	v_mfma_f32_16x16x32_bf16 v[48:51], v[164:167], v[172:175], v[48:51]
	ds_read_b128 v[160:163], v168 offset:12288
	v_mfma_f32_16x16x32_bf16 v[52:55], v[164:167], v[176:179], v[52:55]
	ds_read_b128 v[216:219], v204 offset:38912
	v_mfma_f32_16x16x32_bf16 v[56:59], v[164:167], v[180:183], v[56:59]
	s_add_u32 m0, s26, 0x1c000
	v_mfma_f32_16x16x32_bf16 v[60:63], v[164:167], v[184:187], v[60:63]
	global_load_lds_dwordx4 v144, s[10:11]
	s_waitcnt lgkmcnt(5)
	v_mfma_f32_16x16x32_bf16 v[64:67], v[152:155], v[172:175], v[64:67]
	ds_read_b128 v[164:167], v168 offset:14336
	v_mfma_f32_16x16x32_bf16 v[68:71], v[152:155], v[176:179], v[68:71]
	v_mfma_f32_16x16x32_bf16 v[72:75], v[152:155], v[180:183], v[72:75]
	s_add_u32 m0, s26, 0x16000
	v_mfma_f32_16x16x32_bf16 v[76:79], v[152:155], v[184:187], v[76:79]
	global_load_lds_dwordx4 v146, s[8:9]
	s_waitcnt lgkmcnt(4)
	v_mfma_f32_16x16x32_bf16 v[80:83], v[156:159], v[172:175], v[80:83]
	ds_read_b128 v[152:155], v169
	v_mfma_f32_16x16x32_bf16 v[84:87], v[156:159], v[176:179], v[84:87]
	v_mfma_f32_16x16x32_bf16 v[88:91], v[156:159], v[180:183], v[88:91]
	s_add_u32 m0, s26, 0x1e000
	v_mfma_f32_16x16x32_bf16 v[92:95], v[156:159], v[184:187], v[92:95]
	global_load_lds_dwordx4 v148, s[10:11]
	s_add_u32 s8, s8, 0x80
	s_addc_u32 s9, s9, 0
	s_add_u32 s10, s10, 0x80
	s_addc_u32 s11, s11, 0
	s_waitcnt lgkmcnt(3)
	v_mfma_f32_16x16x32_bf16 v[96:99], v[160:163], v[172:175], v[96:99]
	ds_read_b128 v[156:159], v169 offset:2048
	v_mfma_f32_16x16x32_bf16 v[100:103], v[160:163], v[176:179], v[100:103]
	v_mfma_f32_16x16x32_bf16 v[104:107], v[160:163], v[180:183], v[104:107]
	v_mfma_f32_16x16x32_bf16 v[108:111], v[160:163], v[184:187], v[108:111]
	s_waitcnt lgkmcnt(2)
	v_mfma_f32_16x16x32_bf16 v[112:115], v[164:167], v[172:175], v[112:115]
	ds_read_b128 v[160:163], v169 offset:4096
	v_mfma_f32_16x16x32_bf16 v[116:119], v[164:167], v[176:179], v[116:119]
	v_mfma_f32_16x16x32_bf16 v[120:123], v[164:167], v[180:183], v[120:123]
	v_mfma_f32_16x16x32_bf16 v[124:127], v[164:167], v[184:187], v[124:127]
	s_waitcnt lgkmcnt(2)
	v_mfma_f32_16x16x32_bf16 v[0:3], v[152:155], v[196:199], v[0:3]
	ds_read_b128 v[164:167], v169 offset:6144
	v_mfma_f32_16x16x32_bf16 v[4:7], v[152:155], v[200:203], v[4:7]
	v_mfma_f32_16x16x32_bf16 v[8:11], v[152:155], v[212:215], v[8:11]
	v_mfma_f32_16x16x32_bf16 v[12:15], v[152:155], v[216:219], v[12:15]
	s_waitcnt lgkmcnt(2)
	v_mfma_f32_16x16x32_bf16 v[16:19], v[156:159], v[196:199], v[16:19]
	ds_read_b128 v[152:155], v169 offset:8192
	v_mfma_f32_16x16x32_bf16 v[20:23], v[156:159], v[200:203], v[20:23]
	v_mfma_f32_16x16x32_bf16 v[24:27], v[156:159], v[212:215], v[24:27]
	v_mfma_f32_16x16x32_bf16 v[28:31], v[156:159], v[216:219], v[28:31]
	s_waitcnt lgkmcnt(2)
	v_mfma_f32_16x16x32_bf16 v[32:35], v[160:163], v[196:199], v[32:35]
	ds_read_b128 v[156:159], v169 offset:10240
	v_mfma_f32_16x16x32_bf16 v[36:39], v[160:163], v[200:203], v[36:39]
	v_mfma_f32_16x16x32_bf16 v[40:43], v[160:163], v[212:215], v[40:43]
	v_mfma_f32_16x16x32_bf16 v[44:47], v[160:163], v[216:219], v[44:47]
	s_waitcnt lgkmcnt(2)
	v_mfma_f32_16x16x32_bf16 v[48:51], v[164:167], v[196:199], v[48:51]
	ds_read_b128 v[160:163], v169 offset:12288
	v_mfma_f32_16x16x32_bf16 v[52:55], v[164:167], v[200:203], v[52:55]
	v_mfma_f32_16x16x32_bf16 v[56:59], v[164:167], v[212:215], v[56:59]
	v_mfma_f32_16x16x32_bf16 v[60:63], v[164:167], v[216:219], v[60:63]
	s_waitcnt lgkmcnt(2)
	v_mfma_f32_16x16x32_bf16 v[64:67], v[152:155], v[196:199], v[64:67]
	ds_read_b128 v[164:167], v169 offset:14336
	v_mfma_f32_16x16x32_bf16 v[68:71], v[152:155], v[200:203], v[68:71]
	v_mfma_f32_16x16x32_bf16 v[72:75], v[152:155], v[212:215], v[72:75]
	v_mfma_f32_16x16x32_bf16 v[76:79], v[152:155], v[216:219], v[76:79]
	s_waitcnt lgkmcnt(2)
	v_mfma_f32_16x16x32_bf16 v[80:83], v[156:159], v[196:199], v[80:83]
	v_mfma_f32_16x16x32_bf16 v[84:87], v[156:159], v[200:203], v[84:87]
	v_mfma_f32_16x16x32_bf16 v[88:91], v[156:159], v[212:215], v[88:91]
	v_mfma_f32_16x16x32_bf16 v[92:95], v[156:159], v[216:219], v[92:95]
	s_waitcnt lgkmcnt(0)
	s_waitcnt vmcnt(0)
	s_barrier
	v_xor_b32_e32 v168, 0x10000, v168
	v_xor_b32_e32 v169, 0x10000, v169
	v_xor_b32_e32 v192, 0x10000, v192
	v_xor_b32_e32 v204, 0x10000, v204
	v_mfma_f32_16x16x32_bf16 v[96:99], v[160:163], v[196:199], v[96:99]
	ds_read_b128 v[152:155], v168
	ds_read_b128 v[156:159], v168 offset:2048
	s_mov_b32 m0, s26
	v_mfma_f32_16x16x32_bf16 v[100:103], v[160:163], v[200:203], v[100:103]
	global_load_lds_dwordx4 v134, s[8:9]
	v_mfma_f32_16x16x32_bf16 v[104:107], v[160:163], v[212:215], v[104:107]
	ds_read_b128 v[172:175], v192 offset:32768
	ds_read_b128 v[176:179], v192 offset:34816
	s_add_u32 m0, s26, 0x8000
	v_mfma_f32_16x16x32_bf16 v[108:111], v[160:163], v[216:219], v[108:111]
	global_load_lds_dwordx4 v136, s[10:11]
	v_mfma_f32_16x16x32_bf16 v[112:115], v[164:167], v[196:199], v[112:115]
	ds_read_b128 v[160:163], v168 offset:4096
	s_add_u32 m0, s26, 0x2000
	v_mfma_f32_16x16x32_bf16 v[116:119], v[164:167], v[200:203], v[116:119]
	global_load_lds_dwordx4 v138, s[8:9]
	ds_read_b128 v[180:183], v192 offset:36864
	ds_read_b128 v[184:187], v192 offset:38912
	v_mfma_f32_16x16x32_bf16 v[120:123], v[164:167], v[212:215], v[120:123]
	s_add_u32 m0, s26, 0xa000
	v_mfma_f32_16x16x32_bf16 v[124:127], v[164:167], v[216:219], v[124:127]
	global_load_lds_dwordx4 v140, s[10:11]
	s_waitcnt lgkmcnt(4)
	v_mfma_f32_16x16x32_bf16 v[0:3], v[152:155], v[172:175], v[0:3]
	ds_read_b128 v[164:167], v168 offset:6144
	s_waitcnt lgkmcnt(4)
	v_mfma_f32_16x16x32_bf16 v[4:7], v[152:155], v[176:179], v[4:7]
	ds_read_b128 v[196:199], v204 offset:32768
	s_waitcnt lgkmcnt(3)
	v_mfma_f32_16x16x32_bf16 v[8:11], v[152:155], v[180:183], v[8:11]
	s_waitcnt lgkmcnt(2)
	v_mfma_f32_16x16x32_bf16 v[12:15], v[152:155], v[184:187], v[12:15]
	v_mfma_f32_16x16x32_bf16 v[16:19], v[156:159], v[172:175], v[16:19]
	ds_read_b128 v[152:155], v168 offset:8192
	v_mfma_f32_16x16x32_bf16 v[20:23], v[156:159], v[176:179], v[20:23]
	ds_read_b128 v[200:203], v204 offset:34816
	v_mfma_f32_16x16x32_bf16 v[24:27], v[156:159], v[180:183], v[24:27]
	v_mfma_f32_16x16x32_bf16 v[28:31], v[156:159], v[184:187], v[28:31]
	v_mfma_f32_16x16x32_bf16 v[32:35], v[160:163], v[172:175], v[32:35]
	ds_read_b128 v[156:159], v168 offset:10240
	v_mfma_f32_16x16x32_bf16 v[36:39], v[160:163], v[176:179], v[36:39]
	ds_read_b128 v[212:215], v204 offset:36864
	v_mfma_f32_16x16x32_bf16 v[40:43], v[160:163], v[180:183], v[40:43]
	s_add_u32 m0, s26, 0x4000
	v_mfma_f32_16x16x32_bf16 v[44:47], v[160:163], v[184:187], v[44:47]
	global_load_lds_dwordx4 v142, s[8:9]
	s_waitcnt lgkmcnt(5)
	v_mfma_f32_16x16x32_bf16 v[48:51], v[164:167], v[172:175], v[48:51]
	ds_read_b128 v[160:163], v168 offset:12288
	v_mfma_f32_16x16x32_bf16 v[52:55], v[164:167], v[176:179], v[52:55]
	ds_read_b128 v[216:219], v204 offset:38912
	v_mfma_f32_16x16x32_bf16 v[56:59], v[164:167], v[180:183], v[56:59]
	s_add_u32 m0, s26, 0xc000
	v_mfma_f32_16x16x32_bf16 v[60:63], v[164:167], v[184:187], v[60:63]
	global_load_lds_dwordx4 v144, s[10:11]
	s_waitcnt lgkmcnt(5)
	v_mfma_f32_16x16x32_bf16 v[64:67], v[152:155], v[172:175], v[64:67]
	ds_read_b128 v[164:167], v168 offset:14336
	v_mfma_f32_16x16x32_bf16 v[68:71], v[152:155], v[176:179], v[68:71]
	v_mfma_f32_16x16x32_bf16 v[72:75], v[152:155], v[180:183], v[72:75]
	s_add_u32 m0, s26, 0x6000
	v_mfma_f32_16x16x32_bf16 v[76:79], v[152:155], v[184:187], v[76:79]
	global_load_lds_dwordx4 v146, s[8:9]
	s_waitcnt lgkmcnt(4)
	v_mfma_f32_16x16x32_bf16 v[80:83], v[156:159], v[172:175], v[80:83]
	ds_read_b128 v[152:155], v169
	v_mfma_f32_16x16x32_bf16 v[84:87], v[156:159], v[176:179], v[84:87]
	v_mfma_f32_16x16x32_bf16 v[88:91], v[156:159], v[180:183], v[88:91]
	s_add_u32 m0, s26, 0xe000
	v_mfma_f32_16x16x32_bf16 v[92:95], v[156:159], v[184:187], v[92:95]
	global_load_lds_dwordx4 v148, s[10:11]
	s_add_u32 s8, s8, 0x80
	s_addc_u32 s9, s9, 0
	s_add_u32 s10, s10, 0x80
	s_addc_u32 s11, s11, 0
	s_waitcnt lgkmcnt(3)
	v_mfma_f32_16x16x32_bf16 v[96:99], v[160:163], v[172:175], v[96:99]
	ds_read_b128 v[156:159], v169 offset:2048
	v_mfma_f32_16x16x32_bf16 v[100:103], v[160:163], v[176:179], v[100:103]
	v_mfma_f32_16x16x32_bf16 v[104:107], v[160:163], v[180:183], v[104:107]
	v_mfma_f32_16x16x32_bf16 v[108:111], v[160:163], v[184:187], v[108:111]
	s_waitcnt lgkmcnt(2)
	v_mfma_f32_16x16x32_bf16 v[112:115], v[164:167], v[172:175], v[112:115]
	ds_read_b128 v[160:163], v169 offset:4096
	v_mfma_f32_16x16x32_bf16 v[116:119], v[164:167], v[176:179], v[116:119]
	v_mfma_f32_16x16x32_bf16 v[120:123], v[164:167], v[180:183], v[120:123]
	v_mfma_f32_16x16x32_bf16 v[124:127], v[164:167], v[184:187], v[124:127]
	s_waitcnt lgkmcnt(2)
	v_mfma_f32_16x16x32_bf16 v[0:3], v[152:155], v[196:199], v[0:3]
	ds_read_b128 v[164:167], v169 offset:6144
	v_mfma_f32_16x16x32_bf16 v[4:7], v[152:155], v[200:203], v[4:7]
	v_mfma_f32_16x16x32_bf16 v[8:11], v[152:155], v[212:215], v[8:11]
	v_mfma_f32_16x16x32_bf16 v[12:15], v[152:155], v[216:219], v[12:15]
	s_waitcnt lgkmcnt(2)
	v_mfma_f32_16x16x32_bf16 v[16:19], v[156:159], v[196:199], v[16:19]
	ds_read_b128 v[152:155], v169 offset:8192
	v_mfma_f32_16x16x32_bf16 v[20:23], v[156:159], v[200:203], v[20:23]
	v_mfma_f32_16x16x32_bf16 v[24:27], v[156:159], v[212:215], v[24:27]
	v_mfma_f32_16x16x32_bf16 v[28:31], v[156:159], v[216:219], v[28:31]
	s_waitcnt lgkmcnt(2)
	v_mfma_f32_16x16x32_bf16 v[32:35], v[160:163], v[196:199], v[32:35]
	ds_read_b128 v[156:159], v169 offset:10240
	v_mfma_f32_16x16x32_bf16 v[36:39], v[160:163], v[200:203], v[36:39]
	v_mfma_f32_16x16x32_bf16 v[40:43], v[160:163], v[212:215], v[40:43]
	v_mfma_f32_16x16x32_bf16 v[44:47], v[160:163], v[216:219], v[44:47]
	s_waitcnt lgkmcnt(2)
	v_mfma_f32_16x16x32_bf16 v[48:51], v[164:167], v[196:199], v[48:51]
	ds_read_b128 v[160:163], v169 offset:12288
	v_mfma_f32_16x16x32_bf16 v[52:55], v[164:167], v[200:203], v[52:55]
	v_mfma_f32_16x16x32_bf16 v[56:59], v[164:167], v[212:215], v[56:59]
	v_mfma_f32_16x16x32_bf16 v[60:63], v[164:167], v[216:219], v[60:63]
	s_waitcnt lgkmcnt(2)
	v_mfma_f32_16x16x32_bf16 v[64:67], v[152:155], v[196:199], v[64:67]
	ds_read_b128 v[164:167], v169 offset:14336
	v_mfma_f32_16x16x32_bf16 v[68:71], v[152:155], v[200:203], v[68:71]
	v_mfma_f32_16x16x32_bf16 v[72:75], v[152:155], v[212:215], v[72:75]
	v_mfma_f32_16x16x32_bf16 v[76:79], v[152:155], v[216:219], v[76:79]
	s_waitcnt lgkmcnt(2)
	v_mfma_f32_16x16x32_bf16 v[80:83], v[156:159], v[196:199], v[80:83]
	v_mfma_f32_16x16x32_bf16 v[84:87], v[156:159], v[200:203], v[84:87]
	v_mfma_f32_16x16x32_bf16 v[88:91], v[156:159], v[212:215], v[88:91]
	v_mfma_f32_16x16x32_bf16 v[92:95], v[156:159], v[216:219], v[92:95]
	s_waitcnt lgkmcnt(0)
	s_waitcnt vmcnt(0)
	s_barrier
	v_xor_b32_e32 v168, 0x10000, v168
	v_xor_b32_e32 v169, 0x10000, v169
	v_xor_b32_e32 v192, 0x10000, v192
	v_xor_b32_e32 v204, 0x10000, v204
	v_mfma_f32_16x16x32_bf16 v[96:99], v[160:163], v[196:199], v[96:99]
	ds_read_b128 v[152:155], v168
	ds_read_b128 v[156:159], v168 offset:2048
	s_add_u32 m0, s26, 0x10000
	v_mfma_f32_16x16x32_bf16 v[100:103], v[160:163], v[200:203], v[100:103]
	global_load_lds_dwordx4 v134, s[8:9]
	v_mfma_f32_16x16x32_bf16 v[104:107], v[160:163], v[212:215], v[104:107]
	ds_read_b128 v[172:175], v192 offset:32768
	ds_read_b128 v[176:179], v192 offset:34816
	s_add_u32 m0, s26, 0x18000
	v_mfma_f32_16x16x32_bf16 v[108:111], v[160:163], v[216:219], v[108:111]
	global_load_lds_dwordx4 v136, s[10:11]
	v_mfma_f32_16x16x32_bf16 v[112:115], v[164:167], v[196:199], v[112:115]
	ds_read_b128 v[160:163], v168 offset:4096
	s_add_u32 m0, s26, 0x12000
	v_mfma_f32_16x16x32_bf16 v[116:119], v[164:167], v[200:203], v[116:119]
	global_load_lds_dwordx4 v138, s[8:9]
	ds_read_b128 v[180:183], v192 offset:36864
	ds_read_b128 v[184:187], v192 offset:38912
	v_mfma_f32_16x16x32_bf16 v[120:123], v[164:167], v[212:215], v[120:123]
	s_add_u32 m0, s26, 0x1a000
	v_mfma_f32_16x16x32_bf16 v[124:127], v[164:167], v[216:219], v[124:127]
	global_load_lds_dwordx4 v140, s[10:11]
	s_waitcnt lgkmcnt(4)
	v_mfma_f32_16x16x32_bf16 v[0:3], v[152:155], v[172:175], v[0:3]
	ds_read_b128 v[164:167], v168 offset:6144
	s_waitcnt lgkmcnt(4)
	v_mfma_f32_16x16x32_bf16 v[4:7], v[152:155], v[176:179], v[4:7]
	ds_read_b128 v[196:199], v204 offset:32768
	s_waitcnt lgkmcnt(3)
	v_mfma_f32_16x16x32_bf16 v[8:11], v[152:155], v[180:183], v[8:11]
	s_waitcnt lgkmcnt(2)
	v_mfma_f32_16x16x32_bf16 v[12:15], v[152:155], v[184:187], v[12:15]
	v_mfma_f32_16x16x32_bf16 v[16:19], v[156:159], v[172:175], v[16:19]
	ds_read_b128 v[152:155], v168 offset:8192
	v_mfma_f32_16x16x32_bf16 v[20:23], v[156:159], v[176:179], v[20:23]
	ds_read_b128 v[200:203], v204 offset:34816
	v_mfma_f32_16x16x32_bf16 v[24:27], v[156:159], v[180:183], v[24:27]
	v_mfma_f32_16x16x32_bf16 v[28:31], v[156:159], v[184:187], v[28:31]
	v_mfma_f32_16x16x32_bf16 v[32:35], v[160:163], v[172:175], v[32:35]
	ds_read_b128 v[156:159], v168 offset:10240
	v_mfma_f32_16x16x32_bf16 v[36:39], v[160:163], v[176:179], v[36:39]
	ds_read_b128 v[212:215], v204 offset:36864
	v_mfma_f32_16x16x32_bf16 v[40:43], v[160:163], v[180:183], v[40:43]
	s_add_u32 m0, s26, 0x14000
	v_mfma_f32_16x16x32_bf16 v[44:47], v[160:163], v[184:187], v[44:47]
	global_load_lds_dwordx4 v142, s[8:9]
	s_waitcnt lgkmcnt(5)
	v_mfma_f32_16x16x32_bf16 v[48:51], v[164:167], v[172:175], v[48:51]
	ds_read_b128 v[160:163], v168 offset:12288
	v_mfma_f32_16x16x32_bf16 v[52:55], v[164:167], v[176:179], v[52:55]
	ds_read_b128 v[216:219], v204 offset:38912
	v_mfma_f32_16x16x32_bf16 v[56:59], v[164:167], v[180:183], v[56:59]
	s_add_u32 m0, s26, 0x1c000
	v_mfma_f32_16x16x32_bf16 v[60:63], v[164:167], v[184:187], v[60:63]
	global_load_lds_dwordx4 v144, s[10:11]
	s_waitcnt lgkmcnt(5)
	v_mfma_f32_16x16x32_bf16 v[64:67], v[152:155], v[172:175], v[64:67]
	ds_read_b128 v[164:167], v168 offset:14336
	v_mfma_f32_16x16x32_bf16 v[68:71], v[152:155], v[176:179], v[68:71]
	v_mfma_f32_16x16x32_bf16 v[72:75], v[152:155], v[180:183], v[72:75]
	s_add_u32 m0, s26, 0x16000
	v_mfma_f32_16x16x32_bf16 v[76:79], v[152:155], v[184:187], v[76:79]
	global_load_lds_dwordx4 v146, s[8:9]
	s_waitcnt lgkmcnt(4)
	v_mfma_f32_16x16x32_bf16 v[80:83], v[156:159], v[172:175], v[80:83]
	ds_read_b128 v[152:155], v169
	v_mfma_f32_16x16x32_bf16 v[84:87], v[156:159], v[176:179], v[84:87]
	v_mfma_f32_16x16x32_bf16 v[88:91], v[156:159], v[180:183], v[88:91]
	s_add_u32 m0, s26, 0x1e000
	v_mfma_f32_16x16x32_bf16 v[92:95], v[156:159], v[184:187], v[92:95]
	global_load_lds_dwordx4 v148, s[10:11]
	s_add_u32 s8, s8, 0x80
	s_addc_u32 s9, s9, 0
	s_add_u32 s10, s10, 0x80
	s_addc_u32 s11, s11, 0
	s_waitcnt lgkmcnt(3)
	v_mfma_f32_16x16x32_bf16 v[96:99], v[160:163], v[172:175], v[96:99]
	ds_read_b128 v[156:159], v169 offset:2048
	v_mfma_f32_16x16x32_bf16 v[100:103], v[160:163], v[176:179], v[100:103]
	v_mfma_f32_16x16x32_bf16 v[104:107], v[160:163], v[180:183], v[104:107]
	v_mfma_f32_16x16x32_bf16 v[108:111], v[160:163], v[184:187], v[108:111]
	s_waitcnt lgkmcnt(2)
	v_mfma_f32_16x16x32_bf16 v[112:115], v[164:167], v[172:175], v[112:115]
	ds_read_b128 v[160:163], v169 offset:4096
	v_mfma_f32_16x16x32_bf16 v[116:119], v[164:167], v[176:179], v[116:119]
	v_mfma_f32_16x16x32_bf16 v[120:123], v[164:167], v[180:183], v[120:123]
	v_mfma_f32_16x16x32_bf16 v[124:127], v[164:167], v[184:187], v[124:127]
	s_waitcnt lgkmcnt(2)
	v_mfma_f32_16x16x32_bf16 v[0:3], v[152:155], v[196:199], v[0:3]
	ds_read_b128 v[164:167], v169 offset:6144
	v_mfma_f32_16x16x32_bf16 v[4:7], v[152:155], v[200:203], v[4:7]
	v_mfma_f32_16x16x32_bf16 v[8:11], v[152:155], v[212:215], v[8:11]
	v_mfma_f32_16x16x32_bf16 v[12:15], v[152:155], v[216:219], v[12:15]
	s_waitcnt lgkmcnt(2)
	v_mfma_f32_16x16x32_bf16 v[16:19], v[156:159], v[196:199], v[16:19]
	ds_read_b128 v[152:155], v169 offset:8192
	v_mfma_f32_16x16x32_bf16 v[20:23], v[156:159], v[200:203], v[20:23]
	v_mfma_f32_16x16x32_bf16 v[24:27], v[156:159], v[212:215], v[24:27]
	v_mfma_f32_16x16x32_bf16 v[28:31], v[156:159], v[216:219], v[28:31]
	s_waitcnt lgkmcnt(2)
	v_mfma_f32_16x16x32_bf16 v[32:35], v[160:163], v[196:199], v[32:35]
	ds_read_b128 v[156:159], v169 offset:10240
	v_mfma_f32_16x16x32_bf16 v[36:39], v[160:163], v[200:203], v[36:39]
	v_mfma_f32_16x16x32_bf16 v[40:43], v[160:163], v[212:215], v[40:43]
	v_mfma_f32_16x16x32_bf16 v[44:47], v[160:163], v[216:219], v[44:47]
	s_waitcnt lgkmcnt(2)
	v_mfma_f32_16x16x32_bf16 v[48:51], v[164:167], v[196:199], v[48:51]
	ds_read_b128 v[160:163], v169 offset:12288
	v_mfma_f32_16x16x32_bf16 v[52:55], v[164:167], v[200:203], v[52:55]
	v_mfma_f32_16x16x32_bf16 v[56:59], v[164:167], v[212:215], v[56:59]
	v_mfma_f32_16x16x32_bf16 v[60:63], v[164:167], v[216:219], v[60:63]
	s_waitcnt lgkmcnt(2)
	v_mfma_f32_16x16x32_bf16 v[64:67], v[152:155], v[196:199], v[64:67]
	ds_read_b128 v[164:167], v169 offset:14336
	v_mfma_f32_16x16x32_bf16 v[68:71], v[152:155], v[200:203], v[68:71]
	v_mfma_f32_16x16x32_bf16 v[72:75], v[152:155], v[212:215], v[72:75]
	v_mfma_f32_16x16x32_bf16 v[76:79], v[152:155], v[216:219], v[76:79]
	s_waitcnt lgkmcnt(2)
	v_mfma_f32_16x16x32_bf16 v[80:83], v[156:159], v[196:199], v[80:83]
	v_mfma_f32_16x16x32_bf16 v[84:87], v[156:159], v[200:203], v[84:87]
	v_mfma_f32_16x16x32_bf16 v[88:91], v[156:159], v[212:215], v[88:91]
	v_mfma_f32_16x16x32_bf16 v[92:95], v[156:159], v[216:219], v[92:95]
	s_waitcnt lgkmcnt(0)
	s_waitcnt vmcnt(0)
	s_barrier
	v_xor_b32_e32 v168, 0x10000, v168
	v_xor_b32_e32 v169, 0x10000, v169
	v_xor_b32_e32 v192, 0x10000, v192
	v_xor_b32_e32 v204, 0x10000, v204
	v_mfma_f32_16x16x32_bf16 v[96:99], v[160:163], v[196:199], v[96:99]
	ds_read_b128 v[152:155], v168
	ds_read_b128 v[156:159], v168 offset:2048
	s_mov_b32 m0, s26
	v_mfma_f32_16x16x32_bf16 v[100:103], v[160:163], v[200:203], v[100:103]
	global_load_lds_dwordx4 v134, s[8:9]
	v_mfma_f32_16x16x32_bf16 v[104:107], v[160:163], v[212:215], v[104:107]
	ds_read_b128 v[172:175], v192 offset:32768
	ds_read_b128 v[176:179], v192 offset:34816
	s_add_u32 m0, s26, 0x8000
	v_mfma_f32_16x16x32_bf16 v[108:111], v[160:163], v[216:219], v[108:111]
	global_load_lds_dwordx4 v136, s[10:11]
	v_mfma_f32_16x16x32_bf16 v[112:115], v[164:167], v[196:199], v[112:115]
	ds_read_b128 v[160:163], v168 offset:4096
	s_add_u32 m0, s26, 0x2000
	v_mfma_f32_16x16x32_bf16 v[116:119], v[164:167], v[200:203], v[116:119]
	global_load_lds_dwordx4 v138, s[8:9]
	ds_read_b128 v[180:183], v192 offset:36864
	ds_read_b128 v[184:187], v192 offset:38912
	v_mfma_f32_16x16x32_bf16 v[120:123], v[164:167], v[212:215], v[120:123]
	s_add_u32 m0, s26, 0xa000
	v_mfma_f32_16x16x32_bf16 v[124:127], v[164:167], v[216:219], v[124:127]
	global_load_lds_dwordx4 v140, s[10:11]
	s_waitcnt lgkmcnt(4)
	v_mfma_f32_16x16x32_bf16 v[0:3], v[152:155], v[172:175], v[0:3]
	ds_read_b128 v[164:167], v168 offset:6144
	s_waitcnt lgkmcnt(4)
	v_mfma_f32_16x16x32_bf16 v[4:7], v[152:155], v[176:179], v[4:7]
	ds_read_b128 v[196:199], v204 offset:32768
	s_waitcnt lgkmcnt(3)
	v_mfma_f32_16x16x32_bf16 v[8:11], v[152:155], v[180:183], v[8:11]
	s_waitcnt lgkmcnt(2)
	v_mfma_f32_16x16x32_bf16 v[12:15], v[152:155], v[184:187], v[12:15]
	v_mfma_f32_16x16x32_bf16 v[16:19], v[156:159], v[172:175], v[16:19]
	ds_read_b128 v[152:155], v168 offset:8192
	v_mfma_f32_16x16x32_bf16 v[20:23], v[156:159], v[176:179], v[20:23]
	ds_read_b128 v[200:203], v204 offset:34816
	v_mfma_f32_16x16x32_bf16 v[24:27], v[156:159], v[180:183], v[24:27]
	v_mfma_f32_16x16x32_bf16 v[28:31], v[156:159], v[184:187], v[28:31]
	v_mfma_f32_16x16x32_bf16 v[32:35], v[160:163], v[172:175], v[32:35]
	ds_read_b128 v[156:159], v168 offset:10240
	v_mfma_f32_16x16x32_bf16 v[36:39], v[160:163], v[176:179], v[36:39]
	ds_read_b128 v[212:215], v204 offset:36864
	v_mfma_f32_16x16x32_bf16 v[40:43], v[160:163], v[180:183], v[40:43]
	s_add_u32 m0, s26, 0x4000
	v_mfma_f32_16x16x32_bf16 v[44:47], v[160:163], v[184:187], v[44:47]
	global_load_lds_dwordx4 v142, s[8:9]
	s_waitcnt lgkmcnt(5)
	v_mfma_f32_16x16x32_bf16 v[48:51], v[164:167], v[172:175], v[48:51]
	ds_read_b128 v[160:163], v168 offset:12288
	v_mfma_f32_16x16x32_bf16 v[52:55], v[164:167], v[176:179], v[52:55]
	ds_read_b128 v[216:219], v204 offset:38912
	v_mfma_f32_16x16x32_bf16 v[56:59], v[164:167], v[180:183], v[56:59]
	s_add_u32 m0, s26, 0xc000
	v_mfma_f32_16x16x32_bf16 v[60:63], v[164:167], v[184:187], v[60:63]
	global_load_lds_dwordx4 v144, s[10:11]
	s_waitcnt lgkmcnt(5)
	v_mfma_f32_16x16x32_bf16 v[64:67], v[152:155], v[172:175], v[64:67]
	ds_read_b128 v[164:167], v168 offset:14336
	v_mfma_f32_16x16x32_bf16 v[68:71], v[152:155], v[176:179], v[68:71]
	v_mfma_f32_16x16x32_bf16 v[72:75], v[152:155], v[180:183], v[72:75]
	s_add_u32 m0, s26, 0x6000
	v_mfma_f32_16x16x32_bf16 v[76:79], v[152:155], v[184:187], v[76:79]
	global_load_lds_dwordx4 v146, s[8:9]
	s_waitcnt lgkmcnt(4)
	v_mfma_f32_16x16x32_bf16 v[80:83], v[156:159], v[172:175], v[80:83]
	ds_read_b128 v[152:155], v169
	v_mfma_f32_16x16x32_bf16 v[84:87], v[156:159], v[176:179], v[84:87]
	v_mfma_f32_16x16x32_bf16 v[88:91], v[156:159], v[180:183], v[88:91]
	s_add_u32 m0, s26, 0xe000
	v_mfma_f32_16x16x32_bf16 v[92:95], v[156:159], v[184:187], v[92:95]
	global_load_lds_dwordx4 v148, s[10:11]
	s_add_u32 s8, s8, 0x80
	s_addc_u32 s9, s9, 0
	s_add_u32 s10, s10, 0x80
	s_addc_u32 s11, s11, 0
	s_waitcnt lgkmcnt(3)
	v_mfma_f32_16x16x32_bf16 v[96:99], v[160:163], v[172:175], v[96:99]
	ds_read_b128 v[156:159], v169 offset:2048
	v_mfma_f32_16x16x32_bf16 v[100:103], v[160:163], v[176:179], v[100:103]
	v_mfma_f32_16x16x32_bf16 v[104:107], v[160:163], v[180:183], v[104:107]
	v_mfma_f32_16x16x32_bf16 v[108:111], v[160:163], v[184:187], v[108:111]
	s_waitcnt lgkmcnt(2)
	v_mfma_f32_16x16x32_bf16 v[112:115], v[164:167], v[172:175], v[112:115]
	ds_read_b128 v[160:163], v169 offset:4096
	v_mfma_f32_16x16x32_bf16 v[116:119], v[164:167], v[176:179], v[116:119]
	v_mfma_f32_16x16x32_bf16 v[120:123], v[164:167], v[180:183], v[120:123]
	v_mfma_f32_16x16x32_bf16 v[124:127], v[164:167], v[184:187], v[124:127]
	s_waitcnt lgkmcnt(2)
	v_mfma_f32_16x16x32_bf16 v[0:3], v[152:155], v[196:199], v[0:3]
	ds_read_b128 v[164:167], v169 offset:6144
	v_mfma_f32_16x16x32_bf16 v[4:7], v[152:155], v[200:203], v[4:7]
	v_mfma_f32_16x16x32_bf16 v[8:11], v[152:155], v[212:215], v[8:11]
	v_mfma_f32_16x16x32_bf16 v[12:15], v[152:155], v[216:219], v[12:15]
	s_waitcnt lgkmcnt(2)
	v_mfma_f32_16x16x32_bf16 v[16:19], v[156:159], v[196:199], v[16:19]
	ds_read_b128 v[152:155], v169 offset:8192
	v_mfma_f32_16x16x32_bf16 v[20:23], v[156:159], v[200:203], v[20:23]
	v_mfma_f32_16x16x32_bf16 v[24:27], v[156:159], v[212:215], v[24:27]
	v_mfma_f32_16x16x32_bf16 v[28:31], v[156:159], v[216:219], v[28:31]
	s_waitcnt lgkmcnt(2)
	v_mfma_f32_16x16x32_bf16 v[32:35], v[160:163], v[196:199], v[32:35]
	ds_read_b128 v[156:159], v169 offset:10240
	v_mfma_f32_16x16x32_bf16 v[36:39], v[160:163], v[200:203], v[36:39]
	v_mfma_f32_16x16x32_bf16 v[40:43], v[160:163], v[212:215], v[40:43]
	v_mfma_f32_16x16x32_bf16 v[44:47], v[160:163], v[216:219], v[44:47]
	s_waitcnt lgkmcnt(2)
	v_mfma_f32_16x16x32_bf16 v[48:51], v[164:167], v[196:199], v[48:51]
	ds_read_b128 v[160:163], v169 offset:12288
	v_mfma_f32_16x16x32_bf16 v[52:55], v[164:167], v[200:203], v[52:55]
	v_mfma_f32_16x16x32_bf16 v[56:59], v[164:167], v[212:215], v[56:59]
	v_mfma_f32_16x16x32_bf16 v[60:63], v[164:167], v[216:219], v[60:63]
	s_waitcnt lgkmcnt(2)
	v_mfma_f32_16x16x32_bf16 v[64:67], v[152:155], v[196:199], v[64:67]
	ds_read_b128 v[164:167], v169 offset:14336
	v_mfma_f32_16x16x32_bf16 v[68:71], v[152:155], v[200:203], v[68:71]
	v_mfma_f32_16x16x32_bf16 v[72:75], v[152:155], v[212:215], v[72:75]
	v_mfma_f32_16x16x32_bf16 v[76:79], v[152:155], v[216:219], v[76:79]
	s_waitcnt lgkmcnt(2)
	v_mfma_f32_16x16x32_bf16 v[80:83], v[156:159], v[196:199], v[80:83]
	v_mfma_f32_16x16x32_bf16 v[84:87], v[156:159], v[200:203], v[84:87]
	v_mfma_f32_16x16x32_bf16 v[88:91], v[156:159], v[212:215], v[88:91]
	v_mfma_f32_16x16x32_bf16 v[92:95], v[156:159], v[216:219], v[92:95]
	s_waitcnt lgkmcnt(0)
	s_waitcnt vmcnt(0)
	s_barrier
	v_xor_b32_e32 v168, 0x10000, v168
	v_xor_b32_e32 v169, 0x10000, v169
	v_xor_b32_e32 v192, 0x10000, v192
	v_xor_b32_e32 v204, 0x10000, v204
	v_mfma_f32_16x16x32_bf16 v[96:99], v[160:163], v[196:199], v[96:99]
	ds_read_b128 v[152:155], v168
	ds_read_b128 v[156:159], v168 offset:2048
	s_add_u32 m0, s26, 0x10000
	v_mfma_f32_16x16x32_bf16 v[100:103], v[160:163], v[200:203], v[100:103]
	global_load_lds_dwordx4 v134, s[8:9]
	v_mfma_f32_16x16x32_bf16 v[104:107], v[160:163], v[212:215], v[104:107]
	ds_read_b128 v[172:175], v192 offset:32768
	ds_read_b128 v[176:179], v192 offset:34816
	s_add_u32 m0, s26, 0x18000
	v_mfma_f32_16x16x32_bf16 v[108:111], v[160:163], v[216:219], v[108:111]
	global_load_lds_dwordx4 v136, s[10:11]
	v_mfma_f32_16x16x32_bf16 v[112:115], v[164:167], v[196:199], v[112:115]
	ds_read_b128 v[160:163], v168 offset:4096
	s_add_u32 m0, s26, 0x12000
	v_mfma_f32_16x16x32_bf16 v[116:119], v[164:167], v[200:203], v[116:119]
	global_load_lds_dwordx4 v138, s[8:9]
	ds_read_b128 v[180:183], v192 offset:36864
	ds_read_b128 v[184:187], v192 offset:38912
	v_mfma_f32_16x16x32_bf16 v[120:123], v[164:167], v[212:215], v[120:123]
	s_add_u32 m0, s26, 0x1a000
	v_mfma_f32_16x16x32_bf16 v[124:127], v[164:167], v[216:219], v[124:127]
	global_load_lds_dwordx4 v140, s[10:11]
	s_waitcnt lgkmcnt(4)
	v_mfma_f32_16x16x32_bf16 v[0:3], v[152:155], v[172:175], v[0:3]
	ds_read_b128 v[164:167], v168 offset:6144
	s_waitcnt lgkmcnt(4)
	v_mfma_f32_16x16x32_bf16 v[4:7], v[152:155], v[176:179], v[4:7]
	ds_read_b128 v[196:199], v204 offset:32768
	s_waitcnt lgkmcnt(3)
	v_mfma_f32_16x16x32_bf16 v[8:11], v[152:155], v[180:183], v[8:11]
	s_waitcnt lgkmcnt(2)
	v_mfma_f32_16x16x32_bf16 v[12:15], v[152:155], v[184:187], v[12:15]
	v_mfma_f32_16x16x32_bf16 v[16:19], v[156:159], v[172:175], v[16:19]
	ds_read_b128 v[152:155], v168 offset:8192
	v_mfma_f32_16x16x32_bf16 v[20:23], v[156:159], v[176:179], v[20:23]
	ds_read_b128 v[200:203], v204 offset:34816
	v_mfma_f32_16x16x32_bf16 v[24:27], v[156:159], v[180:183], v[24:27]
	v_mfma_f32_16x16x32_bf16 v[28:31], v[156:159], v[184:187], v[28:31]
	v_mfma_f32_16x16x32_bf16 v[32:35], v[160:163], v[172:175], v[32:35]
	ds_read_b128 v[156:159], v168 offset:10240
	v_mfma_f32_16x16x32_bf16 v[36:39], v[160:163], v[176:179], v[36:39]
	ds_read_b128 v[212:215], v204 offset:36864
	v_mfma_f32_16x16x32_bf16 v[40:43], v[160:163], v[180:183], v[40:43]
	s_add_u32 m0, s26, 0x14000
	v_mfma_f32_16x16x32_bf16 v[44:47], v[160:163], v[184:187], v[44:47]
	global_load_lds_dwordx4 v142, s[8:9]
	s_waitcnt lgkmcnt(5)
	v_mfma_f32_16x16x32_bf16 v[48:51], v[164:167], v[172:175], v[48:51]
	ds_read_b128 v[160:163], v168 offset:12288
	v_mfma_f32_16x16x32_bf16 v[52:55], v[164:167], v[176:179], v[52:55]
	ds_read_b128 v[216:219], v204 offset:38912
	v_mfma_f32_16x16x32_bf16 v[56:59], v[164:167], v[180:183], v[56:59]
	s_add_u32 m0, s26, 0x1c000
	v_mfma_f32_16x16x32_bf16 v[60:63], v[164:167], v[184:187], v[60:63]
	global_load_lds_dwordx4 v144, s[10:11]
	s_waitcnt lgkmcnt(5)
	v_mfma_f32_16x16x32_bf16 v[64:67], v[152:155], v[172:175], v[64:67]
	ds_read_b128 v[164:167], v168 offset:14336
	v_mfma_f32_16x16x32_bf16 v[68:71], v[152:155], v[176:179], v[68:71]
	v_mfma_f32_16x16x32_bf16 v[72:75], v[152:155], v[180:183], v[72:75]
	s_add_u32 m0, s26, 0x16000
	v_mfma_f32_16x16x32_bf16 v[76:79], v[152:155], v[184:187], v[76:79]
	global_load_lds_dwordx4 v146, s[8:9]
	s_waitcnt lgkmcnt(4)
	v_mfma_f32_16x16x32_bf16 v[80:83], v[156:159], v[172:175], v[80:83]
	ds_read_b128 v[152:155], v169
	v_mfma_f32_16x16x32_bf16 v[84:87], v[156:159], v[176:179], v[84:87]
	v_mfma_f32_16x16x32_bf16 v[88:91], v[156:159], v[180:183], v[88:91]
	s_add_u32 m0, s26, 0x1e000
	v_mfma_f32_16x16x32_bf16 v[92:95], v[156:159], v[184:187], v[92:95]
	global_load_lds_dwordx4 v148, s[10:11]
	s_add_u32 s8, s8, 0x80
	s_addc_u32 s9, s9, 0
	s_add_u32 s10, s10, 0x80
	s_addc_u32 s11, s11, 0
	s_waitcnt lgkmcnt(3)
	v_mfma_f32_16x16x32_bf16 v[96:99], v[160:163], v[172:175], v[96:99]
	ds_read_b128 v[156:159], v169 offset:2048
	v_mfma_f32_16x16x32_bf16 v[100:103], v[160:163], v[176:179], v[100:103]
	v_mfma_f32_16x16x32_bf16 v[104:107], v[160:163], v[180:183], v[104:107]
	v_mfma_f32_16x16x32_bf16 v[108:111], v[160:163], v[184:187], v[108:111]
	s_waitcnt lgkmcnt(2)
	v_mfma_f32_16x16x32_bf16 v[112:115], v[164:167], v[172:175], v[112:115]
	ds_read_b128 v[160:163], v169 offset:4096
	v_mfma_f32_16x16x32_bf16 v[116:119], v[164:167], v[176:179], v[116:119]
	v_mfma_f32_16x16x32_bf16 v[120:123], v[164:167], v[180:183], v[120:123]
	v_mfma_f32_16x16x32_bf16 v[124:127], v[164:167], v[184:187], v[124:127]
	s_waitcnt lgkmcnt(2)
	v_mfma_f32_16x16x32_bf16 v[0:3], v[152:155], v[196:199], v[0:3]
	ds_read_b128 v[164:167], v169 offset:6144
	v_mfma_f32_16x16x32_bf16 v[4:7], v[152:155], v[200:203], v[4:7]
	v_mfma_f32_16x16x32_bf16 v[8:11], v[152:155], v[212:215], v[8:11]
	v_mfma_f32_16x16x32_bf16 v[12:15], v[152:155], v[216:219], v[12:15]
	s_waitcnt lgkmcnt(2)
	v_mfma_f32_16x16x32_bf16 v[16:19], v[156:159], v[196:199], v[16:19]
	ds_read_b128 v[152:155], v169 offset:8192
	v_mfma_f32_16x16x32_bf16 v[20:23], v[156:159], v[200:203], v[20:23]
	v_mfma_f32_16x16x32_bf16 v[24:27], v[156:159], v[212:215], v[24:27]
	v_mfma_f32_16x16x32_bf16 v[28:31], v[156:159], v[216:219], v[28:31]
	s_waitcnt lgkmcnt(2)
	v_mfma_f32_16x16x32_bf16 v[32:35], v[160:163], v[196:199], v[32:35]
	ds_read_b128 v[156:159], v169 offset:10240
	v_mfma_f32_16x16x32_bf16 v[36:39], v[160:163], v[200:203], v[36:39]
	v_mfma_f32_16x16x32_bf16 v[40:43], v[160:163], v[212:215], v[40:43]
	v_mfma_f32_16x16x32_bf16 v[44:47], v[160:163], v[216:219], v[44:47]
	s_waitcnt lgkmcnt(2)
	v_mfma_f32_16x16x32_bf16 v[48:51], v[164:167], v[196:199], v[48:51]
	ds_read_b128 v[160:163], v169 offset:12288
	v_mfma_f32_16x16x32_bf16 v[52:55], v[164:167], v[200:203], v[52:55]
	v_mfma_f32_16x16x32_bf16 v[56:59], v[164:167], v[212:215], v[56:59]
	v_mfma_f32_16x16x32_bf16 v[60:63], v[164:167], v[216:219], v[60:63]
	s_waitcnt lgkmcnt(2)
	v_mfma_f32_16x16x32_bf16 v[64:67], v[152:155], v[196:199], v[64:67]
	ds_read_b128 v[164:167], v169 offset:14336
	v_mfma_f32_16x16x32_bf16 v[68:71], v[152:155], v[200:203], v[68:71]
	v_mfma_f32_16x16x32_bf16 v[72:75], v[152:155], v[212:215], v[72:75]
	v_mfma_f32_16x16x32_bf16 v[76:79], v[152:155], v[216:219], v[76:79]
	s_waitcnt lgkmcnt(2)
	v_mfma_f32_16x16x32_bf16 v[80:83], v[156:159], v[196:199], v[80:83]
	v_mfma_f32_16x16x32_bf16 v[84:87], v[156:159], v[200:203], v[84:87]
	v_mfma_f32_16x16x32_bf16 v[88:91], v[156:159], v[212:215], v[88:91]
	v_mfma_f32_16x16x32_bf16 v[92:95], v[156:159], v[216:219], v[92:95]
	s_waitcnt lgkmcnt(0)
	s_waitcnt vmcnt(0)
	s_barrier
	v_xor_b32_e32 v168, 0x10000, v168
	v_xor_b32_e32 v169, 0x10000, v169
	v_xor_b32_e32 v192, 0x10000, v192
	v_xor_b32_e32 v204, 0x10000, v204
	v_mfma_f32_16x16x32_bf16 v[96:99], v[160:163], v[196:199], v[96:99]
	ds_read_b128 v[152:155], v168
	ds_read_b128 v[156:159], v168 offset:2048
	s_mov_b32 m0, s26
	v_mfma_f32_16x16x32_bf16 v[100:103], v[160:163], v[200:203], v[100:103]
	global_load_lds_dwordx4 v134, s[8:9]
	v_mfma_f32_16x16x32_bf16 v[104:107], v[160:163], v[212:215], v[104:107]
	ds_read_b128 v[172:175], v192 offset:32768
	ds_read_b128 v[176:179], v192 offset:34816
	s_add_u32 m0, s26, 0x8000
	v_mfma_f32_16x16x32_bf16 v[108:111], v[160:163], v[216:219], v[108:111]
	global_load_lds_dwordx4 v136, s[10:11]
	v_mfma_f32_16x16x32_bf16 v[112:115], v[164:167], v[196:199], v[112:115]
	ds_read_b128 v[160:163], v168 offset:4096
	s_add_u32 m0, s26, 0x2000
	v_mfma_f32_16x16x32_bf16 v[116:119], v[164:167], v[200:203], v[116:119]
	global_load_lds_dwordx4 v138, s[8:9]
	ds_read_b128 v[180:183], v192 offset:36864
	ds_read_b128 v[184:187], v192 offset:38912
	v_mfma_f32_16x16x32_bf16 v[120:123], v[164:167], v[212:215], v[120:123]
	s_add_u32 m0, s26, 0xa000
	v_mfma_f32_16x16x32_bf16 v[124:127], v[164:167], v[216:219], v[124:127]
	global_load_lds_dwordx4 v140, s[10:11]
	s_waitcnt lgkmcnt(4)
	v_mfma_f32_16x16x32_bf16 v[0:3], v[152:155], v[172:175], v[0:3]
	ds_read_b128 v[164:167], v168 offset:6144
	s_waitcnt lgkmcnt(4)
	v_mfma_f32_16x16x32_bf16 v[4:7], v[152:155], v[176:179], v[4:7]
	ds_read_b128 v[196:199], v204 offset:32768
	s_waitcnt lgkmcnt(3)
	v_mfma_f32_16x16x32_bf16 v[8:11], v[152:155], v[180:183], v[8:11]
	s_waitcnt lgkmcnt(2)
	v_mfma_f32_16x16x32_bf16 v[12:15], v[152:155], v[184:187], v[12:15]
	v_mfma_f32_16x16x32_bf16 v[16:19], v[156:159], v[172:175], v[16:19]
	ds_read_b128 v[152:155], v168 offset:8192
	v_mfma_f32_16x16x32_bf16 v[20:23], v[156:159], v[176:179], v[20:23]
	ds_read_b128 v[200:203], v204 offset:34816
	v_mfma_f32_16x16x32_bf16 v[24:27], v[156:159], v[180:183], v[24:27]
	v_mfma_f32_16x16x32_bf16 v[28:31], v[156:159], v[184:187], v[28:31]
	v_mfma_f32_16x16x32_bf16 v[32:35], v[160:163], v[172:175], v[32:35]
	ds_read_b128 v[156:159], v168 offset:10240
	v_mfma_f32_16x16x32_bf16 v[36:39], v[160:163], v[176:179], v[36:39]
	ds_read_b128 v[212:215], v204 offset:36864
	v_mfma_f32_16x16x32_bf16 v[40:43], v[160:163], v[180:183], v[40:43]
	s_add_u32 m0, s26, 0x4000
	v_mfma_f32_16x16x32_bf16 v[44:47], v[160:163], v[184:187], v[44:47]
	global_load_lds_dwordx4 v142, s[8:9]
	s_waitcnt lgkmcnt(5)
	v_mfma_f32_16x16x32_bf16 v[48:51], v[164:167], v[172:175], v[48:51]
	ds_read_b128 v[160:163], v168 offset:12288
	v_mfma_f32_16x16x32_bf16 v[52:55], v[164:167], v[176:179], v[52:55]
	ds_read_b128 v[216:219], v204 offset:38912
	v_mfma_f32_16x16x32_bf16 v[56:59], v[164:167], v[180:183], v[56:59]
	s_add_u32 m0, s26, 0xc000
	v_mfma_f32_16x16x32_bf16 v[60:63], v[164:167], v[184:187], v[60:63]
	global_load_lds_dwordx4 v144, s[10:11]
	s_waitcnt lgkmcnt(5)
	v_mfma_f32_16x16x32_bf16 v[64:67], v[152:155], v[172:175], v[64:67]
	ds_read_b128 v[164:167], v168 offset:14336
	v_mfma_f32_16x16x32_bf16 v[68:71], v[152:155], v[176:179], v[68:71]
	v_mfma_f32_16x16x32_bf16 v[72:75], v[152:155], v[180:183], v[72:75]
	s_add_u32 m0, s26, 0x6000
	v_mfma_f32_16x16x32_bf16 v[76:79], v[152:155], v[184:187], v[76:79]
	global_load_lds_dwordx4 v146, s[8:9]
	s_waitcnt lgkmcnt(4)
	v_mfma_f32_16x16x32_bf16 v[80:83], v[156:159], v[172:175], v[80:83]
	ds_read_b128 v[152:155], v169
	v_mfma_f32_16x16x32_bf16 v[84:87], v[156:159], v[176:179], v[84:87]
	v_mfma_f32_16x16x32_bf16 v[88:91], v[156:159], v[180:183], v[88:91]
	s_add_u32 m0, s26, 0xe000
	v_mfma_f32_16x16x32_bf16 v[92:95], v[156:159], v[184:187], v[92:95]
	global_load_lds_dwordx4 v148, s[10:11]
	s_add_u32 s8, s8, 0x80
	s_addc_u32 s9, s9, 0
	s_add_u32 s10, s10, 0x80
	s_addc_u32 s11, s11, 0
	s_waitcnt lgkmcnt(3)
	v_mfma_f32_16x16x32_bf16 v[96:99], v[160:163], v[172:175], v[96:99]
	ds_read_b128 v[156:159], v169 offset:2048
	v_mfma_f32_16x16x32_bf16 v[100:103], v[160:163], v[176:179], v[100:103]
	v_mfma_f32_16x16x32_bf16 v[104:107], v[160:163], v[180:183], v[104:107]
	v_mfma_f32_16x16x32_bf16 v[108:111], v[160:163], v[184:187], v[108:111]
	s_waitcnt lgkmcnt(2)
	v_mfma_f32_16x16x32_bf16 v[112:115], v[164:167], v[172:175], v[112:115]
	ds_read_b128 v[160:163], v169 offset:4096
	v_mfma_f32_16x16x32_bf16 v[116:119], v[164:167], v[176:179], v[116:119]
	v_mfma_f32_16x16x32_bf16 v[120:123], v[164:167], v[180:183], v[120:123]
	v_mfma_f32_16x16x32_bf16 v[124:127], v[164:167], v[184:187], v[124:127]
	s_waitcnt lgkmcnt(2)
	v_mfma_f32_16x16x32_bf16 v[0:3], v[152:155], v[196:199], v[0:3]
	ds_read_b128 v[164:167], v169 offset:6144
	v_mfma_f32_16x16x32_bf16 v[4:7], v[152:155], v[200:203], v[4:7]
	v_mfma_f32_16x16x32_bf16 v[8:11], v[152:155], v[212:215], v[8:11]
	v_mfma_f32_16x16x32_bf16 v[12:15], v[152:155], v[216:219], v[12:15]
	s_waitcnt lgkmcnt(2)
	v_mfma_f32_16x16x32_bf16 v[16:19], v[156:159], v[196:199], v[16:19]
	ds_read_b128 v[152:155], v169 offset:8192
	v_mfma_f32_16x16x32_bf16 v[20:23], v[156:159], v[200:203], v[20:23]
	v_mfma_f32_16x16x32_bf16 v[24:27], v[156:159], v[212:215], v[24:27]
	v_mfma_f32_16x16x32_bf16 v[28:31], v[156:159], v[216:219], v[28:31]
	s_waitcnt lgkmcnt(2)
	v_mfma_f32_16x16x32_bf16 v[32:35], v[160:163], v[196:199], v[32:35]
	ds_read_b128 v[156:159], v169 offset:10240
	v_mfma_f32_16x16x32_bf16 v[36:39], v[160:163], v[200:203], v[36:39]
	v_mfma_f32_16x16x32_bf16 v[40:43], v[160:163], v[212:215], v[40:43]
	v_mfma_f32_16x16x32_bf16 v[44:47], v[160:163], v[216:219], v[44:47]
	s_waitcnt lgkmcnt(2)
	v_mfma_f32_16x16x32_bf16 v[48:51], v[164:167], v[196:199], v[48:51]
	ds_read_b128 v[160:163], v169 offset:12288
	v_mfma_f32_16x16x32_bf16 v[52:55], v[164:167], v[200:203], v[52:55]
	v_mfma_f32_16x16x32_bf16 v[56:59], v[164:167], v[212:215], v[56:59]
	v_mfma_f32_16x16x32_bf16 v[60:63], v[164:167], v[216:219], v[60:63]
	s_waitcnt lgkmcnt(2)
	v_mfma_f32_16x16x32_bf16 v[64:67], v[152:155], v[196:199], v[64:67]
	ds_read_b128 v[164:167], v169 offset:14336
	v_mfma_f32_16x16x32_bf16 v[68:71], v[152:155], v[200:203], v[68:71]
	v_mfma_f32_16x16x32_bf16 v[72:75], v[152:155], v[212:215], v[72:75]
	v_mfma_f32_16x16x32_bf16 v[76:79], v[152:155], v[216:219], v[76:79]
	s_waitcnt lgkmcnt(2)
	v_mfma_f32_16x16x32_bf16 v[80:83], v[156:159], v[196:199], v[80:83]
	v_mfma_f32_16x16x32_bf16 v[84:87], v[156:159], v[200:203], v[84:87]
	v_mfma_f32_16x16x32_bf16 v[88:91], v[156:159], v[212:215], v[88:91]
	v_mfma_f32_16x16x32_bf16 v[92:95], v[156:159], v[216:219], v[92:95]
	s_waitcnt lgkmcnt(0)
	s_waitcnt vmcnt(0)
	s_barrier
	v_xor_b32_e32 v168, 0x10000, v168
	v_xor_b32_e32 v169, 0x10000, v169
	v_xor_b32_e32 v192, 0x10000, v192
	v_xor_b32_e32 v204, 0x10000, v204
	v_mfma_f32_16x16x32_bf16 v[96:99], v[160:163], v[196:199], v[96:99]
	ds_read_b128 v[152:155], v168
	ds_read_b128 v[156:159], v168 offset:2048
	s_add_u32 m0, s26, 0x10000
	v_mfma_f32_16x16x32_bf16 v[100:103], v[160:163], v[200:203], v[100:103]
	global_load_lds_dwordx4 v134, s[8:9]
	v_mfma_f32_16x16x32_bf16 v[104:107], v[160:163], v[212:215], v[104:107]
	ds_read_b128 v[172:175], v192 offset:32768
	ds_read_b128 v[176:179], v192 offset:34816
	s_add_u32 m0, s26, 0x18000
	v_mfma_f32_16x16x32_bf16 v[108:111], v[160:163], v[216:219], v[108:111]
	global_load_lds_dwordx4 v136, s[10:11]
	v_mfma_f32_16x16x32_bf16 v[112:115], v[164:167], v[196:199], v[112:115]
	ds_read_b128 v[160:163], v168 offset:4096
	s_add_u32 m0, s26, 0x12000
	v_mfma_f32_16x16x32_bf16 v[116:119], v[164:167], v[200:203], v[116:119]
	global_load_lds_dwordx4 v138, s[8:9]
	ds_read_b128 v[180:183], v192 offset:36864
	ds_read_b128 v[184:187], v192 offset:38912
	v_mfma_f32_16x16x32_bf16 v[120:123], v[164:167], v[212:215], v[120:123]
	s_add_u32 m0, s26, 0x1a000
	v_mfma_f32_16x16x32_bf16 v[124:127], v[164:167], v[216:219], v[124:127]
	global_load_lds_dwordx4 v140, s[10:11]
	s_waitcnt lgkmcnt(4)
	v_mfma_f32_16x16x32_bf16 v[0:3], v[152:155], v[172:175], v[0:3]
	ds_read_b128 v[164:167], v168 offset:6144
	s_waitcnt lgkmcnt(4)
	v_mfma_f32_16x16x32_bf16 v[4:7], v[152:155], v[176:179], v[4:7]
	ds_read_b128 v[196:199], v204 offset:32768
	s_waitcnt lgkmcnt(3)
	v_mfma_f32_16x16x32_bf16 v[8:11], v[152:155], v[180:183], v[8:11]
	s_waitcnt lgkmcnt(2)
	v_mfma_f32_16x16x32_bf16 v[12:15], v[152:155], v[184:187], v[12:15]
	v_mfma_f32_16x16x32_bf16 v[16:19], v[156:159], v[172:175], v[16:19]
	ds_read_b128 v[152:155], v168 offset:8192
	v_mfma_f32_16x16x32_bf16 v[20:23], v[156:159], v[176:179], v[20:23]
	ds_read_b128 v[200:203], v204 offset:34816
	v_mfma_f32_16x16x32_bf16 v[24:27], v[156:159], v[180:183], v[24:27]
	v_mfma_f32_16x16x32_bf16 v[28:31], v[156:159], v[184:187], v[28:31]
	v_mfma_f32_16x16x32_bf16 v[32:35], v[160:163], v[172:175], v[32:35]
	ds_read_b128 v[156:159], v168 offset:10240
	v_mfma_f32_16x16x32_bf16 v[36:39], v[160:163], v[176:179], v[36:39]
	ds_read_b128 v[212:215], v204 offset:36864
	v_mfma_f32_16x16x32_bf16 v[40:43], v[160:163], v[180:183], v[40:43]
	s_add_u32 m0, s26, 0x14000
	v_mfma_f32_16x16x32_bf16 v[44:47], v[160:163], v[184:187], v[44:47]
	global_load_lds_dwordx4 v142, s[8:9]
	s_waitcnt lgkmcnt(5)
	v_mfma_f32_16x16x32_bf16 v[48:51], v[164:167], v[172:175], v[48:51]
	ds_read_b128 v[160:163], v168 offset:12288
	v_mfma_f32_16x16x32_bf16 v[52:55], v[164:167], v[176:179], v[52:55]
	ds_read_b128 v[216:219], v204 offset:38912
	v_mfma_f32_16x16x32_bf16 v[56:59], v[164:167], v[180:183], v[56:59]
	s_add_u32 m0, s26, 0x1c000
	v_mfma_f32_16x16x32_bf16 v[60:63], v[164:167], v[184:187], v[60:63]
	global_load_lds_dwordx4 v144, s[10:11]
	s_waitcnt lgkmcnt(5)
	v_mfma_f32_16x16x32_bf16 v[64:67], v[152:155], v[172:175], v[64:67]
	ds_read_b128 v[164:167], v168 offset:14336
	v_mfma_f32_16x16x32_bf16 v[68:71], v[152:155], v[176:179], v[68:71]
	v_mfma_f32_16x16x32_bf16 v[72:75], v[152:155], v[180:183], v[72:75]
	s_add_u32 m0, s26, 0x16000
	v_mfma_f32_16x16x32_bf16 v[76:79], v[152:155], v[184:187], v[76:79]
	global_load_lds_dwordx4 v146, s[8:9]
	s_waitcnt lgkmcnt(4)
	v_mfma_f32_16x16x32_bf16 v[80:83], v[156:159], v[172:175], v[80:83]
	ds_read_b128 v[152:155], v169
	v_mfma_f32_16x16x32_bf16 v[84:87], v[156:159], v[176:179], v[84:87]
	v_mfma_f32_16x16x32_bf16 v[88:91], v[156:159], v[180:183], v[88:91]
	s_add_u32 m0, s26, 0x1e000
	v_mfma_f32_16x16x32_bf16 v[92:95], v[156:159], v[184:187], v[92:95]
	global_load_lds_dwordx4 v148, s[10:11]
	s_add_u32 s8, s8, 0x80
	s_addc_u32 s9, s9, 0
	s_add_u32 s10, s10, 0x80
	s_addc_u32 s11, s11, 0
	s_waitcnt lgkmcnt(3)
	v_mfma_f32_16x16x32_bf16 v[96:99], v[160:163], v[172:175], v[96:99]
	ds_read_b128 v[156:159], v169 offset:2048
	v_mfma_f32_16x16x32_bf16 v[100:103], v[160:163], v[176:179], v[100:103]
	v_mfma_f32_16x16x32_bf16 v[104:107], v[160:163], v[180:183], v[104:107]
	v_mfma_f32_16x16x32_bf16 v[108:111], v[160:163], v[184:187], v[108:111]
	s_waitcnt lgkmcnt(2)
	v_mfma_f32_16x16x32_bf16 v[112:115], v[164:167], v[172:175], v[112:115]
	ds_read_b128 v[160:163], v169 offset:4096
	v_mfma_f32_16x16x32_bf16 v[116:119], v[164:167], v[176:179], v[116:119]
	v_mfma_f32_16x16x32_bf16 v[120:123], v[164:167], v[180:183], v[120:123]
	v_mfma_f32_16x16x32_bf16 v[124:127], v[164:167], v[184:187], v[124:127]
	s_waitcnt lgkmcnt(2)
	v_mfma_f32_16x16x32_bf16 v[0:3], v[152:155], v[196:199], v[0:3]
	ds_read_b128 v[164:167], v169 offset:6144
	v_mfma_f32_16x16x32_bf16 v[4:7], v[152:155], v[200:203], v[4:7]
	v_mfma_f32_16x16x32_bf16 v[8:11], v[152:155], v[212:215], v[8:11]
	v_mfma_f32_16x16x32_bf16 v[12:15], v[152:155], v[216:219], v[12:15]
	s_waitcnt lgkmcnt(2)
	v_mfma_f32_16x16x32_bf16 v[16:19], v[156:159], v[196:199], v[16:19]
	ds_read_b128 v[152:155], v169 offset:8192
	v_mfma_f32_16x16x32_bf16 v[20:23], v[156:159], v[200:203], v[20:23]
	v_mfma_f32_16x16x32_bf16 v[24:27], v[156:159], v[212:215], v[24:27]
	v_mfma_f32_16x16x32_bf16 v[28:31], v[156:159], v[216:219], v[28:31]
	s_waitcnt lgkmcnt(2)
	v_mfma_f32_16x16x32_bf16 v[32:35], v[160:163], v[196:199], v[32:35]
	ds_read_b128 v[156:159], v169 offset:10240
	v_mfma_f32_16x16x32_bf16 v[36:39], v[160:163], v[200:203], v[36:39]
	v_mfma_f32_16x16x32_bf16 v[40:43], v[160:163], v[212:215], v[40:43]
	v_mfma_f32_16x16x32_bf16 v[44:47], v[160:163], v[216:219], v[44:47]
	s_waitcnt lgkmcnt(2)
	v_mfma_f32_16x16x32_bf16 v[48:51], v[164:167], v[196:199], v[48:51]
	ds_read_b128 v[160:163], v169 offset:12288
	v_mfma_f32_16x16x32_bf16 v[52:55], v[164:167], v[200:203], v[52:55]
	v_mfma_f32_16x16x32_bf16 v[56:59], v[164:167], v[212:215], v[56:59]
	v_mfma_f32_16x16x32_bf16 v[60:63], v[164:167], v[216:219], v[60:63]
	s_waitcnt lgkmcnt(2)
	v_mfma_f32_16x16x32_bf16 v[64:67], v[152:155], v[196:199], v[64:67]
	ds_read_b128 v[164:167], v169 offset:14336
	v_mfma_f32_16x16x32_bf16 v[68:71], v[152:155], v[200:203], v[68:71]
	v_mfma_f32_16x16x32_bf16 v[72:75], v[152:155], v[212:215], v[72:75]
	v_mfma_f32_16x16x32_bf16 v[76:79], v[152:155], v[216:219], v[76:79]
	s_waitcnt lgkmcnt(2)
	v_mfma_f32_16x16x32_bf16 v[80:83], v[156:159], v[196:199], v[80:83]
	v_mfma_f32_16x16x32_bf16 v[84:87], v[156:159], v[200:203], v[84:87]
	v_mfma_f32_16x16x32_bf16 v[88:91], v[156:159], v[212:215], v[88:91]
	v_mfma_f32_16x16x32_bf16 v[92:95], v[156:159], v[216:219], v[92:95]
	s_waitcnt lgkmcnt(0)
	s_waitcnt vmcnt(0)
	s_barrier
	v_xor_b32_e32 v168, 0x10000, v168
	v_xor_b32_e32 v169, 0x10000, v169
	v_xor_b32_e32 v192, 0x10000, v192
	v_xor_b32_e32 v204, 0x10000, v204
	v_mfma_f32_16x16x32_bf16 v[96:99], v[160:163], v[196:199], v[96:99]
	ds_read_b128 v[152:155], v168
	ds_read_b128 v[156:159], v168 offset:2048
	s_mov_b32 m0, s26
	v_mfma_f32_16x16x32_bf16 v[100:103], v[160:163], v[200:203], v[100:103]
	global_load_lds_dwordx4 v134, s[8:9]
	v_mfma_f32_16x16x32_bf16 v[104:107], v[160:163], v[212:215], v[104:107]
	ds_read_b128 v[172:175], v192 offset:32768
	ds_read_b128 v[176:179], v192 offset:34816
	s_add_u32 m0, s26, 0x8000
	v_mfma_f32_16x16x32_bf16 v[108:111], v[160:163], v[216:219], v[108:111]
	global_load_lds_dwordx4 v136, s[10:11]
	v_mfma_f32_16x16x32_bf16 v[112:115], v[164:167], v[196:199], v[112:115]
	ds_read_b128 v[160:163], v168 offset:4096
	s_add_u32 m0, s26, 0x2000
	v_mfma_f32_16x16x32_bf16 v[116:119], v[164:167], v[200:203], v[116:119]
	global_load_lds_dwordx4 v138, s[8:9]
	ds_read_b128 v[180:183], v192 offset:36864
	ds_read_b128 v[184:187], v192 offset:38912
	v_mfma_f32_16x16x32_bf16 v[120:123], v[164:167], v[212:215], v[120:123]
	s_add_u32 m0, s26, 0xa000
	v_mfma_f32_16x16x32_bf16 v[124:127], v[164:167], v[216:219], v[124:127]
	global_load_lds_dwordx4 v140, s[10:11]
	s_waitcnt lgkmcnt(4)
	v_mfma_f32_16x16x32_bf16 v[0:3], v[152:155], v[172:175], v[0:3]
	ds_read_b128 v[164:167], v168 offset:6144
	s_waitcnt lgkmcnt(4)
	v_mfma_f32_16x16x32_bf16 v[4:7], v[152:155], v[176:179], v[4:7]
	ds_read_b128 v[196:199], v204 offset:32768
	s_waitcnt lgkmcnt(3)
	v_mfma_f32_16x16x32_bf16 v[8:11], v[152:155], v[180:183], v[8:11]
	s_waitcnt lgkmcnt(2)
	v_mfma_f32_16x16x32_bf16 v[12:15], v[152:155], v[184:187], v[12:15]
	v_mfma_f32_16x16x32_bf16 v[16:19], v[156:159], v[172:175], v[16:19]
	ds_read_b128 v[152:155], v168 offset:8192
	v_mfma_f32_16x16x32_bf16 v[20:23], v[156:159], v[176:179], v[20:23]
	ds_read_b128 v[200:203], v204 offset:34816
	v_mfma_f32_16x16x32_bf16 v[24:27], v[156:159], v[180:183], v[24:27]
	v_mfma_f32_16x16x32_bf16 v[28:31], v[156:159], v[184:187], v[28:31]
	v_mfma_f32_16x16x32_bf16 v[32:35], v[160:163], v[172:175], v[32:35]
	ds_read_b128 v[156:159], v168 offset:10240
	v_mfma_f32_16x16x32_bf16 v[36:39], v[160:163], v[176:179], v[36:39]
	ds_read_b128 v[212:215], v204 offset:36864
	v_mfma_f32_16x16x32_bf16 v[40:43], v[160:163], v[180:183], v[40:43]
	s_add_u32 m0, s26, 0x4000
	v_mfma_f32_16x16x32_bf16 v[44:47], v[160:163], v[184:187], v[44:47]
	global_load_lds_dwordx4 v142, s[8:9]
	s_waitcnt lgkmcnt(5)
	v_mfma_f32_16x16x32_bf16 v[48:51], v[164:167], v[172:175], v[48:51]
	ds_read_b128 v[160:163], v168 offset:12288
	v_mfma_f32_16x16x32_bf16 v[52:55], v[164:167], v[176:179], v[52:55]
	ds_read_b128 v[216:219], v204 offset:38912
	v_mfma_f32_16x16x32_bf16 v[56:59], v[164:167], v[180:183], v[56:59]
	s_add_u32 m0, s26, 0xc000
	v_mfma_f32_16x16x32_bf16 v[60:63], v[164:167], v[184:187], v[60:63]
	global_load_lds_dwordx4 v144, s[10:11]
	s_waitcnt lgkmcnt(5)
	v_mfma_f32_16x16x32_bf16 v[64:67], v[152:155], v[172:175], v[64:67]
	ds_read_b128 v[164:167], v168 offset:14336
	v_mfma_f32_16x16x32_bf16 v[68:71], v[152:155], v[176:179], v[68:71]
	v_mfma_f32_16x16x32_bf16 v[72:75], v[152:155], v[180:183], v[72:75]
	s_add_u32 m0, s26, 0x6000
	v_mfma_f32_16x16x32_bf16 v[76:79], v[152:155], v[184:187], v[76:79]
	global_load_lds_dwordx4 v146, s[8:9]
	s_waitcnt lgkmcnt(4)
	v_mfma_f32_16x16x32_bf16 v[80:83], v[156:159], v[172:175], v[80:83]
	ds_read_b128 v[152:155], v169
	v_mfma_f32_16x16x32_bf16 v[84:87], v[156:159], v[176:179], v[84:87]
	v_mfma_f32_16x16x32_bf16 v[88:91], v[156:159], v[180:183], v[88:91]
	s_add_u32 m0, s26, 0xe000
	v_mfma_f32_16x16x32_bf16 v[92:95], v[156:159], v[184:187], v[92:95]
	global_load_lds_dwordx4 v148, s[10:11]
	s_add_u32 s8, s8, 0x80
	s_addc_u32 s9, s9, 0
	s_add_u32 s10, s10, 0x80
	s_addc_u32 s11, s11, 0
	s_waitcnt lgkmcnt(3)
	v_mfma_f32_16x16x32_bf16 v[96:99], v[160:163], v[172:175], v[96:99]
	ds_read_b128 v[156:159], v169 offset:2048
	v_mfma_f32_16x16x32_bf16 v[100:103], v[160:163], v[176:179], v[100:103]
	v_mfma_f32_16x16x32_bf16 v[104:107], v[160:163], v[180:183], v[104:107]
	v_mfma_f32_16x16x32_bf16 v[108:111], v[160:163], v[184:187], v[108:111]
	s_waitcnt lgkmcnt(2)
	v_mfma_f32_16x16x32_bf16 v[112:115], v[164:167], v[172:175], v[112:115]
	ds_read_b128 v[160:163], v169 offset:4096
	v_mfma_f32_16x16x32_bf16 v[116:119], v[164:167], v[176:179], v[116:119]
	v_mfma_f32_16x16x32_bf16 v[120:123], v[164:167], v[180:183], v[120:123]
	v_mfma_f32_16x16x32_bf16 v[124:127], v[164:167], v[184:187], v[124:127]
	s_waitcnt lgkmcnt(2)
	v_mfma_f32_16x16x32_bf16 v[0:3], v[152:155], v[196:199], v[0:3]
	ds_read_b128 v[164:167], v169 offset:6144
	v_mfma_f32_16x16x32_bf16 v[4:7], v[152:155], v[200:203], v[4:7]
	v_mfma_f32_16x16x32_bf16 v[8:11], v[152:155], v[212:215], v[8:11]
	v_mfma_f32_16x16x32_bf16 v[12:15], v[152:155], v[216:219], v[12:15]
	s_waitcnt lgkmcnt(2)
	v_mfma_f32_16x16x32_bf16 v[16:19], v[156:159], v[196:199], v[16:19]
	ds_read_b128 v[152:155], v169 offset:8192
	v_mfma_f32_16x16x32_bf16 v[20:23], v[156:159], v[200:203], v[20:23]
	v_mfma_f32_16x16x32_bf16 v[24:27], v[156:159], v[212:215], v[24:27]
	v_mfma_f32_16x16x32_bf16 v[28:31], v[156:159], v[216:219], v[28:31]
	s_waitcnt lgkmcnt(2)
	v_mfma_f32_16x16x32_bf16 v[32:35], v[160:163], v[196:199], v[32:35]
	ds_read_b128 v[156:159], v169 offset:10240
	v_mfma_f32_16x16x32_bf16 v[36:39], v[160:163], v[200:203], v[36:39]
	v_mfma_f32_16x16x32_bf16 v[40:43], v[160:163], v[212:215], v[40:43]
	v_mfma_f32_16x16x32_bf16 v[44:47], v[160:163], v[216:219], v[44:47]
	s_waitcnt lgkmcnt(2)
	v_mfma_f32_16x16x32_bf16 v[48:51], v[164:167], v[196:199], v[48:51]
	ds_read_b128 v[160:163], v169 offset:12288
	v_mfma_f32_16x16x32_bf16 v[52:55], v[164:167], v[200:203], v[52:55]
	v_mfma_f32_16x16x32_bf16 v[56:59], v[164:167], v[212:215], v[56:59]
	v_mfma_f32_16x16x32_bf16 v[60:63], v[164:167], v[216:219], v[60:63]
	s_waitcnt lgkmcnt(2)
	v_mfma_f32_16x16x32_bf16 v[64:67], v[152:155], v[196:199], v[64:67]
	ds_read_b128 v[164:167], v169 offset:14336
	v_mfma_f32_16x16x32_bf16 v[68:71], v[152:155], v[200:203], v[68:71]
	v_mfma_f32_16x16x32_bf16 v[72:75], v[152:155], v[212:215], v[72:75]
	v_mfma_f32_16x16x32_bf16 v[76:79], v[152:155], v[216:219], v[76:79]
	s_waitcnt lgkmcnt(2)
	v_mfma_f32_16x16x32_bf16 v[80:83], v[156:159], v[196:199], v[80:83]
	v_mfma_f32_16x16x32_bf16 v[84:87], v[156:159], v[200:203], v[84:87]
	v_mfma_f32_16x16x32_bf16 v[88:91], v[156:159], v[212:215], v[88:91]
	v_mfma_f32_16x16x32_bf16 v[92:95], v[156:159], v[216:219], v[92:95]
	s_waitcnt lgkmcnt(0)
	s_waitcnt vmcnt(0)
	s_barrier
	v_xor_b32_e32 v168, 0x10000, v168
	v_xor_b32_e32 v169, 0x10000, v169
	v_xor_b32_e32 v192, 0x10000, v192
	v_xor_b32_e32 v204, 0x10000, v204
	v_mfma_f32_16x16x32_bf16 v[96:99], v[160:163], v[196:199], v[96:99]
	ds_read_b128 v[152:155], v168
	ds_read_b128 v[156:159], v168 offset:2048
	s_add_u32 m0, s26, 0x10000
	v_mfma_f32_16x16x32_bf16 v[100:103], v[160:163], v[200:203], v[100:103]
	global_load_lds_dwordx4 v134, s[8:9]
	v_mfma_f32_16x16x32_bf16 v[104:107], v[160:163], v[212:215], v[104:107]
	ds_read_b128 v[172:175], v192 offset:32768
	ds_read_b128 v[176:179], v192 offset:34816
	s_add_u32 m0, s26, 0x18000
	v_mfma_f32_16x16x32_bf16 v[108:111], v[160:163], v[216:219], v[108:111]
	global_load_lds_dwordx4 v136, s[10:11]
	v_mfma_f32_16x16x32_bf16 v[112:115], v[164:167], v[196:199], v[112:115]
	ds_read_b128 v[160:163], v168 offset:4096
	s_add_u32 m0, s26, 0x12000
	v_mfma_f32_16x16x32_bf16 v[116:119], v[164:167], v[200:203], v[116:119]
	global_load_lds_dwordx4 v138, s[8:9]
	ds_read_b128 v[180:183], v192 offset:36864
	ds_read_b128 v[184:187], v192 offset:38912
	v_mfma_f32_16x16x32_bf16 v[120:123], v[164:167], v[212:215], v[120:123]
	s_add_u32 m0, s26, 0x1a000
	v_mfma_f32_16x16x32_bf16 v[124:127], v[164:167], v[216:219], v[124:127]
	global_load_lds_dwordx4 v140, s[10:11]
	s_waitcnt lgkmcnt(4)
	v_mfma_f32_16x16x32_bf16 v[0:3], v[152:155], v[172:175], v[0:3]
	ds_read_b128 v[164:167], v168 offset:6144
	s_waitcnt lgkmcnt(4)
	v_mfma_f32_16x16x32_bf16 v[4:7], v[152:155], v[176:179], v[4:7]
	ds_read_b128 v[196:199], v204 offset:32768
	s_waitcnt lgkmcnt(3)
	v_mfma_f32_16x16x32_bf16 v[8:11], v[152:155], v[180:183], v[8:11]
	s_waitcnt lgkmcnt(2)
	v_mfma_f32_16x16x32_bf16 v[12:15], v[152:155], v[184:187], v[12:15]
	v_mfma_f32_16x16x32_bf16 v[16:19], v[156:159], v[172:175], v[16:19]
	ds_read_b128 v[152:155], v168 offset:8192
	v_mfma_f32_16x16x32_bf16 v[20:23], v[156:159], v[176:179], v[20:23]
	ds_read_b128 v[200:203], v204 offset:34816
	v_mfma_f32_16x16x32_bf16 v[24:27], v[156:159], v[180:183], v[24:27]
	v_mfma_f32_16x16x32_bf16 v[28:31], v[156:159], v[184:187], v[28:31]
	v_mfma_f32_16x16x32_bf16 v[32:35], v[160:163], v[172:175], v[32:35]
	ds_read_b128 v[156:159], v168 offset:10240
	v_mfma_f32_16x16x32_bf16 v[36:39], v[160:163], v[176:179], v[36:39]
	ds_read_b128 v[212:215], v204 offset:36864
	v_mfma_f32_16x16x32_bf16 v[40:43], v[160:163], v[180:183], v[40:43]
	s_add_u32 m0, s26, 0x14000
	v_mfma_f32_16x16x32_bf16 v[44:47], v[160:163], v[184:187], v[44:47]
	global_load_lds_dwordx4 v142, s[8:9]
	s_waitcnt lgkmcnt(5)
	v_mfma_f32_16x16x32_bf16 v[48:51], v[164:167], v[172:175], v[48:51]
	ds_read_b128 v[160:163], v168 offset:12288
	v_mfma_f32_16x16x32_bf16 v[52:55], v[164:167], v[176:179], v[52:55]
	ds_read_b128 v[216:219], v204 offset:38912
	v_mfma_f32_16x16x32_bf16 v[56:59], v[164:167], v[180:183], v[56:59]
	s_add_u32 m0, s26, 0x1c000
	v_mfma_f32_16x16x32_bf16 v[60:63], v[164:167], v[184:187], v[60:63]
	global_load_lds_dwordx4 v144, s[10:11]
	s_waitcnt lgkmcnt(5)
	v_mfma_f32_16x16x32_bf16 v[64:67], v[152:155], v[172:175], v[64:67]
	ds_read_b128 v[164:167], v168 offset:14336
	v_mfma_f32_16x16x32_bf16 v[68:71], v[152:155], v[176:179], v[68:71]
	v_mfma_f32_16x16x32_bf16 v[72:75], v[152:155], v[180:183], v[72:75]
	s_add_u32 m0, s26, 0x16000
	v_mfma_f32_16x16x32_bf16 v[76:79], v[152:155], v[184:187], v[76:79]
	global_load_lds_dwordx4 v146, s[8:9]
	s_waitcnt lgkmcnt(4)
	v_mfma_f32_16x16x32_bf16 v[80:83], v[156:159], v[172:175], v[80:83]
	ds_read_b128 v[152:155], v169
	v_mfma_f32_16x16x32_bf16 v[84:87], v[156:159], v[176:179], v[84:87]
	v_mfma_f32_16x16x32_bf16 v[88:91], v[156:159], v[180:183], v[88:91]
	s_add_u32 m0, s26, 0x1e000
	v_mfma_f32_16x16x32_bf16 v[92:95], v[156:159], v[184:187], v[92:95]
	global_load_lds_dwordx4 v148, s[10:11]
	s_add_u32 s8, s8, 0x80
	s_addc_u32 s9, s9, 0
	s_add_u32 s10, s10, 0x80
	s_addc_u32 s11, s11, 0
	s_waitcnt lgkmcnt(3)
	v_mfma_f32_16x16x32_bf16 v[96:99], v[160:163], v[172:175], v[96:99]
	ds_read_b128 v[156:159], v169 offset:2048
	v_mfma_f32_16x16x32_bf16 v[100:103], v[160:163], v[176:179], v[100:103]
	v_mfma_f32_16x16x32_bf16 v[104:107], v[160:163], v[180:183], v[104:107]
	v_mfma_f32_16x16x32_bf16 v[108:111], v[160:163], v[184:187], v[108:111]
	s_waitcnt lgkmcnt(2)
	v_mfma_f32_16x16x32_bf16 v[112:115], v[164:167], v[172:175], v[112:115]
	ds_read_b128 v[160:163], v169 offset:4096
	v_mfma_f32_16x16x32_bf16 v[116:119], v[164:167], v[176:179], v[116:119]
	v_mfma_f32_16x16x32_bf16 v[120:123], v[164:167], v[180:183], v[120:123]
	v_mfma_f32_16x16x32_bf16 v[124:127], v[164:167], v[184:187], v[124:127]
	s_waitcnt lgkmcnt(2)
	v_mfma_f32_16x16x32_bf16 v[0:3], v[152:155], v[196:199], v[0:3]
	ds_read_b128 v[164:167], v169 offset:6144
	v_mfma_f32_16x16x32_bf16 v[4:7], v[152:155], v[200:203], v[4:7]
	v_mfma_f32_16x16x32_bf16 v[8:11], v[152:155], v[212:215], v[8:11]
	v_mfma_f32_16x16x32_bf16 v[12:15], v[152:155], v[216:219], v[12:15]
	s_waitcnt lgkmcnt(2)
	v_mfma_f32_16x16x32_bf16 v[16:19], v[156:159], v[196:199], v[16:19]
	ds_read_b128 v[152:155], v169 offset:8192
	v_mfma_f32_16x16x32_bf16 v[20:23], v[156:159], v[200:203], v[20:23]
	v_mfma_f32_16x16x32_bf16 v[24:27], v[156:159], v[212:215], v[24:27]
	v_mfma_f32_16x16x32_bf16 v[28:31], v[156:159], v[216:219], v[28:31]
	s_waitcnt lgkmcnt(2)
	v_mfma_f32_16x16x32_bf16 v[32:35], v[160:163], v[196:199], v[32:35]
	ds_read_b128 v[156:159], v169 offset:10240
	v_mfma_f32_16x16x32_bf16 v[36:39], v[160:163], v[200:203], v[36:39]
	v_mfma_f32_16x16x32_bf16 v[40:43], v[160:163], v[212:215], v[40:43]
	v_mfma_f32_16x16x32_bf16 v[44:47], v[160:163], v[216:219], v[44:47]
	s_waitcnt lgkmcnt(2)
	v_mfma_f32_16x16x32_bf16 v[48:51], v[164:167], v[196:199], v[48:51]
	ds_read_b128 v[160:163], v169 offset:12288
	v_mfma_f32_16x16x32_bf16 v[52:55], v[164:167], v[200:203], v[52:55]
	v_mfma_f32_16x16x32_bf16 v[56:59], v[164:167], v[212:215], v[56:59]
	v_mfma_f32_16x16x32_bf16 v[60:63], v[164:167], v[216:219], v[60:63]
	s_waitcnt lgkmcnt(2)
	v_mfma_f32_16x16x32_bf16 v[64:67], v[152:155], v[196:199], v[64:67]
	ds_read_b128 v[164:167], v169 offset:14336
	v_mfma_f32_16x16x32_bf16 v[68:71], v[152:155], v[200:203], v[68:71]
	v_mfma_f32_16x16x32_bf16 v[72:75], v[152:155], v[212:215], v[72:75]
	v_mfma_f32_16x16x32_bf16 v[76:79], v[152:155], v[216:219], v[76:79]
	s_waitcnt lgkmcnt(2)
	v_mfma_f32_16x16x32_bf16 v[80:83], v[156:159], v[196:199], v[80:83]
	v_mfma_f32_16x16x32_bf16 v[84:87], v[156:159], v[200:203], v[84:87]
	v_mfma_f32_16x16x32_bf16 v[88:91], v[156:159], v[212:215], v[88:91]
	v_mfma_f32_16x16x32_bf16 v[92:95], v[156:159], v[216:219], v[92:95]
	s_waitcnt lgkmcnt(0)
	s_waitcnt vmcnt(0)
	s_barrier
	v_xor_b32_e32 v168, 0x10000, v168
	v_xor_b32_e32 v169, 0x10000, v169
	v_xor_b32_e32 v192, 0x10000, v192
	v_xor_b32_e32 v204, 0x10000, v204
	v_mfma_f32_16x16x32_bf16 v[96:99], v[160:163], v[196:199], v[96:99]
	ds_read_b128 v[152:155], v168
	ds_read_b128 v[156:159], v168 offset:2048
	s_mov_b32 m0, s26
	v_mfma_f32_16x16x32_bf16 v[100:103], v[160:163], v[200:203], v[100:103]
	global_load_lds_dwordx4 v134, s[8:9]
	v_mfma_f32_16x16x32_bf16 v[104:107], v[160:163], v[212:215], v[104:107]
	ds_read_b128 v[172:175], v192 offset:32768
	ds_read_b128 v[176:179], v192 offset:34816
	s_add_u32 m0, s26, 0x8000
	v_mfma_f32_16x16x32_bf16 v[108:111], v[160:163], v[216:219], v[108:111]
	global_load_lds_dwordx4 v136, s[10:11]
	v_mfma_f32_16x16x32_bf16 v[112:115], v[164:167], v[196:199], v[112:115]
	ds_read_b128 v[160:163], v168 offset:4096
	s_add_u32 m0, s26, 0x2000
	v_mfma_f32_16x16x32_bf16 v[116:119], v[164:167], v[200:203], v[116:119]
	global_load_lds_dwordx4 v138, s[8:9]
	ds_read_b128 v[180:183], v192 offset:36864
	ds_read_b128 v[184:187], v192 offset:38912
	v_mfma_f32_16x16x32_bf16 v[120:123], v[164:167], v[212:215], v[120:123]
	s_add_u32 m0, s26, 0xa000
	v_mfma_f32_16x16x32_bf16 v[124:127], v[164:167], v[216:219], v[124:127]
	global_load_lds_dwordx4 v140, s[10:11]
	s_waitcnt lgkmcnt(4)
	v_mfma_f32_16x16x32_bf16 v[0:3], v[152:155], v[172:175], v[0:3]
	ds_read_b128 v[164:167], v168 offset:6144
	s_waitcnt lgkmcnt(4)
	v_mfma_f32_16x16x32_bf16 v[4:7], v[152:155], v[176:179], v[4:7]
	ds_read_b128 v[196:199], v204 offset:32768
	s_waitcnt lgkmcnt(3)
	v_mfma_f32_16x16x32_bf16 v[8:11], v[152:155], v[180:183], v[8:11]
	s_waitcnt lgkmcnt(2)
	v_mfma_f32_16x16x32_bf16 v[12:15], v[152:155], v[184:187], v[12:15]
	v_mfma_f32_16x16x32_bf16 v[16:19], v[156:159], v[172:175], v[16:19]
	ds_read_b128 v[152:155], v168 offset:8192
	v_mfma_f32_16x16x32_bf16 v[20:23], v[156:159], v[176:179], v[20:23]
	ds_read_b128 v[200:203], v204 offset:34816
	v_mfma_f32_16x16x32_bf16 v[24:27], v[156:159], v[180:183], v[24:27]
	v_mfma_f32_16x16x32_bf16 v[28:31], v[156:159], v[184:187], v[28:31]
	v_mfma_f32_16x16x32_bf16 v[32:35], v[160:163], v[172:175], v[32:35]
	ds_read_b128 v[156:159], v168 offset:10240
	v_mfma_f32_16x16x32_bf16 v[36:39], v[160:163], v[176:179], v[36:39]
	ds_read_b128 v[212:215], v204 offset:36864
	v_mfma_f32_16x16x32_bf16 v[40:43], v[160:163], v[180:183], v[40:43]
	s_add_u32 m0, s26, 0x4000
	v_mfma_f32_16x16x32_bf16 v[44:47], v[160:163], v[184:187], v[44:47]
	global_load_lds_dwordx4 v142, s[8:9]
	s_waitcnt lgkmcnt(5)
	v_mfma_f32_16x16x32_bf16 v[48:51], v[164:167], v[172:175], v[48:51]
	ds_read_b128 v[160:163], v168 offset:12288
	v_mfma_f32_16x16x32_bf16 v[52:55], v[164:167], v[176:179], v[52:55]
	ds_read_b128 v[216:219], v204 offset:38912
	v_mfma_f32_16x16x32_bf16 v[56:59], v[164:167], v[180:183], v[56:59]
	s_add_u32 m0, s26, 0xc000
	v_mfma_f32_16x16x32_bf16 v[60:63], v[164:167], v[184:187], v[60:63]
	global_load_lds_dwordx4 v144, s[10:11]
	s_waitcnt lgkmcnt(5)
	v_mfma_f32_16x16x32_bf16 v[64:67], v[152:155], v[172:175], v[64:67]
	ds_read_b128 v[164:167], v168 offset:14336
	v_mfma_f32_16x16x32_bf16 v[68:71], v[152:155], v[176:179], v[68:71]
	v_mfma_f32_16x16x32_bf16 v[72:75], v[152:155], v[180:183], v[72:75]
	s_add_u32 m0, s26, 0x6000
	v_mfma_f32_16x16x32_bf16 v[76:79], v[152:155], v[184:187], v[76:79]
	global_load_lds_dwordx4 v146, s[8:9]
	s_waitcnt lgkmcnt(4)
	v_mfma_f32_16x16x32_bf16 v[80:83], v[156:159], v[172:175], v[80:83]
	ds_read_b128 v[152:155], v169
	v_mfma_f32_16x16x32_bf16 v[84:87], v[156:159], v[176:179], v[84:87]
	v_mfma_f32_16x16x32_bf16 v[88:91], v[156:159], v[180:183], v[88:91]
	s_add_u32 m0, s26, 0xe000
	v_mfma_f32_16x16x32_bf16 v[92:95], v[156:159], v[184:187], v[92:95]
	global_load_lds_dwordx4 v148, s[10:11]
	s_add_u32 s8, s8, 0x80
	s_addc_u32 s9, s9, 0
	s_add_u32 s10, s10, 0x80
	s_addc_u32 s11, s11, 0
	s_waitcnt lgkmcnt(3)
	v_mfma_f32_16x16x32_bf16 v[96:99], v[160:163], v[172:175], v[96:99]
	ds_read_b128 v[156:159], v169 offset:2048
	v_mfma_f32_16x16x32_bf16 v[100:103], v[160:163], v[176:179], v[100:103]
	v_mfma_f32_16x16x32_bf16 v[104:107], v[160:163], v[180:183], v[104:107]
	v_mfma_f32_16x16x32_bf16 v[108:111], v[160:163], v[184:187], v[108:111]
	s_waitcnt lgkmcnt(2)
	v_mfma_f32_16x16x32_bf16 v[112:115], v[164:167], v[172:175], v[112:115]
	ds_read_b128 v[160:163], v169 offset:4096
	v_mfma_f32_16x16x32_bf16 v[116:119], v[164:167], v[176:179], v[116:119]
	v_mfma_f32_16x16x32_bf16 v[120:123], v[164:167], v[180:183], v[120:123]
	v_mfma_f32_16x16x32_bf16 v[124:127], v[164:167], v[184:187], v[124:127]
	s_waitcnt lgkmcnt(2)
	v_mfma_f32_16x16x32_bf16 v[0:3], v[152:155], v[196:199], v[0:3]
	ds_read_b128 v[164:167], v169 offset:6144
	v_mfma_f32_16x16x32_bf16 v[4:7], v[152:155], v[200:203], v[4:7]
	v_mfma_f32_16x16x32_bf16 v[8:11], v[152:155], v[212:215], v[8:11]
	v_mfma_f32_16x16x32_bf16 v[12:15], v[152:155], v[216:219], v[12:15]
	s_waitcnt lgkmcnt(2)
	v_mfma_f32_16x16x32_bf16 v[16:19], v[156:159], v[196:199], v[16:19]
	ds_read_b128 v[152:155], v169 offset:8192
	v_mfma_f32_16x16x32_bf16 v[20:23], v[156:159], v[200:203], v[20:23]
	v_mfma_f32_16x16x32_bf16 v[24:27], v[156:159], v[212:215], v[24:27]
	v_mfma_f32_16x16x32_bf16 v[28:31], v[156:159], v[216:219], v[28:31]
	s_waitcnt lgkmcnt(2)
	v_mfma_f32_16x16x32_bf16 v[32:35], v[160:163], v[196:199], v[32:35]
	ds_read_b128 v[156:159], v169 offset:10240
	v_mfma_f32_16x16x32_bf16 v[36:39], v[160:163], v[200:203], v[36:39]
	v_mfma_f32_16x16x32_bf16 v[40:43], v[160:163], v[212:215], v[40:43]
	v_mfma_f32_16x16x32_bf16 v[44:47], v[160:163], v[216:219], v[44:47]
	s_waitcnt lgkmcnt(2)
	v_mfma_f32_16x16x32_bf16 v[48:51], v[164:167], v[196:199], v[48:51]
	ds_read_b128 v[160:163], v169 offset:12288
	v_mfma_f32_16x16x32_bf16 v[52:55], v[164:167], v[200:203], v[52:55]
	v_mfma_f32_16x16x32_bf16 v[56:59], v[164:167], v[212:215], v[56:59]
	v_mfma_f32_16x16x32_bf16 v[60:63], v[164:167], v[216:219], v[60:63]
	s_waitcnt lgkmcnt(2)
	v_mfma_f32_16x16x32_bf16 v[64:67], v[152:155], v[196:199], v[64:67]
	ds_read_b128 v[164:167], v169 offset:14336
	v_mfma_f32_16x16x32_bf16 v[68:71], v[152:155], v[200:203], v[68:71]
	v_mfma_f32_16x16x32_bf16 v[72:75], v[152:155], v[212:215], v[72:75]
	v_mfma_f32_16x16x32_bf16 v[76:79], v[152:155], v[216:219], v[76:79]
	s_waitcnt lgkmcnt(2)
	v_mfma_f32_16x16x32_bf16 v[80:83], v[156:159], v[196:199], v[80:83]
	v_mfma_f32_16x16x32_bf16 v[84:87], v[156:159], v[200:203], v[84:87]
	v_mfma_f32_16x16x32_bf16 v[88:91], v[156:159], v[212:215], v[88:91]
	v_mfma_f32_16x16x32_bf16 v[92:95], v[156:159], v[216:219], v[92:95]
	s_waitcnt lgkmcnt(0)
	s_waitcnt vmcnt(0)
	s_barrier
	v_xor_b32_e32 v168, 0x10000, v168
	v_xor_b32_e32 v169, 0x10000, v169
	v_xor_b32_e32 v192, 0x10000, v192
	v_xor_b32_e32 v204, 0x10000, v204
	v_mfma_f32_16x16x32_bf16 v[96:99], v[160:163], v[196:199], v[96:99]
	ds_read_b128 v[152:155], v168
	ds_read_b128 v[156:159], v168 offset:2048
	s_add_u32 m0, s26, 0x10000
	v_mfma_f32_16x16x32_bf16 v[100:103], v[160:163], v[200:203], v[100:103]
	global_load_lds_dwordx4 v134, s[8:9]
	v_mfma_f32_16x16x32_bf16 v[104:107], v[160:163], v[212:215], v[104:107]
	ds_read_b128 v[172:175], v192 offset:32768
	ds_read_b128 v[176:179], v192 offset:34816
	s_add_u32 m0, s26, 0x18000
	v_mfma_f32_16x16x32_bf16 v[108:111], v[160:163], v[216:219], v[108:111]
	global_load_lds_dwordx4 v136, s[10:11]
	v_mfma_f32_16x16x32_bf16 v[112:115], v[164:167], v[196:199], v[112:115]
	ds_read_b128 v[160:163], v168 offset:4096
	s_add_u32 m0, s26, 0x12000
	v_mfma_f32_16x16x32_bf16 v[116:119], v[164:167], v[200:203], v[116:119]
	global_load_lds_dwordx4 v138, s[8:9]
	ds_read_b128 v[180:183], v192 offset:36864
	ds_read_b128 v[184:187], v192 offset:38912
	v_mfma_f32_16x16x32_bf16 v[120:123], v[164:167], v[212:215], v[120:123]
	s_add_u32 m0, s26, 0x1a000
	v_mfma_f32_16x16x32_bf16 v[124:127], v[164:167], v[216:219], v[124:127]
	global_load_lds_dwordx4 v140, s[10:11]
	s_waitcnt lgkmcnt(4)
	v_mfma_f32_16x16x32_bf16 v[0:3], v[152:155], v[172:175], v[0:3]
	ds_read_b128 v[164:167], v168 offset:6144
	s_waitcnt lgkmcnt(4)
	v_mfma_f32_16x16x32_bf16 v[4:7], v[152:155], v[176:179], v[4:7]
	ds_read_b128 v[196:199], v204 offset:32768
	s_waitcnt lgkmcnt(3)
	v_mfma_f32_16x16x32_bf16 v[8:11], v[152:155], v[180:183], v[8:11]
	s_waitcnt lgkmcnt(2)
	v_mfma_f32_16x16x32_bf16 v[12:15], v[152:155], v[184:187], v[12:15]
	v_mfma_f32_16x16x32_bf16 v[16:19], v[156:159], v[172:175], v[16:19]
	ds_read_b128 v[152:155], v168 offset:8192
	v_mfma_f32_16x16x32_bf16 v[20:23], v[156:159], v[176:179], v[20:23]
	ds_read_b128 v[200:203], v204 offset:34816
	v_mfma_f32_16x16x32_bf16 v[24:27], v[156:159], v[180:183], v[24:27]
	v_mfma_f32_16x16x32_bf16 v[28:31], v[156:159], v[184:187], v[28:31]
	v_mfma_f32_16x16x32_bf16 v[32:35], v[160:163], v[172:175], v[32:35]
	ds_read_b128 v[156:159], v168 offset:10240
	v_mfma_f32_16x16x32_bf16 v[36:39], v[160:163], v[176:179], v[36:39]
	ds_read_b128 v[212:215], v204 offset:36864
	v_mfma_f32_16x16x32_bf16 v[40:43], v[160:163], v[180:183], v[40:43]
	s_add_u32 m0, s26, 0x14000
	v_mfma_f32_16x16x32_bf16 v[44:47], v[160:163], v[184:187], v[44:47]
	global_load_lds_dwordx4 v142, s[8:9]
	s_waitcnt lgkmcnt(5)
	v_mfma_f32_16x16x32_bf16 v[48:51], v[164:167], v[172:175], v[48:51]
	ds_read_b128 v[160:163], v168 offset:12288
	v_mfma_f32_16x16x32_bf16 v[52:55], v[164:167], v[176:179], v[52:55]
	ds_read_b128 v[216:219], v204 offset:38912
	v_mfma_f32_16x16x32_bf16 v[56:59], v[164:167], v[180:183], v[56:59]
	s_add_u32 m0, s26, 0x1c000
	v_mfma_f32_16x16x32_bf16 v[60:63], v[164:167], v[184:187], v[60:63]
	global_load_lds_dwordx4 v144, s[10:11]
	s_waitcnt lgkmcnt(5)
	v_mfma_f32_16x16x32_bf16 v[64:67], v[152:155], v[172:175], v[64:67]
	ds_read_b128 v[164:167], v168 offset:14336
	v_mfma_f32_16x16x32_bf16 v[68:71], v[152:155], v[176:179], v[68:71]
	v_mfma_f32_16x16x32_bf16 v[72:75], v[152:155], v[180:183], v[72:75]
	s_add_u32 m0, s26, 0x16000
	v_mfma_f32_16x16x32_bf16 v[76:79], v[152:155], v[184:187], v[76:79]
	global_load_lds_dwordx4 v146, s[8:9]
	s_waitcnt lgkmcnt(4)
	v_mfma_f32_16x16x32_bf16 v[80:83], v[156:159], v[172:175], v[80:83]
	ds_read_b128 v[152:155], v169
	v_mfma_f32_16x16x32_bf16 v[84:87], v[156:159], v[176:179], v[84:87]
	v_mfma_f32_16x16x32_bf16 v[88:91], v[156:159], v[180:183], v[88:91]
	s_add_u32 m0, s26, 0x1e000
	v_mfma_f32_16x16x32_bf16 v[92:95], v[156:159], v[184:187], v[92:95]
	global_load_lds_dwordx4 v148, s[10:11]
	s_add_u32 s8, s8, 0x80
	s_addc_u32 s9, s9, 0
	s_add_u32 s10, s10, 0x80
	s_addc_u32 s11, s11, 0
	s_waitcnt lgkmcnt(3)
	v_mfma_f32_16x16x32_bf16 v[96:99], v[160:163], v[172:175], v[96:99]
	ds_read_b128 v[156:159], v169 offset:2048
	v_mfma_f32_16x16x32_bf16 v[100:103], v[160:163], v[176:179], v[100:103]
	v_mfma_f32_16x16x32_bf16 v[104:107], v[160:163], v[180:183], v[104:107]
	v_mfma_f32_16x16x32_bf16 v[108:111], v[160:163], v[184:187], v[108:111]
	s_waitcnt lgkmcnt(2)
	v_mfma_f32_16x16x32_bf16 v[112:115], v[164:167], v[172:175], v[112:115]
	ds_read_b128 v[160:163], v169 offset:4096
	v_mfma_f32_16x16x32_bf16 v[116:119], v[164:167], v[176:179], v[116:119]
	v_mfma_f32_16x16x32_bf16 v[120:123], v[164:167], v[180:183], v[120:123]
	v_mfma_f32_16x16x32_bf16 v[124:127], v[164:167], v[184:187], v[124:127]
	s_waitcnt lgkmcnt(2)
	v_mfma_f32_16x16x32_bf16 v[0:3], v[152:155], v[196:199], v[0:3]
	ds_read_b128 v[164:167], v169 offset:6144
	v_mfma_f32_16x16x32_bf16 v[4:7], v[152:155], v[200:203], v[4:7]
	v_mfma_f32_16x16x32_bf16 v[8:11], v[152:155], v[212:215], v[8:11]
	v_mfma_f32_16x16x32_bf16 v[12:15], v[152:155], v[216:219], v[12:15]
	s_waitcnt lgkmcnt(2)
	v_mfma_f32_16x16x32_bf16 v[16:19], v[156:159], v[196:199], v[16:19]
	ds_read_b128 v[152:155], v169 offset:8192
	v_mfma_f32_16x16x32_bf16 v[20:23], v[156:159], v[200:203], v[20:23]
	v_mfma_f32_16x16x32_bf16 v[24:27], v[156:159], v[212:215], v[24:27]
	v_mfma_f32_16x16x32_bf16 v[28:31], v[156:159], v[216:219], v[28:31]
	s_waitcnt lgkmcnt(2)
	v_mfma_f32_16x16x32_bf16 v[32:35], v[160:163], v[196:199], v[32:35]
	ds_read_b128 v[156:159], v169 offset:10240
	v_mfma_f32_16x16x32_bf16 v[36:39], v[160:163], v[200:203], v[36:39]
	v_mfma_f32_16x16x32_bf16 v[40:43], v[160:163], v[212:215], v[40:43]
	v_mfma_f32_16x16x32_bf16 v[44:47], v[160:163], v[216:219], v[44:47]
	s_waitcnt lgkmcnt(2)
	v_mfma_f32_16x16x32_bf16 v[48:51], v[164:167], v[196:199], v[48:51]
	ds_read_b128 v[160:163], v169 offset:12288
	v_mfma_f32_16x16x32_bf16 v[52:55], v[164:167], v[200:203], v[52:55]
	v_mfma_f32_16x16x32_bf16 v[56:59], v[164:167], v[212:215], v[56:59]
	v_mfma_f32_16x16x32_bf16 v[60:63], v[164:167], v[216:219], v[60:63]
	s_waitcnt lgkmcnt(2)
	v_mfma_f32_16x16x32_bf16 v[64:67], v[152:155], v[196:199], v[64:67]
	ds_read_b128 v[164:167], v169 offset:14336
	v_mfma_f32_16x16x32_bf16 v[68:71], v[152:155], v[200:203], v[68:71]
	v_mfma_f32_16x16x32_bf16 v[72:75], v[152:155], v[212:215], v[72:75]
	v_mfma_f32_16x16x32_bf16 v[76:79], v[152:155], v[216:219], v[76:79]
	s_waitcnt lgkmcnt(2)
	v_mfma_f32_16x16x32_bf16 v[80:83], v[156:159], v[196:199], v[80:83]
	v_mfma_f32_16x16x32_bf16 v[84:87], v[156:159], v[200:203], v[84:87]
	v_mfma_f32_16x16x32_bf16 v[88:91], v[156:159], v[212:215], v[88:91]
	v_mfma_f32_16x16x32_bf16 v[92:95], v[156:159], v[216:219], v[92:95]
	s_waitcnt lgkmcnt(0)
	s_waitcnt vmcnt(0)
	s_barrier
	v_xor_b32_e32 v168, 0x10000, v168
	v_xor_b32_e32 v169, 0x10000, v169
	v_xor_b32_e32 v192, 0x10000, v192
	v_xor_b32_e32 v204, 0x10000, v204
	v_mfma_f32_16x16x32_bf16 v[96:99], v[160:163], v[196:199], v[96:99]
	ds_read_b128 v[152:155], v168
	ds_read_b128 v[156:159], v168 offset:2048
	s_mov_b32 m0, s26
	v_mfma_f32_16x16x32_bf16 v[100:103], v[160:163], v[200:203], v[100:103]
	global_load_lds_dwordx4 v134, s[8:9]
	v_mfma_f32_16x16x32_bf16 v[104:107], v[160:163], v[212:215], v[104:107]
	ds_read_b128 v[172:175], v192 offset:32768
	ds_read_b128 v[176:179], v192 offset:34816
	s_add_u32 m0, s26, 0x8000
	v_mfma_f32_16x16x32_bf16 v[108:111], v[160:163], v[216:219], v[108:111]
	global_load_lds_dwordx4 v136, s[10:11]
	v_mfma_f32_16x16x32_bf16 v[112:115], v[164:167], v[196:199], v[112:115]
	ds_read_b128 v[160:163], v168 offset:4096
	s_add_u32 m0, s26, 0x2000
	v_mfma_f32_16x16x32_bf16 v[116:119], v[164:167], v[200:203], v[116:119]
	global_load_lds_dwordx4 v138, s[8:9]
	ds_read_b128 v[180:183], v192 offset:36864
	ds_read_b128 v[184:187], v192 offset:38912
	v_mfma_f32_16x16x32_bf16 v[120:123], v[164:167], v[212:215], v[120:123]
	s_add_u32 m0, s26, 0xa000
	v_mfma_f32_16x16x32_bf16 v[124:127], v[164:167], v[216:219], v[124:127]
	global_load_lds_dwordx4 v140, s[10:11]
	s_waitcnt lgkmcnt(4)
	v_mfma_f32_16x16x32_bf16 v[0:3], v[152:155], v[172:175], v[0:3]
	ds_read_b128 v[164:167], v168 offset:6144
	s_waitcnt lgkmcnt(4)
	v_mfma_f32_16x16x32_bf16 v[4:7], v[152:155], v[176:179], v[4:7]
	ds_read_b128 v[196:199], v204 offset:32768
	s_waitcnt lgkmcnt(3)
	v_mfma_f32_16x16x32_bf16 v[8:11], v[152:155], v[180:183], v[8:11]
	s_waitcnt lgkmcnt(2)
	v_mfma_f32_16x16x32_bf16 v[12:15], v[152:155], v[184:187], v[12:15]
	v_mfma_f32_16x16x32_bf16 v[16:19], v[156:159], v[172:175], v[16:19]
	ds_read_b128 v[152:155], v168 offset:8192
	v_mfma_f32_16x16x32_bf16 v[20:23], v[156:159], v[176:179], v[20:23]
	ds_read_b128 v[200:203], v204 offset:34816
	v_mfma_f32_16x16x32_bf16 v[24:27], v[156:159], v[180:183], v[24:27]
	v_mfma_f32_16x16x32_bf16 v[28:31], v[156:159], v[184:187], v[28:31]
	v_mfma_f32_16x16x32_bf16 v[32:35], v[160:163], v[172:175], v[32:35]
	ds_read_b128 v[156:159], v168 offset:10240
	v_mfma_f32_16x16x32_bf16 v[36:39], v[160:163], v[176:179], v[36:39]
	ds_read_b128 v[212:215], v204 offset:36864
	v_mfma_f32_16x16x32_bf16 v[40:43], v[160:163], v[180:183], v[40:43]
	s_add_u32 m0, s26, 0x4000
	v_mfma_f32_16x16x32_bf16 v[44:47], v[160:163], v[184:187], v[44:47]
	global_load_lds_dwordx4 v142, s[8:9]
	s_waitcnt lgkmcnt(5)
	v_mfma_f32_16x16x32_bf16 v[48:51], v[164:167], v[172:175], v[48:51]
	ds_read_b128 v[160:163], v168 offset:12288
	v_mfma_f32_16x16x32_bf16 v[52:55], v[164:167], v[176:179], v[52:55]
	ds_read_b128 v[216:219], v204 offset:38912
	v_mfma_f32_16x16x32_bf16 v[56:59], v[164:167], v[180:183], v[56:59]
	s_add_u32 m0, s26, 0xc000
	v_mfma_f32_16x16x32_bf16 v[60:63], v[164:167], v[184:187], v[60:63]
	global_load_lds_dwordx4 v144, s[10:11]
	s_waitcnt lgkmcnt(5)
	v_mfma_f32_16x16x32_bf16 v[64:67], v[152:155], v[172:175], v[64:67]
	ds_read_b128 v[164:167], v168 offset:14336
	v_mfma_f32_16x16x32_bf16 v[68:71], v[152:155], v[176:179], v[68:71]
	v_mfma_f32_16x16x32_bf16 v[72:75], v[152:155], v[180:183], v[72:75]
	s_add_u32 m0, s26, 0x6000
	v_mfma_f32_16x16x32_bf16 v[76:79], v[152:155], v[184:187], v[76:79]
	global_load_lds_dwordx4 v146, s[8:9]
	s_waitcnt lgkmcnt(4)
	v_mfma_f32_16x16x32_bf16 v[80:83], v[156:159], v[172:175], v[80:83]
	ds_read_b128 v[152:155], v169
	v_mfma_f32_16x16x32_bf16 v[84:87], v[156:159], v[176:179], v[84:87]
	v_mfma_f32_16x16x32_bf16 v[88:91], v[156:159], v[180:183], v[88:91]
	s_add_u32 m0, s26, 0xe000
	v_mfma_f32_16x16x32_bf16 v[92:95], v[156:159], v[184:187], v[92:95]
	global_load_lds_dwordx4 v148, s[10:11]
	s_add_u32 s8, s8, 0x80
	s_addc_u32 s9, s9, 0
	s_add_u32 s10, s10, 0x80
	s_addc_u32 s11, s11, 0
	s_waitcnt lgkmcnt(3)
	v_mfma_f32_16x16x32_bf16 v[96:99], v[160:163], v[172:175], v[96:99]
	ds_read_b128 v[156:159], v169 offset:2048
	v_mfma_f32_16x16x32_bf16 v[100:103], v[160:163], v[176:179], v[100:103]
	v_mfma_f32_16x16x32_bf16 v[104:107], v[160:163], v[180:183], v[104:107]
	v_mfma_f32_16x16x32_bf16 v[108:111], v[160:163], v[184:187], v[108:111]
	s_waitcnt lgkmcnt(2)
	v_mfma_f32_16x16x32_bf16 v[112:115], v[164:167], v[172:175], v[112:115]
	ds_read_b128 v[160:163], v169 offset:4096
	v_mfma_f32_16x16x32_bf16 v[116:119], v[164:167], v[176:179], v[116:119]
	v_mfma_f32_16x16x32_bf16 v[120:123], v[164:167], v[180:183], v[120:123]
	v_mfma_f32_16x16x32_bf16 v[124:127], v[164:167], v[184:187], v[124:127]
	s_waitcnt lgkmcnt(2)
	v_mfma_f32_16x16x32_bf16 v[0:3], v[152:155], v[196:199], v[0:3]
	ds_read_b128 v[164:167], v169 offset:6144
	v_mfma_f32_16x16x32_bf16 v[4:7], v[152:155], v[200:203], v[4:7]
	v_mfma_f32_16x16x32_bf16 v[8:11], v[152:155], v[212:215], v[8:11]
	v_mfma_f32_16x16x32_bf16 v[12:15], v[152:155], v[216:219], v[12:15]
	s_waitcnt lgkmcnt(2)
	v_mfma_f32_16x16x32_bf16 v[16:19], v[156:159], v[196:199], v[16:19]
	ds_read_b128 v[152:155], v169 offset:8192
	v_mfma_f32_16x16x32_bf16 v[20:23], v[156:159], v[200:203], v[20:23]
	v_mfma_f32_16x16x32_bf16 v[24:27], v[156:159], v[212:215], v[24:27]
	v_mfma_f32_16x16x32_bf16 v[28:31], v[156:159], v[216:219], v[28:31]
	s_waitcnt lgkmcnt(2)
	v_mfma_f32_16x16x32_bf16 v[32:35], v[160:163], v[196:199], v[32:35]
	ds_read_b128 v[156:159], v169 offset:10240
	v_mfma_f32_16x16x32_bf16 v[36:39], v[160:163], v[200:203], v[36:39]
	v_mfma_f32_16x16x32_bf16 v[40:43], v[160:163], v[212:215], v[40:43]
	v_mfma_f32_16x16x32_bf16 v[44:47], v[160:163], v[216:219], v[44:47]
	s_waitcnt lgkmcnt(2)
	v_mfma_f32_16x16x32_bf16 v[48:51], v[164:167], v[196:199], v[48:51]
	ds_read_b128 v[160:163], v169 offset:12288
	v_mfma_f32_16x16x32_bf16 v[52:55], v[164:167], v[200:203], v[52:55]
	v_mfma_f32_16x16x32_bf16 v[56:59], v[164:167], v[212:215], v[56:59]
	v_mfma_f32_16x16x32_bf16 v[60:63], v[164:167], v[216:219], v[60:63]
	s_waitcnt lgkmcnt(2)
	v_mfma_f32_16x16x32_bf16 v[64:67], v[152:155], v[196:199], v[64:67]
	ds_read_b128 v[164:167], v169 offset:14336
	v_mfma_f32_16x16x32_bf16 v[68:71], v[152:155], v[200:203], v[68:71]
	v_mfma_f32_16x16x32_bf16 v[72:75], v[152:155], v[212:215], v[72:75]
	v_mfma_f32_16x16x32_bf16 v[76:79], v[152:155], v[216:219], v[76:79]
	s_waitcnt lgkmcnt(2)
	v_mfma_f32_16x16x32_bf16 v[80:83], v[156:159], v[196:199], v[80:83]
	v_mfma_f32_16x16x32_bf16 v[84:87], v[156:159], v[200:203], v[84:87]
	v_mfma_f32_16x16x32_bf16 v[88:91], v[156:159], v[212:215], v[88:91]
	v_mfma_f32_16x16x32_bf16 v[92:95], v[156:159], v[216:219], v[92:95]
	s_waitcnt lgkmcnt(0)
	s_waitcnt vmcnt(0)
	s_barrier
	v_xor_b32_e32 v168, 0x10000, v168
	v_xor_b32_e32 v169, 0x10000, v169
	v_xor_b32_e32 v192, 0x10000, v192
	v_xor_b32_e32 v204, 0x10000, v204
	v_mfma_f32_16x16x32_bf16 v[96:99], v[160:163], v[196:199], v[96:99]
	ds_read_b128 v[152:155], v168
	ds_read_b128 v[156:159], v168 offset:2048
	s_add_u32 m0, s26, 0x10000
	v_mfma_f32_16x16x32_bf16 v[100:103], v[160:163], v[200:203], v[100:103]
	global_load_lds_dwordx4 v134, s[8:9]
	v_mfma_f32_16x16x32_bf16 v[104:107], v[160:163], v[212:215], v[104:107]
	ds_read_b128 v[172:175], v192 offset:32768
	ds_read_b128 v[176:179], v192 offset:34816
	s_add_u32 m0, s26, 0x18000
	v_mfma_f32_16x16x32_bf16 v[108:111], v[160:163], v[216:219], v[108:111]
	global_load_lds_dwordx4 v136, s[10:11]
	v_mfma_f32_16x16x32_bf16 v[112:115], v[164:167], v[196:199], v[112:115]
	ds_read_b128 v[160:163], v168 offset:4096
	s_add_u32 m0, s26, 0x12000
	v_mfma_f32_16x16x32_bf16 v[116:119], v[164:167], v[200:203], v[116:119]
	global_load_lds_dwordx4 v138, s[8:9]
	ds_read_b128 v[180:183], v192 offset:36864
	ds_read_b128 v[184:187], v192 offset:38912
	v_mfma_f32_16x16x32_bf16 v[120:123], v[164:167], v[212:215], v[120:123]
	s_add_u32 m0, s26, 0x1a000
	v_mfma_f32_16x16x32_bf16 v[124:127], v[164:167], v[216:219], v[124:127]
	global_load_lds_dwordx4 v140, s[10:11]
	s_waitcnt lgkmcnt(4)
	v_mfma_f32_16x16x32_bf16 v[0:3], v[152:155], v[172:175], v[0:3]
	ds_read_b128 v[164:167], v168 offset:6144
	s_waitcnt lgkmcnt(4)
	v_mfma_f32_16x16x32_bf16 v[4:7], v[152:155], v[176:179], v[4:7]
	ds_read_b128 v[196:199], v204 offset:32768
	s_waitcnt lgkmcnt(3)
	v_mfma_f32_16x16x32_bf16 v[8:11], v[152:155], v[180:183], v[8:11]
	s_waitcnt lgkmcnt(2)
	v_mfma_f32_16x16x32_bf16 v[12:15], v[152:155], v[184:187], v[12:15]
	v_mfma_f32_16x16x32_bf16 v[16:19], v[156:159], v[172:175], v[16:19]
	ds_read_b128 v[152:155], v168 offset:8192
	v_mfma_f32_16x16x32_bf16 v[20:23], v[156:159], v[176:179], v[20:23]
	ds_read_b128 v[200:203], v204 offset:34816
	v_mfma_f32_16x16x32_bf16 v[24:27], v[156:159], v[180:183], v[24:27]
	v_mfma_f32_16x16x32_bf16 v[28:31], v[156:159], v[184:187], v[28:31]
	v_mfma_f32_16x16x32_bf16 v[32:35], v[160:163], v[172:175], v[32:35]
	ds_read_b128 v[156:159], v168 offset:10240
	v_mfma_f32_16x16x32_bf16 v[36:39], v[160:163], v[176:179], v[36:39]
	ds_read_b128 v[212:215], v204 offset:36864
	v_mfma_f32_16x16x32_bf16 v[40:43], v[160:163], v[180:183], v[40:43]
	s_add_u32 m0, s26, 0x14000
	v_mfma_f32_16x16x32_bf16 v[44:47], v[160:163], v[184:187], v[44:47]
	global_load_lds_dwordx4 v142, s[8:9]
	s_waitcnt lgkmcnt(5)
	v_mfma_f32_16x16x32_bf16 v[48:51], v[164:167], v[172:175], v[48:51]
	ds_read_b128 v[160:163], v168 offset:12288
	v_mfma_f32_16x16x32_bf16 v[52:55], v[164:167], v[176:179], v[52:55]
	ds_read_b128 v[216:219], v204 offset:38912
	v_mfma_f32_16x16x32_bf16 v[56:59], v[164:167], v[180:183], v[56:59]
	s_add_u32 m0, s26, 0x1c000
	v_mfma_f32_16x16x32_bf16 v[60:63], v[164:167], v[184:187], v[60:63]
	global_load_lds_dwordx4 v144, s[10:11]
	s_waitcnt lgkmcnt(5)
	v_mfma_f32_16x16x32_bf16 v[64:67], v[152:155], v[172:175], v[64:67]
	ds_read_b128 v[164:167], v168 offset:14336
	v_mfma_f32_16x16x32_bf16 v[68:71], v[152:155], v[176:179], v[68:71]
	v_mfma_f32_16x16x32_bf16 v[72:75], v[152:155], v[180:183], v[72:75]
	s_add_u32 m0, s26, 0x16000
	v_mfma_f32_16x16x32_bf16 v[76:79], v[152:155], v[184:187], v[76:79]
	global_load_lds_dwordx4 v146, s[8:9]
	s_waitcnt lgkmcnt(4)
	v_mfma_f32_16x16x32_bf16 v[80:83], v[156:159], v[172:175], v[80:83]
	ds_read_b128 v[152:155], v169
	v_mfma_f32_16x16x32_bf16 v[84:87], v[156:159], v[176:179], v[84:87]
	v_mfma_f32_16x16x32_bf16 v[88:91], v[156:159], v[180:183], v[88:91]
	s_add_u32 m0, s26, 0x1e000
	v_mfma_f32_16x16x32_bf16 v[92:95], v[156:159], v[184:187], v[92:95]
	global_load_lds_dwordx4 v148, s[10:11]
	s_add_u32 s8, s8, 0x80
	s_addc_u32 s9, s9, 0
	s_add_u32 s10, s10, 0x80
	s_addc_u32 s11, s11, 0
	s_waitcnt lgkmcnt(3)
	v_mfma_f32_16x16x32_bf16 v[96:99], v[160:163], v[172:175], v[96:99]
	ds_read_b128 v[156:159], v169 offset:2048
	v_mfma_f32_16x16x32_bf16 v[100:103], v[160:163], v[176:179], v[100:103]
	v_mfma_f32_16x16x32_bf16 v[104:107], v[160:163], v[180:183], v[104:107]
	v_mfma_f32_16x16x32_bf16 v[108:111], v[160:163], v[184:187], v[108:111]
	s_waitcnt lgkmcnt(2)
	v_mfma_f32_16x16x32_bf16 v[112:115], v[164:167], v[172:175], v[112:115]
	ds_read_b128 v[160:163], v169 offset:4096
	v_mfma_f32_16x16x32_bf16 v[116:119], v[164:167], v[176:179], v[116:119]
	v_mfma_f32_16x16x32_bf16 v[120:123], v[164:167], v[180:183], v[120:123]
	v_mfma_f32_16x16x32_bf16 v[124:127], v[164:167], v[184:187], v[124:127]
	s_waitcnt lgkmcnt(2)
	v_mfma_f32_16x16x32_bf16 v[0:3], v[152:155], v[196:199], v[0:3]
	ds_read_b128 v[164:167], v169 offset:6144
	v_mfma_f32_16x16x32_bf16 v[4:7], v[152:155], v[200:203], v[4:7]
	v_mfma_f32_16x16x32_bf16 v[8:11], v[152:155], v[212:215], v[8:11]
	v_mfma_f32_16x16x32_bf16 v[12:15], v[152:155], v[216:219], v[12:15]
	s_waitcnt lgkmcnt(2)
	v_mfma_f32_16x16x32_bf16 v[16:19], v[156:159], v[196:199], v[16:19]
	ds_read_b128 v[152:155], v169 offset:8192
	v_mfma_f32_16x16x32_bf16 v[20:23], v[156:159], v[200:203], v[20:23]
	v_mfma_f32_16x16x32_bf16 v[24:27], v[156:159], v[212:215], v[24:27]
	v_mfma_f32_16x16x32_bf16 v[28:31], v[156:159], v[216:219], v[28:31]
	s_waitcnt lgkmcnt(2)
	v_mfma_f32_16x16x32_bf16 v[32:35], v[160:163], v[196:199], v[32:35]
	ds_read_b128 v[156:159], v169 offset:10240
	v_mfma_f32_16x16x32_bf16 v[36:39], v[160:163], v[200:203], v[36:39]
	v_mfma_f32_16x16x32_bf16 v[40:43], v[160:163], v[212:215], v[40:43]
	v_mfma_f32_16x16x32_bf16 v[44:47], v[160:163], v[216:219], v[44:47]
	s_waitcnt lgkmcnt(2)
	v_mfma_f32_16x16x32_bf16 v[48:51], v[164:167], v[196:199], v[48:51]
	ds_read_b128 v[160:163], v169 offset:12288
	v_mfma_f32_16x16x32_bf16 v[52:55], v[164:167], v[200:203], v[52:55]
	v_mfma_f32_16x16x32_bf16 v[56:59], v[164:167], v[212:215], v[56:59]
	v_mfma_f32_16x16x32_bf16 v[60:63], v[164:167], v[216:219], v[60:63]
	s_waitcnt lgkmcnt(2)
	v_mfma_f32_16x16x32_bf16 v[64:67], v[152:155], v[196:199], v[64:67]
	ds_read_b128 v[164:167], v169 offset:14336
	v_mfma_f32_16x16x32_bf16 v[68:71], v[152:155], v[200:203], v[68:71]
	v_mfma_f32_16x16x32_bf16 v[72:75], v[152:155], v[212:215], v[72:75]
	v_mfma_f32_16x16x32_bf16 v[76:79], v[152:155], v[216:219], v[76:79]
	s_waitcnt lgkmcnt(2)
	v_mfma_f32_16x16x32_bf16 v[80:83], v[156:159], v[196:199], v[80:83]
	v_mfma_f32_16x16x32_bf16 v[84:87], v[156:159], v[200:203], v[84:87]
	v_mfma_f32_16x16x32_bf16 v[88:91], v[156:159], v[212:215], v[88:91]
	v_mfma_f32_16x16x32_bf16 v[92:95], v[156:159], v[216:219], v[92:95]
	s_waitcnt lgkmcnt(0)
	s_waitcnt vmcnt(0)
	s_barrier
	v_xor_b32_e32 v168, 0x10000, v168
	v_xor_b32_e32 v169, 0x10000, v169
	v_xor_b32_e32 v192, 0x10000, v192
	v_xor_b32_e32 v204, 0x10000, v204
	v_mfma_f32_16x16x32_bf16 v[96:99], v[160:163], v[196:199], v[96:99]
	ds_read_b128 v[152:155], v168
	ds_read_b128 v[156:159], v168 offset:2048
	v_mfma_f32_16x16x32_bf16 v[100:103], v[160:163], v[200:203], v[100:103]
	v_mfma_f32_16x16x32_bf16 v[104:107], v[160:163], v[212:215], v[104:107]
	ds_read_b128 v[172:175], v192 offset:32768
	ds_read_b128 v[176:179], v192 offset:34816
	v_mfma_f32_16x16x32_bf16 v[108:111], v[160:163], v[216:219], v[108:111]
	v_mfma_f32_16x16x32_bf16 v[112:115], v[164:167], v[196:199], v[112:115]
	ds_read_b128 v[160:163], v168 offset:4096
	v_mfma_f32_16x16x32_bf16 v[116:119], v[164:167], v[200:203], v[116:119]
	ds_read_b128 v[180:183], v192 offset:36864
	ds_read_b128 v[184:187], v192 offset:38912
	v_mfma_f32_16x16x32_bf16 v[120:123], v[164:167], v[212:215], v[120:123]
	v_mfma_f32_16x16x32_bf16 v[124:127], v[164:167], v[216:219], v[124:127]
	s_waitcnt lgkmcnt(4)
	v_mfma_f32_16x16x32_bf16 v[0:3], v[152:155], v[172:175], v[0:3]
	ds_read_b128 v[164:167], v168 offset:6144
	s_waitcnt lgkmcnt(4)
	v_mfma_f32_16x16x32_bf16 v[4:7], v[152:155], v[176:179], v[4:7]
	ds_read_b128 v[196:199], v204 offset:32768
	s_waitcnt lgkmcnt(3)
	v_mfma_f32_16x16x32_bf16 v[8:11], v[152:155], v[180:183], v[8:11]
	s_waitcnt lgkmcnt(2)
	v_mfma_f32_16x16x32_bf16 v[12:15], v[152:155], v[184:187], v[12:15]
	v_mfma_f32_16x16x32_bf16 v[16:19], v[156:159], v[172:175], v[16:19]
	ds_read_b128 v[152:155], v168 offset:8192
	v_mfma_f32_16x16x32_bf16 v[20:23], v[156:159], v[176:179], v[20:23]
	ds_read_b128 v[200:203], v204 offset:34816
	v_mfma_f32_16x16x32_bf16 v[24:27], v[156:159], v[180:183], v[24:27]
	v_mfma_f32_16x16x32_bf16 v[28:31], v[156:159], v[184:187], v[28:31]
	v_mfma_f32_16x16x32_bf16 v[32:35], v[160:163], v[172:175], v[32:35]
	ds_read_b128 v[156:159], v168 offset:10240
	v_mfma_f32_16x16x32_bf16 v[36:39], v[160:163], v[176:179], v[36:39]
	ds_read_b128 v[212:215], v204 offset:36864
	v_mfma_f32_16x16x32_bf16 v[40:43], v[160:163], v[180:183], v[40:43]
	v_mfma_f32_16x16x32_bf16 v[44:47], v[160:163], v[184:187], v[44:47]
	s_waitcnt lgkmcnt(5)
	v_mfma_f32_16x16x32_bf16 v[48:51], v[164:167], v[172:175], v[48:51]
	ds_read_b128 v[160:163], v168 offset:12288
	v_mfma_f32_16x16x32_bf16 v[52:55], v[164:167], v[176:179], v[52:55]
	ds_read_b128 v[216:219], v204 offset:38912
	v_mfma_f32_16x16x32_bf16 v[56:59], v[164:167], v[180:183], v[56:59]
	v_mfma_f32_16x16x32_bf16 v[60:63], v[164:167], v[184:187], v[60:63]
	s_waitcnt lgkmcnt(5)
	v_mfma_f32_16x16x32_bf16 v[64:67], v[152:155], v[172:175], v[64:67]
	ds_read_b128 v[164:167], v168 offset:14336
	v_mfma_f32_16x16x32_bf16 v[68:71], v[152:155], v[176:179], v[68:71]
	v_mfma_f32_16x16x32_bf16 v[72:75], v[152:155], v[180:183], v[72:75]
	v_mfma_f32_16x16x32_bf16 v[76:79], v[152:155], v[184:187], v[76:79]
	s_waitcnt lgkmcnt(4)
	v_mfma_f32_16x16x32_bf16 v[80:83], v[156:159], v[172:175], v[80:83]
	ds_read_b128 v[152:155], v169
	v_mfma_f32_16x16x32_bf16 v[84:87], v[156:159], v[176:179], v[84:87]
	v_mfma_f32_16x16x32_bf16 v[88:91], v[156:159], v[180:183], v[88:91]
	v_mfma_f32_16x16x32_bf16 v[92:95], v[156:159], v[184:187], v[92:95]
	s_waitcnt lgkmcnt(3)
	v_mfma_f32_16x16x32_bf16 v[96:99], v[160:163], v[172:175], v[96:99]
	ds_read_b128 v[156:159], v169 offset:2048
	v_mfma_f32_16x16x32_bf16 v[100:103], v[160:163], v[176:179], v[100:103]
	v_mfma_f32_16x16x32_bf16 v[104:107], v[160:163], v[180:183], v[104:107]
	v_mfma_f32_16x16x32_bf16 v[108:111], v[160:163], v[184:187], v[108:111]
	s_waitcnt lgkmcnt(2)
	v_mfma_f32_16x16x32_bf16 v[112:115], v[164:167], v[172:175], v[112:115]
	ds_read_b128 v[160:163], v169 offset:4096
	v_mfma_f32_16x16x32_bf16 v[116:119], v[164:167], v[176:179], v[116:119]
	v_mfma_f32_16x16x32_bf16 v[120:123], v[164:167], v[180:183], v[120:123]
	v_mfma_f32_16x16x32_bf16 v[124:127], v[164:167], v[184:187], v[124:127]
	s_waitcnt lgkmcnt(2)
	v_mfma_f32_16x16x32_bf16 v[0:3], v[152:155], v[196:199], v[0:3]
	ds_read_b128 v[164:167], v169 offset:6144
	v_mfma_f32_16x16x32_bf16 v[4:7], v[152:155], v[200:203], v[4:7]
	v_mfma_f32_16x16x32_bf16 v[8:11], v[152:155], v[212:215], v[8:11]
	v_mfma_f32_16x16x32_bf16 v[12:15], v[152:155], v[216:219], v[12:15]
	s_waitcnt lgkmcnt(2)
	v_mfma_f32_16x16x32_bf16 v[16:19], v[156:159], v[196:199], v[16:19]
	ds_read_b128 v[152:155], v169 offset:8192
	v_mfma_f32_16x16x32_bf16 v[20:23], v[156:159], v[200:203], v[20:23]
	v_mfma_f32_16x16x32_bf16 v[24:27], v[156:159], v[212:215], v[24:27]
	v_mfma_f32_16x16x32_bf16 v[28:31], v[156:159], v[216:219], v[28:31]
	s_waitcnt lgkmcnt(2)
	v_mfma_f32_16x16x32_bf16 v[32:35], v[160:163], v[196:199], v[32:35]
	ds_read_b128 v[156:159], v169 offset:10240
	v_mfma_f32_16x16x32_bf16 v[36:39], v[160:163], v[200:203], v[36:39]
	v_mfma_f32_16x16x32_bf16 v[40:43], v[160:163], v[212:215], v[40:43]
	v_mfma_f32_16x16x32_bf16 v[44:47], v[160:163], v[216:219], v[44:47]
	s_waitcnt lgkmcnt(2)
	v_mfma_f32_16x16x32_bf16 v[48:51], v[164:167], v[196:199], v[48:51]
	ds_read_b128 v[160:163], v169 offset:12288
	v_mfma_f32_16x16x32_bf16 v[52:55], v[164:167], v[200:203], v[52:55]
	v_mfma_f32_16x16x32_bf16 v[56:59], v[164:167], v[212:215], v[56:59]
	v_mfma_f32_16x16x32_bf16 v[60:63], v[164:167], v[216:219], v[60:63]
	s_waitcnt lgkmcnt(2)
	v_mfma_f32_16x16x32_bf16 v[64:67], v[152:155], v[196:199], v[64:67]
	ds_read_b128 v[164:167], v169 offset:14336
	v_mfma_f32_16x16x32_bf16 v[68:71], v[152:155], v[200:203], v[68:71]
	v_mfma_f32_16x16x32_bf16 v[72:75], v[152:155], v[212:215], v[72:75]
	v_mfma_f32_16x16x32_bf16 v[76:79], v[152:155], v[216:219], v[76:79]
	s_waitcnt lgkmcnt(2)
	v_mfma_f32_16x16x32_bf16 v[80:83], v[156:159], v[196:199], v[80:83]
	v_mfma_f32_16x16x32_bf16 v[84:87], v[156:159], v[200:203], v[84:87]
	v_mfma_f32_16x16x32_bf16 v[88:91], v[156:159], v[212:215], v[88:91]
	v_mfma_f32_16x16x32_bf16 v[92:95], v[156:159], v[216:219], v[92:95]
	s_waitcnt lgkmcnt(0)
	s_waitcnt vmcnt(0)
	s_barrier
	v_xor_b32_e32 v168, 0x10000, v168
	v_xor_b32_e32 v169, 0x10000, v169
	v_xor_b32_e32 v192, 0x10000, v192
	v_xor_b32_e32 v204, 0x10000, v204
	v_mfma_f32_16x16x32_bf16 v[96:99], v[160:163], v[196:199], v[96:99]
	v_mfma_f32_16x16x32_bf16 v[100:103], v[160:163], v[200:203], v[100:103]
	v_mfma_f32_16x16x32_bf16 v[104:107], v[160:163], v[212:215], v[104:107]
	v_mfma_f32_16x16x32_bf16 v[108:111], v[160:163], v[216:219], v[108:111]
	v_mfma_f32_16x16x32_bf16 v[112:115], v[164:167], v[196:199], v[112:115]
	v_mfma_f32_16x16x32_bf16 v[116:119], v[164:167], v[200:203], v[116:119]
	v_mfma_f32_16x16x32_bf16 v[120:123], v[164:167], v[212:215], v[120:123]
	v_mfma_f32_16x16x32_bf16 v[124:127], v[164:167], v[216:219], v[124:127]
	v_lshl_add_u64 v[150:151], s[6:7], 1, v[128:129]
	s_mov_b32 m0, s14
	s_mov_b32 s10, 0
	s_mov_b64 s[8:9], -1
	s_nop 7
	s_nop 3
	s_branch .LBB0_428

.LBB0_428:
	v_mov_b32_e32 v152, v195
	s_nop 0
	v_ashrrev_i32_e32 v153, 8, v152
	v_cmp_eq_u32_e32 vcc, s10, v153
	s_and_saveexec_b64 s[6:7], vcc
	s_cbranch_execz .LBB0_430
	v_bfe_i32 v153, v195, 7, 1
	v_and_b32_e32 v153, 0x10c00, v153
	v_and_b32_e32 v154, 0x4f, v195
	v_lshl_or_b32 v153, v154, 2, v153
	v_bfe_u32 v152, v195, 4, 2
	v_mul_u32_u24_e32 v152, 0x840, v152
	v_add_u32_e32 v152, v152, v153
	v_mov_b32_e32 v153, v152
	v_add_u32_e32 v154, 0x420, v152
	ds_write2_b32 v153, v0, v1 offset1:132
	ds_write2_b32 v154, v2, v3 offset1:132
	ds_write2_b32 v153, v4, v5 offset0:16 offset1:148
	ds_write2_b32 v154, v6, v7 offset0:16 offset1:148
	ds_write2_b32 v153, v8, v9 offset0:32 offset1:164
	ds_write2_b32 v154, v10, v11 offset0:32 offset1:164
	ds_write2_b32 v153, v12, v13 offset0:48 offset1:180
	ds_write2_b32 v154, v14, v15 offset0:48 offset1:180
	v_add_u32_e32 v153, 0x2100, v152
	v_add_u32_e32 v154, 0x2520, v152
	ds_write2_b32 v153, v16, v17 offset1:132
	ds_write2_b32 v154, v18, v19 offset1:132
	ds_write2_b32 v153, v20, v21 offset0:16 offset1:148
	ds_write2_b32 v154, v22, v23 offset0:16 offset1:148
	ds_write2_b32 v153, v24, v25 offset0:32 offset1:164
	ds_write2_b32 v154, v26, v27 offset0:32 offset1:164
	ds_write2_b32 v153, v28, v29 offset0:48 offset1:180
	ds_write2_b32 v154, v30, v31 offset0:48 offset1:180
	v_add_u32_e32 v153, 0x4200, v152
	v_add_u32_e32 v154, 0x4620, v152
	ds_write2_b32 v153, v32, v33 offset1:132
	ds_write2_b32 v154, v34, v35 offset1:132
	ds_write2_b32 v153, v36, v37 offset0:16 offset1:148
	ds_write2_b32 v154, v38, v39 offset0:16 offset1:148
	ds_write2_b32 v153, v40, v41 offset0:32 offset1:164
	ds_write2_b32 v154, v42, v43 offset0:32 offset1:164
	ds_write2_b32 v153, v44, v45 offset0:48 offset1:180
	ds_write2_b32 v154, v46, v47 offset0:48 offset1:180
	v_add_u32_e32 v153, 0x6300, v152
	v_add_u32_e32 v154, 0x6720, v152
	ds_write2_b32 v153, v48, v49 offset1:132
	ds_write2_b32 v154, v50, v51 offset1:132
	ds_write2_b32 v153, v52, v53 offset0:16 offset1:148
	ds_write2_b32 v154, v54, v55 offset0:16 offset1:148
	ds_write2_b32 v153, v56, v57 offset0:32 offset1:164
	ds_write2_b32 v154, v58, v59 offset0:32 offset1:164
	ds_write2_b32 v153, v60, v61 offset0:48 offset1:180
	ds_write2_b32 v154, v62, v63 offset0:48 offset1:180
	v_add_u32_e32 v153, 0x8400, v152
	v_add_u32_e32 v154, 0x8820, v152
	ds_write2_b32 v153, v64, v65 offset1:132
	ds_write2_b32 v154, v66, v67 offset1:132
	ds_write2_b32 v153, v68, v69 offset0:16 offset1:148
	ds_write2_b32 v154, v70, v71 offset0:16 offset1:148
	ds_write2_b32 v153, v72, v73 offset0:32 offset1:164
	ds_write2_b32 v154, v74, v75 offset0:32 offset1:164
	ds_write2_b32 v153, v76, v77 offset0:48 offset1:180
	ds_write2_b32 v154, v78, v79 offset0:48 offset1:180
	v_add_u32_e32 v153, 0xa500, v152
	v_add_u32_e32 v154, 0xa920, v152
	ds_write2_b32 v153, v80, v81 offset1:132
	ds_write2_b32 v154, v82, v83 offset1:132
	ds_write2_b32 v153, v84, v85 offset0:16 offset1:148
	ds_write2_b32 v154, v86, v87 offset0:16 offset1:148
	ds_write2_b32 v153, v88, v89 offset0:32 offset1:164
	ds_write2_b32 v154, v90, v91 offset0:32 offset1:164
	ds_write2_b32 v153, v92, v93 offset0:48 offset1:180
	ds_write2_b32 v154, v94, v95 offset0:48 offset1:180
	v_add_u32_e32 v153, 0xc600, v152
	v_add_u32_e32 v154, 0xca20, v152
	ds_write2_b32 v153, v96, v97 offset1:132
	ds_write2_b32 v154, v98, v99 offset1:132
	ds_write2_b32 v153, v100, v101 offset0:16 offset1:148
	ds_write2_b32 v154, v102, v103 offset0:16 offset1:148
	ds_write2_b32 v153, v104, v105 offset0:32 offset1:164
	ds_write2_b32 v154, v106, v107 offset0:32 offset1:164
	ds_write2_b32 v153, v108, v109 offset0:48 offset1:180
	ds_write2_b32 v154, v110, v111 offset0:48 offset1:180
	v_add_u32_e32 v153, 0xe700, v152
	v_add_u32_e32 v154, 0xeb20, v152
	ds_write2_b32 v153, v112, v113 offset1:132
	ds_write2_b32 v154, v114, v115 offset1:132
	ds_write2_b32 v153, v116, v117 offset0:16 offset1:148
	ds_write2_b32 v154, v118, v119 offset0:16 offset1:148
	ds_write2_b32 v153, v120, v121 offset0:32 offset1:164
	ds_write2_b32 v154, v122, v123 offset0:32 offset1:164
	ds_write2_b32 v153, v124, v125 offset0:48 offset1:180
	ds_write2_b32 v154, v126, v127 offset0:48 offset1:180

.LBB0_733:
	s_lshl_b32 s44, s53, 3
	v_readlane_b32 s45, v254, 21
	s_or_b32 s46, s44, s45
	s_cmp_lt_i32 s46, s50
	v_readlane_b32 s48, v254, 14
	s_cselect_b64 s[44:45], -1, 0
	v_readlane_b32 s49, v254, 15
	s_lshl_b32 s46, s46, 3
	v_readlane_b32 s47, v254, 22
	s_and_b64 s[44:45], s[48:49], s[44:45]
	s_add_i32 s60, s46, s47
	s_cmp_lt_i32 s60, s20
	s_cselect_b64 s[46:47], -1, 0
	s_and_b64 s[48:49], s[44:45], exec
	v_readlane_b32 s48, v253, 15
	s_cselect_b32 s55, s60, s55
	s_cselect_b32 s54, s48, s54
	s_and_b64 s[44:45], s[44:45], s[46:47]
	s_andn2_b64 vcc, exec, s[44:45]
	s_cbranch_vccnz .LBB0_732
	ds_read2_b32 v[0:1], v224 offset1:1
	ds_read2_b32 v[2:3], v225 offset1:1
	ds_read2_b32 v[4:5], v226 offset1:1
	ds_read2_b32 v[6:7], v227 offset1:1
	v_mov_b32_e32 v20, v195
	s_waitcnt lgkmcnt(3)
	v_cmp_ge_i32_e32 vcc, s55, v0
	v_lshl_add_u32 v12, s54, 18, v165
	v_mov_b32_e32 v9, v193
	v_cndmask_b32_e64 v0, 0, 1, vcc
	v_cmp_lt_i32_e32 vcc, s55, v1
	v_add_u32_e32 v8, v12, v163
	v_mov_b32_e32 v11, v193
	v_cndmask_b32_e32 v0, 2, v0, vcc
	s_waitcnt lgkmcnt(2)
	v_cmp_lt_i32_e32 vcc, s55, v2
	v_lshlrev_b64 v[130:131], 1, v[8:9]
	s_mov_b64 s[72:73], 0x100
	v_cndmask_b32_e32 v0, 3, v0, vcc
	v_cmp_lt_i32_e32 vcc, s55, v3
	s_nop 1
	v_cndmask_b32_e32 v0, 4, v0, vcc
	s_waitcnt lgkmcnt(1)
	v_cmp_lt_i32_e32 vcc, s55, v4
	s_nop 1
	v_cndmask_b32_e32 v0, 5, v0, vcc
	v_cmp_lt_i32_e32 vcc, s55, v5
	s_nop 1
	v_cndmask_b32_e32 v0, 6, v0, vcc
	s_waitcnt lgkmcnt(0)
	v_cmp_lt_i32_e32 vcc, s55, v6
	s_nop 1
	v_cndmask_b32_e32 v2, 7, v0, vcc
	ds_read2_b32 v[0:1], v228 offset1:1
	v_cmp_lt_i32_e32 vcc, s55, v7
	s_nop 1
	v_cndmask_b32_e32 v6, 8, v2, vcc
	ds_read2_b32 v[2:3], v229 offset1:1
	ds_read2_b32 v[4:5], v230 offset1:1
	ds_read_b32 v7, v231
	s_waitcnt lgkmcnt(3)
	v_cmp_lt_i32_e32 vcc, s55, v0
	s_nop 1
	v_cndmask_b32_e32 v0, 9, v6, vcc
	v_cmp_lt_i32_e32 vcc, s55, v1
	s_nop 1
	v_cndmask_b32_e32 v0, 10, v0, vcc
	s_waitcnt lgkmcnt(2)
	v_cmp_lt_i32_e32 vcc, s55, v2
	s_nop 1
	v_cndmask_b32_e32 v0, 11, v0, vcc
	v_cmp_lt_i32_e32 vcc, s55, v3
	s_nop 1
	v_cndmask_b32_e32 v0, 12, v0, vcc
	s_waitcnt lgkmcnt(1)
	v_cmp_lt_i32_e32 vcc, s55, v4
	s_nop 1
	v_cndmask_b32_e32 v0, 13, v0, vcc
	v_cmp_lt_i32_e32 vcc, s55, v5
	s_nop 1
	v_cndmask_b32_e32 v0, 14, v0, vcc
	s_waitcnt lgkmcnt(0)
	v_cmp_lt_i32_e32 vcc, s55, v7
	s_nop 1
	v_cndmask_b32_e32 v10, 15, v0, vcc
	v_lshlrev_b32_e32 v0, 2, v10
	v_add_u32_e32 v0, 0x24000, v0
	ds_read_b32 v1, v0 offset:128
	ds_read2_b32 v[140:141], v0 offset1:16
	s_waitcnt lgkmcnt(1)
	v_readfirstlane_b32 s44, v1
	s_sub_i32 s44, s55, s44
	s_lshl_b32 s60, s44, 8
	v_add_u32_e32 v6, s60, v156
	s_waitcnt lgkmcnt(0)
	v_add_u32_e32 v7, -1, v140
	s_mov_b32 s44, 0xc000
	v_mul_hi_u32 v129, v10, s44
	v_mul_lo_u32 v128, v10, s44
	v_min_i32_e32 v2, v6, v7
	v_lshl_add_u64 v[0:1], s[0:1], 0, v[128:129]
	v_ashrrev_i32_e32 v3, 31, v2
	v_lshl_add_u64 v[2:3], v[2:3], 2, v[0:1]
	global_load_dword v13, v[2:3], off
	v_add_u32_e32 v2, 64, v6
	v_min_i32_e32 v2, v2, v7
	v_add_u32_e32 v4, 0x80, v6
	v_add_u32_e32 v6, 0xc0, v6
	v_ashrrev_i32_e32 v3, 31, v2
	v_min_i32_e32 v4, v4, v7
	v_min_i32_e32 v6, v6, v7
	v_lshl_add_u64 v[2:3], v[2:3], 2, v[0:1]
	v_ashrrev_i32_e32 v5, 31, v4
	v_ashrrev_i32_e32 v7, 31, v6
	v_lshl_add_u64 v[4:5], v[4:5], 2, v[0:1]
	v_lshl_add_u64 v[0:1], v[6:7], 2, v[0:1]
	global_load_dword v2, v[2:3], off
	s_nop 0
	global_load_dword v6, v[4:5], off
	global_load_dword v14, v[0:1], off
	v_mov_b32_e32 v1, v193
	v_readfirstlane_b32 s44, v20
	v_or_b32_e32 v0, v12, v157
	s_lshl_b32 s44, s44, 4
	v_lshlrev_b64 v[134:135], 1, v[0:1]
	v_add_u32_e32 v0, s51, v10
	s_and_b32 s68, s44, 0xfffffc00
	s_movk_i32 s44, 0xfc00
	v_ashrrev_i32_e32 v1, 31, v0
	v_lshlrev_b64 v[0:1], 21, v[0:1]
	v_mov_b32_e32 v3, v193
	v_lshl_add_u64 v[142:143], s[6:7], 0, v[0:1]
	v_mov_b32_e32 v5, v193
	v_add_u32_e32 v4, v12, v162
	v_lshl_add_u64 v[0:1], v[142:143], 0, v[134:135]
	s_add_i32 s67, s68, 0x8000
	v_mov_b32_e32 v7, v193
	v_lshlrev_b64 v[132:133], 1, v[4:5]
	s_add_i32 s66, s68, 0x2000
	v_lshl_add_u64 v[4:5], v[142:143], 0, v[132:133]
	s_add_i32 s65, s68, 0xa000
	s_add_i32 s64, s68, 0x4000
	v_add_u32_e32 v12, v12, v164
	v_lshl_add_u64 v[8:9], v[142:143], 0, v[130:131]
	s_add_i32 s63, s68, 0xc000
	s_add_i32 s69, s68, 0x6000
	s_add_i32 s70, s68, 0xe000
	v_and_b32_e32 v17, 31, v20
	v_lshrrev_b32_e32 v16, 5, v20
	s_add_i32 s45, s68, 0x10000
	s_waitcnt vmcnt(3)
	v_lshlrev_b32_e32 v10, 9, v13
	v_and_or_b32 v192, v10, s44, v157
	v_lshlrev_b64 v[150:151], 1, v[192:193]
	v_mov_b32_e32 v13, v193
	v_lshlrev_b64 v[152:153], 1, v[12:13]
	s_waitcnt vmcnt(2)
	v_lshlrev_b32_e32 v2, 9, v2
	s_waitcnt vmcnt(1)
	v_lshlrev_b32_e32 v6, 9, v6
	s_waitcnt vmcnt(0)
	v_lshlrev_b32_e32 v10, 9, v14
	v_and_or_b32 v2, v2, s44, v157
	v_and_or_b32 v6, v6, s44, v157
	v_and_or_b32 v10, v10, s44, v157
	v_lshl_add_u64 v[14:15], s[4:5], 0, v[150:151]
	s_mov_b32 s44, m0
	s_mov_b32 m0, s68
	s_nop 0
	global_load_lds_dwordx4 v[14:15], off
	s_mov_b32 m0, s44
	v_lshlrev_b64 v[148:149], 1, v[2:3]
	s_mov_b32 s44, m0
	s_mov_b32 m0, s67
	s_nop 0
	global_load_lds_dwordx4 v[0:1], off
	s_mov_b32 m0, s44
	v_lshl_add_u64 v[2:3], s[4:5], 0, v[148:149]
	s_mov_b32 s44, m0
	s_mov_b32 m0, s66
	s_nop 0
	global_load_lds_dwordx4 v[2:3], off
	s_mov_b32 m0, s44
	v_lshlrev_b64 v[146:147], 1, v[6:7]
	s_mov_b32 s44, m0
	s_mov_b32 m0, s65
	s_nop 0
	global_load_lds_dwordx4 v[4:5], off
	s_mov_b32 m0, s44
	v_lshl_add_u64 v[6:7], s[4:5], 0, v[146:147]
	s_mov_b32 s44, m0
	s_mov_b32 m0, s64
	s_nop 0
	global_load_lds_dwordx4 v[6:7], off
	s_mov_b32 m0, s44
	v_lshlrev_b64 v[144:145], 1, v[10:11]
	s_mov_b32 s44, m0
	s_mov_b32 m0, s63
	s_nop 0
	global_load_lds_dwordx4 v[8:9], off
	s_mov_b32 m0, s44
	v_lshl_add_u64 v[10:11], s[4:5], 0, v[144:145]
	s_mov_b32 s44, m0
	s_mov_b32 m0, s69
	s_nop 0
	global_load_lds_dwordx4 v[10:11], off
	s_mov_b32 m0, s44
	v_lshl_add_u64 v[0:1], v[142:143], 0, v[152:153]
	s_mov_b32 s44, m0
	s_mov_b32 m0, s70
	s_nop 0
	global_load_lds_dwordx4 v[0:1], off
	s_mov_b32 m0, s44
	v_lshrrev_b32_e32 v0, 1, v20
	s_mov_b32 s44, 0x1ffff80
	v_bfe_u32 v1, v20, 1, 3
	v_and_or_b32 v0, v0, s44, v17
	v_lshlrev_b32_e32 v168, 7, v0
	v_bitop3_b32 v0, v16, v1, 1 bitop3:0x6c
	v_lshlrev_b32_e32 v171, 4, v0
	v_lshl_add_u64 v[0:1], s[8:9], 0, v[150:151]
	s_waitcnt vmcnt(0)
	s_barrier
	s_mov_b32 s61, m0
	s_mov_b32 s62, s4
	s_mov_b32 s63, s5
	v_readfirstlane_b32 s64, v142
	v_readfirstlane_b32 s65, v143
	v_and_b32_e32 v4, 15, v195
	v_lshrrev_b32_e32 v5, 8, v195
	v_lshl_add_u32 v5, v5, 7, v4
	v_lshlrev_b32_e32 v5, 7, v5
	v_bfe_u32 v6, v195, 4, 2
	v_bfe_u32 v7, v195, 1, 3
	v_xor_b32_e32 v6, v6, v7
	v_lshlrev_b32_e32 v6, 4, v6
	v_or_b32_e32 v154, v5, v6
	v_xor_b32_e32 v155, 64, v154
	v_bfe_u32 v7, v195, 6, 2
	v_lshl_add_u32 v7, v7, 6, v4
	v_lshlrev_b32_e32 v7, 7, v7
	v_or_b32_e32 v167, v7, v6
	v_xor_b32_e32 v192, 64, v167
	s_add_u32 s62, s62, 0x80
	s_addc_u32 s63, s63, 0
	s_add_u32 s64, s64, 0x80
	s_addc_u32 s65, s65, 0
	ds_read_b128 v[184:187], v167 offset:32768
	ds_read_b128 v[196:199], v167 offset:34816
	ds_read_b128 v[200:203], v167 offset:36864
	ds_read_b128 v[240:243], v167 offset:38912
	ds_read_b128 v[168:171], v154
	ds_read_b128 v[172:175], v154 offset:2048
	ds_read_b128 v[176:179], v154 offset:4096
	s_add_u32 m0, s68, 0x10000
	s_nop 0
	global_load_lds_dwordx4 v150, s[62:63]
	s_add_u32 m0, s68, 0x18000
	s_nop 0
	global_load_lds_dwordx4 v134, s[64:65]
	s_add_u32 m0, s68, 0x12000
	s_nop 0
	global_load_lds_dwordx4 v148, s[62:63]
	s_add_u32 m0, s68, 0x1a000
	s_nop 0
	global_load_lds_dwordx4 v132, s[64:65]
	s_add_u32 m0, s68, 0x14000
	s_nop 0
	global_load_lds_dwordx4 v146, s[62:63]
	s_add_u32 m0, s68, 0x1c000
	s_nop 0
	global_load_lds_dwordx4 v130, s[64:65]
	s_add_u32 m0, s68, 0x16000
	s_nop 0
	global_load_lds_dwordx4 v144, s[62:63]
	s_add_u32 m0, s68, 0x1e000
	s_nop 0
	global_load_lds_dwordx4 v152, s[64:65]
	s_add_u32 s62, s62, 0x80
	s_addc_u32 s63, s63, 0
	s_add_u32 s64, s64, 0x80
	s_addc_u32 s65, s65, 0
	s_waitcnt lgkmcnt(2)
	v_mfma_f32_16x16x32_bf16 v[0:3], v[168:171], v[184:187], 0
	ds_read_b128 v[180:183], v154 offset:6144
	v_mfma_f32_16x16x32_bf16 v[4:7], v[168:171], v[196:199], 0
	ds_read_b128 v[244:247], v192 offset:32768
	v_mfma_f32_16x16x32_bf16 v[8:11], v[168:171], v[200:203], 0
	v_mfma_f32_16x16x32_bf16 v[12:15], v[168:171], v[240:243], 0
	s_waitcnt lgkmcnt(3)
	v_mfma_f32_16x16x32_bf16 v[16:19], v[172:175], v[184:187], 0
	ds_read_b128 v[168:171], v154 offset:8192
	v_mfma_f32_16x16x32_bf16 v[20:23], v[172:175], v[196:199], 0
	ds_read_b128 v[212:215], v192 offset:34816
	v_mfma_f32_16x16x32_bf16 v[24:27], v[172:175], v[200:203], 0
	v_mfma_f32_16x16x32_bf16 v[28:31], v[172:175], v[240:243], 0
	s_waitcnt lgkmcnt(4)
	v_mfma_f32_16x16x32_bf16 v[32:35], v[176:179], v[184:187], 0
	ds_read_b128 v[172:175], v154 offset:10240
	v_mfma_f32_16x16x32_bf16 v[36:39], v[176:179], v[196:199], 0
	ds_read_b128 v[216:219], v192 offset:36864
	v_mfma_f32_16x16x32_bf16 v[40:43], v[176:179], v[200:203], 0
	v_mfma_f32_16x16x32_bf16 v[44:47], v[176:179], v[240:243], 0
	s_waitcnt lgkmcnt(5)
	v_mfma_f32_16x16x32_bf16 v[48:51], v[180:183], v[184:187], 0
	ds_read_b128 v[176:179], v154 offset:12288
	v_mfma_f32_16x16x32_bf16 v[52:55], v[180:183], v[196:199], 0
	ds_read_b128 v[248:251], v192 offset:38912
	v_mfma_f32_16x16x32_bf16 v[56:59], v[180:183], v[200:203], 0
	v_mfma_f32_16x16x32_bf16 v[60:63], v[180:183], v[240:243], 0
	s_waitcnt lgkmcnt(5)
	v_mfma_f32_16x16x32_bf16 v[64:67], v[168:171], v[184:187], 0
	ds_read_b128 v[180:183], v154 offset:14336
	v_mfma_f32_16x16x32_bf16 v[68:71], v[168:171], v[196:199], 0
	v_mfma_f32_16x16x32_bf16 v[72:75], v[168:171], v[200:203], 0
	v_mfma_f32_16x16x32_bf16 v[76:79], v[168:171], v[240:243], 0
	s_waitcnt lgkmcnt(4)
	v_mfma_f32_16x16x32_bf16 v[80:83], v[172:175], v[184:187], 0
	ds_read_b128 v[168:171], v155
	v_mfma_f32_16x16x32_bf16 v[84:87], v[172:175], v[196:199], 0
	v_mfma_f32_16x16x32_bf16 v[88:91], v[172:175], v[200:203], 0
	v_mfma_f32_16x16x32_bf16 v[92:95], v[172:175], v[240:243], 0
	s_waitcnt lgkmcnt(3)
	v_mfma_f32_16x16x32_bf16 v[96:99], v[176:179], v[184:187], 0
	ds_read_b128 v[172:175], v155 offset:2048
	v_mfma_f32_16x16x32_bf16 v[100:103], v[176:179], v[196:199], 0
	v_mfma_f32_16x16x32_bf16 v[104:107], v[176:179], v[200:203], 0
	v_mfma_f32_16x16x32_bf16 v[108:111], v[176:179], v[240:243], 0
	s_waitcnt lgkmcnt(2)
	v_mfma_f32_16x16x32_bf16 v[112:115], v[180:183], v[184:187], 0
	ds_read_b128 v[176:179], v155 offset:4096
	v_mfma_f32_16x16x32_bf16 v[116:119], v[180:183], v[196:199], 0
	v_mfma_f32_16x16x32_bf16 v[120:123], v[180:183], v[200:203], 0
	v_mfma_f32_16x16x32_bf16 v[124:127], v[180:183], v[240:243], 0
	s_waitcnt lgkmcnt(2)
	v_mfma_f32_16x16x32_bf16 v[0:3], v[168:171], v[244:247], v[0:3]
	ds_read_b128 v[180:183], v155 offset:6144
	v_mfma_f32_16x16x32_bf16 v[4:7], v[168:171], v[212:215], v[4:7]
	v_mfma_f32_16x16x32_bf16 v[8:11], v[168:171], v[216:219], v[8:11]
	v_mfma_f32_16x16x32_bf16 v[12:15], v[168:171], v[248:251], v[12:15]
	s_waitcnt lgkmcnt(2)
	v_mfma_f32_16x16x32_bf16 v[16:19], v[172:175], v[244:247], v[16:19]
	ds_read_b128 v[168:171], v155 offset:8192
	v_mfma_f32_16x16x32_bf16 v[20:23], v[172:175], v[212:215], v[20:23]
	v_mfma_f32_16x16x32_bf16 v[24:27], v[172:175], v[216:219], v[24:27]
	v_mfma_f32_16x16x32_bf16 v[28:31], v[172:175], v[248:251], v[28:31]
	s_waitcnt lgkmcnt(2)
	v_mfma_f32_16x16x32_bf16 v[32:35], v[176:179], v[244:247], v[32:35]
	ds_read_b128 v[172:175], v155 offset:10240
	v_mfma_f32_16x16x32_bf16 v[36:39], v[176:179], v[212:215], v[36:39]
	v_mfma_f32_16x16x32_bf16 v[40:43], v[176:179], v[216:219], v[40:43]
	v_mfma_f32_16x16x32_bf16 v[44:47], v[176:179], v[248:251], v[44:47]
	s_waitcnt lgkmcnt(2)
	v_mfma_f32_16x16x32_bf16 v[48:51], v[180:183], v[244:247], v[48:51]
	ds_read_b128 v[176:179], v155 offset:12288
	v_mfma_f32_16x16x32_bf16 v[52:55], v[180:183], v[212:215], v[52:55]
	v_mfma_f32_16x16x32_bf16 v[56:59], v[180:183], v[216:219], v[56:59]
	v_mfma_f32_16x16x32_bf16 v[60:63], v[180:183], v[248:251], v[60:63]
	s_waitcnt lgkmcnt(2)
	v_mfma_f32_16x16x32_bf16 v[64:67], v[168:171], v[244:247], v[64:67]
	ds_read_b128 v[180:183], v155 offset:14336
	v_mfma_f32_16x16x32_bf16 v[68:71], v[168:171], v[212:215], v[68:71]
	v_mfma_f32_16x16x32_bf16 v[72:75], v[168:171], v[216:219], v[72:75]
	v_mfma_f32_16x16x32_bf16 v[76:79], v[168:171], v[248:251], v[76:79]
	s_waitcnt lgkmcnt(2)
	v_mfma_f32_16x16x32_bf16 v[80:83], v[172:175], v[244:247], v[80:83]
	v_mfma_f32_16x16x32_bf16 v[84:87], v[172:175], v[212:215], v[84:87]
	v_mfma_f32_16x16x32_bf16 v[88:91], v[172:175], v[216:219], v[88:91]
	v_mfma_f32_16x16x32_bf16 v[92:95], v[172:175], v[248:251], v[92:95]
	s_waitcnt lgkmcnt(0)
	s_waitcnt vmcnt(0)
	s_barrier
	v_xor_b32_e32 v154, 0x10000, v154
	v_xor_b32_e32 v155, 0x10000, v155
	v_xor_b32_e32 v167, 0x10000, v167
	v_xor_b32_e32 v192, 0x10000, v192
	v_mfma_f32_16x16x32_bf16 v[96:99], v[176:179], v[244:247], v[96:99]
	ds_read_b128 v[168:171], v154
	ds_read_b128 v[172:175], v154 offset:2048
	s_mov_b32 m0, s68
	v_mfma_f32_16x16x32_bf16 v[100:103], v[176:179], v[212:215], v[100:103]
	global_load_lds_dwordx4 v150, s[62:63]
	v_mfma_f32_16x16x32_bf16 v[104:107], v[176:179], v[216:219], v[104:107]
	ds_read_b128 v[184:187], v167 offset:32768
	ds_read_b128 v[196:199], v167 offset:34816
	s_add_u32 m0, s68, 0x8000
	v_mfma_f32_16x16x32_bf16 v[108:111], v[176:179], v[248:251], v[108:111]
	global_load_lds_dwordx4 v134, s[64:65]
	v_mfma_f32_16x16x32_bf16 v[112:115], v[180:183], v[244:247], v[112:115]
	ds_read_b128 v[176:179], v154 offset:4096
	s_add_u32 m0, s68, 0x2000
	v_mfma_f32_16x16x32_bf16 v[116:119], v[180:183], v[212:215], v[116:119]
	global_load_lds_dwordx4 v148, s[62:63]
	ds_read_b128 v[200:203], v167 offset:36864
	ds_read_b128 v[240:243], v167 offset:38912
	v_mfma_f32_16x16x32_bf16 v[120:123], v[180:183], v[216:219], v[120:123]
	s_add_u32 m0, s68, 0xa000
	v_mfma_f32_16x16x32_bf16 v[124:127], v[180:183], v[248:251], v[124:127]
	global_load_lds_dwordx4 v132, s[64:65]
	s_waitcnt lgkmcnt(4)
	v_mfma_f32_16x16x32_bf16 v[0:3], v[168:171], v[184:187], v[0:3]
	ds_read_b128 v[180:183], v154 offset:6144
	s_waitcnt lgkmcnt(4)
	v_mfma_f32_16x16x32_bf16 v[4:7], v[168:171], v[196:199], v[4:7]
	ds_read_b128 v[244:247], v192 offset:32768
	s_waitcnt lgkmcnt(3)
	v_mfma_f32_16x16x32_bf16 v[8:11], v[168:171], v[200:203], v[8:11]
	s_waitcnt lgkmcnt(2)
	v_mfma_f32_16x16x32_bf16 v[12:15], v[168:171], v[240:243], v[12:15]
	v_mfma_f32_16x16x32_bf16 v[16:19], v[172:175], v[184:187], v[16:19]
	ds_read_b128 v[168:171], v154 offset:8192
	v_mfma_f32_16x16x32_bf16 v[20:23], v[172:175], v[196:199], v[20:23]
	ds_read_b128 v[212:215], v192 offset:34816
	v_mfma_f32_16x16x32_bf16 v[24:27], v[172:175], v[200:203], v[24:27]
	v_mfma_f32_16x16x32_bf16 v[28:31], v[172:175], v[240:243], v[28:31]
	v_mfma_f32_16x16x32_bf16 v[32:35], v[176:179], v[184:187], v[32:35]
	ds_read_b128 v[172:175], v154 offset:10240
	v_mfma_f32_16x16x32_bf16 v[36:39], v[176:179], v[196:199], v[36:39]
	ds_read_b128 v[216:219], v192 offset:36864
	v_mfma_f32_16x16x32_bf16 v[40:43], v[176:179], v[200:203], v[40:43]
	s_add_u32 m0, s68, 0x4000
	v_mfma_f32_16x16x32_bf16 v[44:47], v[176:179], v[240:243], v[44:47]
	global_load_lds_dwordx4 v146, s[62:63]
	s_waitcnt lgkmcnt(5)
	v_mfma_f32_16x16x32_bf16 v[48:51], v[180:183], v[184:187], v[48:51]
	ds_read_b128 v[176:179], v154 offset:12288
	v_mfma_f32_16x16x32_bf16 v[52:55], v[180:183], v[196:199], v[52:55]
	ds_read_b128 v[248:251], v192 offset:38912
	v_mfma_f32_16x16x32_bf16 v[56:59], v[180:183], v[200:203], v[56:59]
	s_add_u32 m0, s68, 0xc000
	v_mfma_f32_16x16x32_bf16 v[60:63], v[180:183], v[240:243], v[60:63]
	global_load_lds_dwordx4 v130, s[64:65]
	s_waitcnt lgkmcnt(5)
	v_mfma_f32_16x16x32_bf16 v[64:67], v[168:171], v[184:187], v[64:67]
	ds_read_b128 v[180:183], v154 offset:14336
	v_mfma_f32_16x16x32_bf16 v[68:71], v[168:171], v[196:199], v[68:71]
	v_mfma_f32_16x16x32_bf16 v[72:75], v[168:171], v[200:203], v[72:75]
	s_add_u32 m0, s68, 0x6000
	v_mfma_f32_16x16x32_bf16 v[76:79], v[168:171], v[240:243], v[76:79]
	global_load_lds_dwordx4 v144, s[62:63]
	s_waitcnt lgkmcnt(4)
	v_mfma_f32_16x16x32_bf16 v[80:83], v[172:175], v[184:187], v[80:83]
	ds_read_b128 v[168:171], v155
	v_mfma_f32_16x16x32_bf16 v[84:87], v[172:175], v[196:199], v[84:87]
	v_mfma_f32_16x16x32_bf16 v[88:91], v[172:175], v[200:203], v[88:91]
	s_add_u32 m0, s68, 0xe000
	v_mfma_f32_16x16x32_bf16 v[92:95], v[172:175], v[240:243], v[92:95]
	global_load_lds_dwordx4 v152, s[64:65]
	s_add_u32 s62, s62, 0x80
	s_addc_u32 s63, s63, 0
	s_add_u32 s64, s64, 0x80
	s_addc_u32 s65, s65, 0
	s_waitcnt lgkmcnt(3)
	v_mfma_f32_16x16x32_bf16 v[96:99], v[176:179], v[184:187], v[96:99]
	ds_read_b128 v[172:175], v155 offset:2048
	v_mfma_f32_16x16x32_bf16 v[100:103], v[176:179], v[196:199], v[100:103]
	v_mfma_f32_16x16x32_bf16 v[104:107], v[176:179], v[200:203], v[104:107]
	v_mfma_f32_16x16x32_bf16 v[108:111], v[176:179], v[240:243], v[108:111]
	s_waitcnt lgkmcnt(2)
	v_mfma_f32_16x16x32_bf16 v[112:115], v[180:183], v[184:187], v[112:115]
	ds_read_b128 v[176:179], v155 offset:4096
	v_mfma_f32_16x16x32_bf16 v[116:119], v[180:183], v[196:199], v[116:119]
	v_mfma_f32_16x16x32_bf16 v[120:123], v[180:183], v[200:203], v[120:123]
	v_mfma_f32_16x16x32_bf16 v[124:127], v[180:183], v[240:243], v[124:127]
	s_waitcnt lgkmcnt(2)
	v_mfma_f32_16x16x32_bf16 v[0:3], v[168:171], v[244:247], v[0:3]
	ds_read_b128 v[180:183], v155 offset:6144
	v_mfma_f32_16x16x32_bf16 v[4:7], v[168:171], v[212:215], v[4:7]
	v_mfma_f32_16x16x32_bf16 v[8:11], v[168:171], v[216:219], v[8:11]
	v_mfma_f32_16x16x32_bf16 v[12:15], v[168:171], v[248:251], v[12:15]
	s_waitcnt lgkmcnt(2)
	v_mfma_f32_16x16x32_bf16 v[16:19], v[172:175], v[244:247], v[16:19]
	ds_read_b128 v[168:171], v155 offset:8192
	v_mfma_f32_16x16x32_bf16 v[20:23], v[172:175], v[212:215], v[20:23]
	v_mfma_f32_16x16x32_bf16 v[24:27], v[172:175], v[216:219], v[24:27]
	v_mfma_f32_16x16x32_bf16 v[28:31], v[172:175], v[248:251], v[28:31]
	s_waitcnt lgkmcnt(2)
	v_mfma_f32_16x16x32_bf16 v[32:35], v[176:179], v[244:247], v[32:35]
	ds_read_b128 v[172:175], v155 offset:10240
	v_mfma_f32_16x16x32_bf16 v[36:39], v[176:179], v[212:215], v[36:39]
	v_mfma_f32_16x16x32_bf16 v[40:43], v[176:179], v[216:219], v[40:43]
	v_mfma_f32_16x16x32_bf16 v[44:47], v[176:179], v[248:251], v[44:47]
	s_waitcnt lgkmcnt(2)
	v_mfma_f32_16x16x32_bf16 v[48:51], v[180:183], v[244:247], v[48:51]
	ds_read_b128 v[176:179], v155 offset:12288
	v_mfma_f32_16x16x32_bf16 v[52:55], v[180:183], v[212:215], v[52:55]
	v_mfma_f32_16x16x32_bf16 v[56:59], v[180:183], v[216:219], v[56:59]
	v_mfma_f32_16x16x32_bf16 v[60:63], v[180:183], v[248:251], v[60:63]
	s_waitcnt lgkmcnt(2)
	v_mfma_f32_16x16x32_bf16 v[64:67], v[168:171], v[244:247], v[64:67]
	ds_read_b128 v[180:183], v155 offset:14336
	v_mfma_f32_16x16x32_bf16 v[68:71], v[168:171], v[212:215], v[68:71]
	v_mfma_f32_16x16x32_bf16 v[72:75], v[168:171], v[216:219], v[72:75]
	v_mfma_f32_16x16x32_bf16 v[76:79], v[168:171], v[248:251], v[76:79]
	s_waitcnt lgkmcnt(2)
	v_mfma_f32_16x16x32_bf16 v[80:83], v[172:175], v[244:247], v[80:83]
	v_mfma_f32_16x16x32_bf16 v[84:87], v[172:175], v[212:215], v[84:87]
	v_mfma_f32_16x16x32_bf16 v[88:91], v[172:175], v[216:219], v[88:91]
	v_mfma_f32_16x16x32_bf16 v[92:95], v[172:175], v[248:251], v[92:95]
	s_waitcnt lgkmcnt(0)
	s_waitcnt vmcnt(0)
	s_barrier
	v_xor_b32_e32 v154, 0x10000, v154
	v_xor_b32_e32 v155, 0x10000, v155
	v_xor_b32_e32 v167, 0x10000, v167
	v_xor_b32_e32 v192, 0x10000, v192
	v_mfma_f32_16x16x32_bf16 v[96:99], v[176:179], v[244:247], v[96:99]
	ds_read_b128 v[168:171], v154
	ds_read_b128 v[172:175], v154 offset:2048
	s_add_u32 m0, s68, 0x10000
	v_mfma_f32_16x16x32_bf16 v[100:103], v[176:179], v[212:215], v[100:103]
	global_load_lds_dwordx4 v150, s[62:63]
	v_mfma_f32_16x16x32_bf16 v[104:107], v[176:179], v[216:219], v[104:107]
	ds_read_b128 v[184:187], v167 offset:32768
	ds_read_b128 v[196:199], v167 offset:34816
	s_add_u32 m0, s68, 0x18000
	v_mfma_f32_16x16x32_bf16 v[108:111], v[176:179], v[248:251], v[108:111]
	global_load_lds_dwordx4 v134, s[64:65]
	v_mfma_f32_16x16x32_bf16 v[112:115], v[180:183], v[244:247], v[112:115]
	ds_read_b128 v[176:179], v154 offset:4096
	s_add_u32 m0, s68, 0x12000
	v_mfma_f32_16x16x32_bf16 v[116:119], v[180:183], v[212:215], v[116:119]
	global_load_lds_dwordx4 v148, s[62:63]
	ds_read_b128 v[200:203], v167 offset:36864
	ds_read_b128 v[240:243], v167 offset:38912
	v_mfma_f32_16x16x32_bf16 v[120:123], v[180:183], v[216:219], v[120:123]
	s_add_u32 m0, s68, 0x1a000
	v_mfma_f32_16x16x32_bf16 v[124:127], v[180:183], v[248:251], v[124:127]
	global_load_lds_dwordx4 v132, s[64:65]
	s_waitcnt lgkmcnt(4)
	v_mfma_f32_16x16x32_bf16 v[0:3], v[168:171], v[184:187], v[0:3]
	ds_read_b128 v[180:183], v154 offset:6144
	s_waitcnt lgkmcnt(4)
	v_mfma_f32_16x16x32_bf16 v[4:7], v[168:171], v[196:199], v[4:7]
	ds_read_b128 v[244:247], v192 offset:32768
	s_waitcnt lgkmcnt(3)
	v_mfma_f32_16x16x32_bf16 v[8:11], v[168:171], v[200:203], v[8:11]
	s_waitcnt lgkmcnt(2)
	v_mfma_f32_16x16x32_bf16 v[12:15], v[168:171], v[240:243], v[12:15]
	v_mfma_f32_16x16x32_bf16 v[16:19], v[172:175], v[184:187], v[16:19]
	ds_read_b128 v[168:171], v154 offset:8192
	v_mfma_f32_16x16x32_bf16 v[20:23], v[172:175], v[196:199], v[20:23]
	ds_read_b128 v[212:215], v192 offset:34816
	v_mfma_f32_16x16x32_bf16 v[24:27], v[172:175], v[200:203], v[24:27]
	v_mfma_f32_16x16x32_bf16 v[28:31], v[172:175], v[240:243], v[28:31]
	v_mfma_f32_16x16x32_bf16 v[32:35], v[176:179], v[184:187], v[32:35]
	ds_read_b128 v[172:175], v154 offset:10240
	v_mfma_f32_16x16x32_bf16 v[36:39], v[176:179], v[196:199], v[36:39]
	ds_read_b128 v[216:219], v192 offset:36864
	v_mfma_f32_16x16x32_bf16 v[40:43], v[176:179], v[200:203], v[40:43]
	s_add_u32 m0, s68, 0x14000
	v_mfma_f32_16x16x32_bf16 v[44:47], v[176:179], v[240:243], v[44:47]
	global_load_lds_dwordx4 v146, s[62:63]
	s_waitcnt lgkmcnt(5)
	v_mfma_f32_16x16x32_bf16 v[48:51], v[180:183], v[184:187], v[48:51]
	ds_read_b128 v[176:179], v154 offset:12288
	v_mfma_f32_16x16x32_bf16 v[52:55], v[180:183], v[196:199], v[52:55]
	ds_read_b128 v[248:251], v192 offset:38912
	v_mfma_f32_16x16x32_bf16 v[56:59], v[180:183], v[200:203], v[56:59]
	s_add_u32 m0, s68, 0x1c000
	v_mfma_f32_16x16x32_bf16 v[60:63], v[180:183], v[240:243], v[60:63]
	global_load_lds_dwordx4 v130, s[64:65]
	s_waitcnt lgkmcnt(5)
	v_mfma_f32_16x16x32_bf16 v[64:67], v[168:171], v[184:187], v[64:67]
	ds_read_b128 v[180:183], v154 offset:14336
	v_mfma_f32_16x16x32_bf16 v[68:71], v[168:171], v[196:199], v[68:71]
	v_mfma_f32_16x16x32_bf16 v[72:75], v[168:171], v[200:203], v[72:75]
	s_add_u32 m0, s68, 0x16000
	v_mfma_f32_16x16x32_bf16 v[76:79], v[168:171], v[240:243], v[76:79]
	global_load_lds_dwordx4 v144, s[62:63]
	s_waitcnt lgkmcnt(4)
	v_mfma_f32_16x16x32_bf16 v[80:83], v[172:175], v[184:187], v[80:83]
	ds_read_b128 v[168:171], v155
	v_mfma_f32_16x16x32_bf16 v[84:87], v[172:175], v[196:199], v[84:87]
	v_mfma_f32_16x16x32_bf16 v[88:91], v[172:175], v[200:203], v[88:91]
	s_add_u32 m0, s68, 0x1e000
	v_mfma_f32_16x16x32_bf16 v[92:95], v[172:175], v[240:243], v[92:95]
	global_load_lds_dwordx4 v152, s[64:65]
	s_add_u32 s62, s62, 0x80
	s_addc_u32 s63, s63, 0
	s_add_u32 s64, s64, 0x80
	s_addc_u32 s65, s65, 0
	s_waitcnt lgkmcnt(3)
	v_mfma_f32_16x16x32_bf16 v[96:99], v[176:179], v[184:187], v[96:99]
	ds_read_b128 v[172:175], v155 offset:2048
	v_mfma_f32_16x16x32_bf16 v[100:103], v[176:179], v[196:199], v[100:103]
	v_mfma_f32_16x16x32_bf16 v[104:107], v[176:179], v[200:203], v[104:107]
	v_mfma_f32_16x16x32_bf16 v[108:111], v[176:179], v[240:243], v[108:111]
	s_waitcnt lgkmcnt(2)
	v_mfma_f32_16x16x32_bf16 v[112:115], v[180:183], v[184:187], v[112:115]
	ds_read_b128 v[176:179], v155 offset:4096
	v_mfma_f32_16x16x32_bf16 v[116:119], v[180:183], v[196:199], v[116:119]
	v_mfma_f32_16x16x32_bf16 v[120:123], v[180:183], v[200:203], v[120:123]
	v_mfma_f32_16x16x32_bf16 v[124:127], v[180:183], v[240:243], v[124:127]
	s_waitcnt lgkmcnt(2)
	v_mfma_f32_16x16x32_bf16 v[0:3], v[168:171], v[244:247], v[0:3]
	ds_read_b128 v[180:183], v155 offset:6144
	v_mfma_f32_16x16x32_bf16 v[4:7], v[168:171], v[212:215], v[4:7]
	v_mfma_f32_16x16x32_bf16 v[8:11], v[168:171], v[216:219], v[8:11]
	v_mfma_f32_16x16x32_bf16 v[12:15], v[168:171], v[248:251], v[12:15]
	s_waitcnt lgkmcnt(2)
	v_mfma_f32_16x16x32_bf16 v[16:19], v[172:175], v[244:247], v[16:19]
	ds_read_b128 v[168:171], v155 offset:8192
	v_mfma_f32_16x16x32_bf16 v[20:23], v[172:175], v[212:215], v[20:23]
	v_mfma_f32_16x16x32_bf16 v[24:27], v[172:175], v[216:219], v[24:27]
	v_mfma_f32_16x16x32_bf16 v[28:31], v[172:175], v[248:251], v[28:31]
	s_waitcnt lgkmcnt(2)
	v_mfma_f32_16x16x32_bf16 v[32:35], v[176:179], v[244:247], v[32:35]
	ds_read_b128 v[172:175], v155 offset:10240
	v_mfma_f32_16x16x32_bf16 v[36:39], v[176:179], v[212:215], v[36:39]
	v_mfma_f32_16x16x32_bf16 v[40:43], v[176:179], v[216:219], v[40:43]
	v_mfma_f32_16x16x32_bf16 v[44:47], v[176:179], v[248:251], v[44:47]
	s_waitcnt lgkmcnt(2)
	v_mfma_f32_16x16x32_bf16 v[48:51], v[180:183], v[244:247], v[48:51]
	ds_read_b128 v[176:179], v155 offset:12288
	v_mfma_f32_16x16x32_bf16 v[52:55], v[180:183], v[212:215], v[52:55]
	v_mfma_f32_16x16x32_bf16 v[56:59], v[180:183], v[216:219], v[56:59]
	v_mfma_f32_16x16x32_bf16 v[60:63], v[180:183], v[248:251], v[60:63]
	s_waitcnt lgkmcnt(2)
	v_mfma_f32_16x16x32_bf16 v[64:67], v[168:171], v[244:247], v[64:67]
	ds_read_b128 v[180:183], v155 offset:14336
	v_mfma_f32_16x16x32_bf16 v[68:71], v[168:171], v[212:215], v[68:71]
	v_mfma_f32_16x16x32_bf16 v[72:75], v[168:171], v[216:219], v[72:75]
	v_mfma_f32_16x16x32_bf16 v[76:79], v[168:171], v[248:251], v[76:79]
	s_waitcnt lgkmcnt(2)
	v_mfma_f32_16x16x32_bf16 v[80:83], v[172:175], v[244:247], v[80:83]
	v_mfma_f32_16x16x32_bf16 v[84:87], v[172:175], v[212:215], v[84:87]
	v_mfma_f32_16x16x32_bf16 v[88:91], v[172:175], v[216:219], v[88:91]
	v_mfma_f32_16x16x32_bf16 v[92:95], v[172:175], v[248:251], v[92:95]
	s_waitcnt lgkmcnt(0)
	s_waitcnt vmcnt(0)
	s_barrier
	v_xor_b32_e32 v154, 0x10000, v154
	v_xor_b32_e32 v155, 0x10000, v155
	v_xor_b32_e32 v167, 0x10000, v167
	v_xor_b32_e32 v192, 0x10000, v192
	v_mfma_f32_16x16x32_bf16 v[96:99], v[176:179], v[244:247], v[96:99]
	ds_read_b128 v[168:171], v154
	ds_read_b128 v[172:175], v154 offset:2048
	s_mov_b32 m0, s68
	v_mfma_f32_16x16x32_bf16 v[100:103], v[176:179], v[212:215], v[100:103]
	global_load_lds_dwordx4 v150, s[62:63]
	v_mfma_f32_16x16x32_bf16 v[104:107], v[176:179], v[216:219], v[104:107]
	ds_read_b128 v[184:187], v167 offset:32768
	ds_read_b128 v[196:199], v167 offset:34816
	s_add_u32 m0, s68, 0x8000
	v_mfma_f32_16x16x32_bf16 v[108:111], v[176:179], v[248:251], v[108:111]
	global_load_lds_dwordx4 v134, s[64:65]
	v_mfma_f32_16x16x32_bf16 v[112:115], v[180:183], v[244:247], v[112:115]
	ds_read_b128 v[176:179], v154 offset:4096
	s_add_u32 m0, s68, 0x2000
	v_mfma_f32_16x16x32_bf16 v[116:119], v[180:183], v[212:215], v[116:119]
	global_load_lds_dwordx4 v148, s[62:63]
	ds_read_b128 v[200:203], v167 offset:36864
	ds_read_b128 v[240:243], v167 offset:38912
	v_mfma_f32_16x16x32_bf16 v[120:123], v[180:183], v[216:219], v[120:123]
	s_add_u32 m0, s68, 0xa000
	v_mfma_f32_16x16x32_bf16 v[124:127], v[180:183], v[248:251], v[124:127]
	global_load_lds_dwordx4 v132, s[64:65]
	s_waitcnt lgkmcnt(4)
	v_mfma_f32_16x16x32_bf16 v[0:3], v[168:171], v[184:187], v[0:3]
	ds_read_b128 v[180:183], v154 offset:6144
	s_waitcnt lgkmcnt(4)
	v_mfma_f32_16x16x32_bf16 v[4:7], v[168:171], v[196:199], v[4:7]
	ds_read_b128 v[244:247], v192 offset:32768
	s_waitcnt lgkmcnt(3)
	v_mfma_f32_16x16x32_bf16 v[8:11], v[168:171], v[200:203], v[8:11]
	s_waitcnt lgkmcnt(2)
	v_mfma_f32_16x16x32_bf16 v[12:15], v[168:171], v[240:243], v[12:15]
	v_mfma_f32_16x16x32_bf16 v[16:19], v[172:175], v[184:187], v[16:19]
	ds_read_b128 v[168:171], v154 offset:8192
	v_mfma_f32_16x16x32_bf16 v[20:23], v[172:175], v[196:199], v[20:23]
	ds_read_b128 v[212:215], v192 offset:34816
	v_mfma_f32_16x16x32_bf16 v[24:27], v[172:175], v[200:203], v[24:27]
	v_mfma_f32_16x16x32_bf16 v[28:31], v[172:175], v[240:243], v[28:31]
	v_mfma_f32_16x16x32_bf16 v[32:35], v[176:179], v[184:187], v[32:35]
	ds_read_b128 v[172:175], v154 offset:10240
	v_mfma_f32_16x16x32_bf16 v[36:39], v[176:179], v[196:199], v[36:39]
	ds_read_b128 v[216:219], v192 offset:36864
	v_mfma_f32_16x16x32_bf16 v[40:43], v[176:179], v[200:203], v[40:43]
	s_add_u32 m0, s68, 0x4000
	v_mfma_f32_16x16x32_bf16 v[44:47], v[176:179], v[240:243], v[44:47]
	global_load_lds_dwordx4 v146, s[62:63]
	s_waitcnt lgkmcnt(5)
	v_mfma_f32_16x16x32_bf16 v[48:51], v[180:183], v[184:187], v[48:51]
	ds_read_b128 v[176:179], v154 offset:12288
	v_mfma_f32_16x16x32_bf16 v[52:55], v[180:183], v[196:199], v[52:55]
	ds_read_b128 v[248:251], v192 offset:38912
	v_mfma_f32_16x16x32_bf16 v[56:59], v[180:183], v[200:203], v[56:59]
	s_add_u32 m0, s68, 0xc000
	v_mfma_f32_16x16x32_bf16 v[60:63], v[180:183], v[240:243], v[60:63]
	global_load_lds_dwordx4 v130, s[64:65]
	s_waitcnt lgkmcnt(5)
	v_mfma_f32_16x16x32_bf16 v[64:67], v[168:171], v[184:187], v[64:67]
	ds_read_b128 v[180:183], v154 offset:14336
	v_mfma_f32_16x16x32_bf16 v[68:71], v[168:171], v[196:199], v[68:71]
	v_mfma_f32_16x16x32_bf16 v[72:75], v[168:171], v[200:203], v[72:75]
	s_add_u32 m0, s68, 0x6000
	v_mfma_f32_16x16x32_bf16 v[76:79], v[168:171], v[240:243], v[76:79]
	global_load_lds_dwordx4 v144, s[62:63]
	s_waitcnt lgkmcnt(4)
	v_mfma_f32_16x16x32_bf16 v[80:83], v[172:175], v[184:187], v[80:83]
	ds_read_b128 v[168:171], v155
	v_mfma_f32_16x16x32_bf16 v[84:87], v[172:175], v[196:199], v[84:87]
	v_mfma_f32_16x16x32_bf16 v[88:91], v[172:175], v[200:203], v[88:91]
	s_add_u32 m0, s68, 0xe000
	v_mfma_f32_16x16x32_bf16 v[92:95], v[172:175], v[240:243], v[92:95]
	global_load_lds_dwordx4 v152, s[64:65]
	s_add_u32 s62, s62, 0x80
	s_addc_u32 s63, s63, 0
	s_add_u32 s64, s64, 0x80
	s_addc_u32 s65, s65, 0
	s_waitcnt lgkmcnt(3)
	v_mfma_f32_16x16x32_bf16 v[96:99], v[176:179], v[184:187], v[96:99]
	ds_read_b128 v[172:175], v155 offset:2048
	v_mfma_f32_16x16x32_bf16 v[100:103], v[176:179], v[196:199], v[100:103]
	v_mfma_f32_16x16x32_bf16 v[104:107], v[176:179], v[200:203], v[104:107]
	v_mfma_f32_16x16x32_bf16 v[108:111], v[176:179], v[240:243], v[108:111]
	s_waitcnt lgkmcnt(2)
	v_mfma_f32_16x16x32_bf16 v[112:115], v[180:183], v[184:187], v[112:115]
	ds_read_b128 v[176:179], v155 offset:4096
	v_mfma_f32_16x16x32_bf16 v[116:119], v[180:183], v[196:199], v[116:119]
	v_mfma_f32_16x16x32_bf16 v[120:123], v[180:183], v[200:203], v[120:123]
	v_mfma_f32_16x16x32_bf16 v[124:127], v[180:183], v[240:243], v[124:127]
	s_waitcnt lgkmcnt(2)
	v_mfma_f32_16x16x32_bf16 v[0:3], v[168:171], v[244:247], v[0:3]
	ds_read_b128 v[180:183], v155 offset:6144
	v_mfma_f32_16x16x32_bf16 v[4:7], v[168:171], v[212:215], v[4:7]
	v_mfma_f32_16x16x32_bf16 v[8:11], v[168:171], v[216:219], v[8:11]
	v_mfma_f32_16x16x32_bf16 v[12:15], v[168:171], v[248:251], v[12:15]
	s_waitcnt lgkmcnt(2)
	v_mfma_f32_16x16x32_bf16 v[16:19], v[172:175], v[244:247], v[16:19]
	ds_read_b128 v[168:171], v155 offset:8192
	v_mfma_f32_16x16x32_bf16 v[20:23], v[172:175], v[212:215], v[20:23]
	v_mfma_f32_16x16x32_bf16 v[24:27], v[172:175], v[216:219], v[24:27]
	v_mfma_f32_16x16x32_bf16 v[28:31], v[172:175], v[248:251], v[28:31]
	s_waitcnt lgkmcnt(2)
	v_mfma_f32_16x16x32_bf16 v[32:35], v[176:179], v[244:247], v[32:35]
	ds_read_b128 v[172:175], v155 offset:10240
	v_mfma_f32_16x16x32_bf16 v[36:39], v[176:179], v[212:215], v[36:39]
	v_mfma_f32_16x16x32_bf16 v[40:43], v[176:179], v[216:219], v[40:43]
	v_mfma_f32_16x16x32_bf16 v[44:47], v[176:179], v[248:251], v[44:47]
	s_waitcnt lgkmcnt(2)
	v_mfma_f32_16x16x32_bf16 v[48:51], v[180:183], v[244:247], v[48:51]
	ds_read_b128 v[176:179], v155 offset:12288
	v_mfma_f32_16x16x32_bf16 v[52:55], v[180:183], v[212:215], v[52:55]
	v_mfma_f32_16x16x32_bf16 v[56:59], v[180:183], v[216:219], v[56:59]
	v_mfma_f32_16x16x32_bf16 v[60:63], v[180:183], v[248:251], v[60:63]
	s_waitcnt lgkmcnt(2)
	v_mfma_f32_16x16x32_bf16 v[64:67], v[168:171], v[244:247], v[64:67]
	ds_read_b128 v[180:183], v155 offset:14336
	v_mfma_f32_16x16x32_bf16 v[68:71], v[168:171], v[212:215], v[68:71]
	v_mfma_f32_16x16x32_bf16 v[72:75], v[168:171], v[216:219], v[72:75]
	v_mfma_f32_16x16x32_bf16 v[76:79], v[168:171], v[248:251], v[76:79]
	s_waitcnt lgkmcnt(2)
	v_mfma_f32_16x16x32_bf16 v[80:83], v[172:175], v[244:247], v[80:83]
	v_mfma_f32_16x16x32_bf16 v[84:87], v[172:175], v[212:215], v[84:87]
	v_mfma_f32_16x16x32_bf16 v[88:91], v[172:175], v[216:219], v[88:91]
	v_mfma_f32_16x16x32_bf16 v[92:95], v[172:175], v[248:251], v[92:95]
	s_waitcnt lgkmcnt(0)
	s_waitcnt vmcnt(0)
	s_barrier
	v_xor_b32_e32 v154, 0x10000, v154
	v_xor_b32_e32 v155, 0x10000, v155
	v_xor_b32_e32 v167, 0x10000, v167
	v_xor_b32_e32 v192, 0x10000, v192
	v_mfma_f32_16x16x32_bf16 v[96:99], v[176:179], v[244:247], v[96:99]
	ds_read_b128 v[168:171], v154
	ds_read_b128 v[172:175], v154 offset:2048
	s_add_u32 m0, s68, 0x10000
	v_mfma_f32_16x16x32_bf16 v[100:103], v[176:179], v[212:215], v[100:103]
	global_load_lds_dwordx4 v150, s[62:63]
	v_mfma_f32_16x16x32_bf16 v[104:107], v[176:179], v[216:219], v[104:107]
	ds_read_b128 v[184:187], v167 offset:32768
	ds_read_b128 v[196:199], v167 offset:34816
	s_add_u32 m0, s68, 0x18000
	v_mfma_f32_16x16x32_bf16 v[108:111], v[176:179], v[248:251], v[108:111]
	global_load_lds_dwordx4 v134, s[64:65]
	v_mfma_f32_16x16x32_bf16 v[112:115], v[180:183], v[244:247], v[112:115]
	ds_read_b128 v[176:179], v154 offset:4096
	s_add_u32 m0, s68, 0x12000
	v_mfma_f32_16x16x32_bf16 v[116:119], v[180:183], v[212:215], v[116:119]
	global_load_lds_dwordx4 v148, s[62:63]
	ds_read_b128 v[200:203], v167 offset:36864
	ds_read_b128 v[240:243], v167 offset:38912
	v_mfma_f32_16x16x32_bf16 v[120:123], v[180:183], v[216:219], v[120:123]
	s_add_u32 m0, s68, 0x1a000
	v_mfma_f32_16x16x32_bf16 v[124:127], v[180:183], v[248:251], v[124:127]
	global_load_lds_dwordx4 v132, s[64:65]
	s_waitcnt lgkmcnt(4)
	v_mfma_f32_16x16x32_bf16 v[0:3], v[168:171], v[184:187], v[0:3]
	ds_read_b128 v[180:183], v154 offset:6144
	s_waitcnt lgkmcnt(4)
	v_mfma_f32_16x16x32_bf16 v[4:7], v[168:171], v[196:199], v[4:7]
	ds_read_b128 v[244:247], v192 offset:32768
	s_waitcnt lgkmcnt(3)
	v_mfma_f32_16x16x32_bf16 v[8:11], v[168:171], v[200:203], v[8:11]
	s_waitcnt lgkmcnt(2)
	v_mfma_f32_16x16x32_bf16 v[12:15], v[168:171], v[240:243], v[12:15]
	v_mfma_f32_16x16x32_bf16 v[16:19], v[172:175], v[184:187], v[16:19]
	ds_read_b128 v[168:171], v154 offset:8192
	v_mfma_f32_16x16x32_bf16 v[20:23], v[172:175], v[196:199], v[20:23]
	ds_read_b128 v[212:215], v192 offset:34816
	v_mfma_f32_16x16x32_bf16 v[24:27], v[172:175], v[200:203], v[24:27]
	v_mfma_f32_16x16x32_bf16 v[28:31], v[172:175], v[240:243], v[28:31]
	v_mfma_f32_16x16x32_bf16 v[32:35], v[176:179], v[184:187], v[32:35]
	ds_read_b128 v[172:175], v154 offset:10240
	v_mfma_f32_16x16x32_bf16 v[36:39], v[176:179], v[196:199], v[36:39]
	ds_read_b128 v[216:219], v192 offset:36864
	v_mfma_f32_16x16x32_bf16 v[40:43], v[176:179], v[200:203], v[40:43]
	s_add_u32 m0, s68, 0x14000
	v_mfma_f32_16x16x32_bf16 v[44:47], v[176:179], v[240:243], v[44:47]
	global_load_lds_dwordx4 v146, s[62:63]
	s_waitcnt lgkmcnt(5)
	v_mfma_f32_16x16x32_bf16 v[48:51], v[180:183], v[184:187], v[48:51]
	ds_read_b128 v[176:179], v154 offset:12288
	v_mfma_f32_16x16x32_bf16 v[52:55], v[180:183], v[196:199], v[52:55]
	ds_read_b128 v[248:251], v192 offset:38912
	v_mfma_f32_16x16x32_bf16 v[56:59], v[180:183], v[200:203], v[56:59]
	s_add_u32 m0, s68, 0x1c000
	v_mfma_f32_16x16x32_bf16 v[60:63], v[180:183], v[240:243], v[60:63]
	global_load_lds_dwordx4 v130, s[64:65]
	s_waitcnt lgkmcnt(5)
	v_mfma_f32_16x16x32_bf16 v[64:67], v[168:171], v[184:187], v[64:67]
	ds_read_b128 v[180:183], v154 offset:14336
	v_mfma_f32_16x16x32_bf16 v[68:71], v[168:171], v[196:199], v[68:71]
	v_mfma_f32_16x16x32_bf16 v[72:75], v[168:171], v[200:203], v[72:75]
	s_add_u32 m0, s68, 0x16000
	v_mfma_f32_16x16x32_bf16 v[76:79], v[168:171], v[240:243], v[76:79]
	global_load_lds_dwordx4 v144, s[62:63]
	s_waitcnt lgkmcnt(4)
	v_mfma_f32_16x16x32_bf16 v[80:83], v[172:175], v[184:187], v[80:83]
	ds_read_b128 v[168:171], v155
	v_mfma_f32_16x16x32_bf16 v[84:87], v[172:175], v[196:199], v[84:87]
	v_mfma_f32_16x16x32_bf16 v[88:91], v[172:175], v[200:203], v[88:91]
	s_add_u32 m0, s68, 0x1e000
	v_mfma_f32_16x16x32_bf16 v[92:95], v[172:175], v[240:243], v[92:95]
	global_load_lds_dwordx4 v152, s[64:65]
	s_add_u32 s62, s62, 0x80
	s_addc_u32 s63, s63, 0
	s_add_u32 s64, s64, 0x80
	s_addc_u32 s65, s65, 0
	s_waitcnt lgkmcnt(3)
	v_mfma_f32_16x16x32_bf16 v[96:99], v[176:179], v[184:187], v[96:99]
	ds_read_b128 v[172:175], v155 offset:2048
	v_mfma_f32_16x16x32_bf16 v[100:103], v[176:179], v[196:199], v[100:103]
	v_mfma_f32_16x16x32_bf16 v[104:107], v[176:179], v[200:203], v[104:107]
	v_mfma_f32_16x16x32_bf16 v[108:111], v[176:179], v[240:243], v[108:111]
	s_waitcnt lgkmcnt(2)
	v_mfma_f32_16x16x32_bf16 v[112:115], v[180:183], v[184:187], v[112:115]
	ds_read_b128 v[176:179], v155 offset:4096
	v_mfma_f32_16x16x32_bf16 v[116:119], v[180:183], v[196:199], v[116:119]
	v_mfma_f32_16x16x32_bf16 v[120:123], v[180:183], v[200:203], v[120:123]
	v_mfma_f32_16x16x32_bf16 v[124:127], v[180:183], v[240:243], v[124:127]
	s_waitcnt lgkmcnt(2)
	v_mfma_f32_16x16x32_bf16 v[0:3], v[168:171], v[244:247], v[0:3]
	ds_read_b128 v[180:183], v155 offset:6144
	v_mfma_f32_16x16x32_bf16 v[4:7], v[168:171], v[212:215], v[4:7]
	v_mfma_f32_16x16x32_bf16 v[8:11], v[168:171], v[216:219], v[8:11]
	v_mfma_f32_16x16x32_bf16 v[12:15], v[168:171], v[248:251], v[12:15]
	s_waitcnt lgkmcnt(2)
	v_mfma_f32_16x16x32_bf16 v[16:19], v[172:175], v[244:247], v[16:19]
	ds_read_b128 v[168:171], v155 offset:8192
	v_mfma_f32_16x16x32_bf16 v[20:23], v[172:175], v[212:215], v[20:23]
	v_mfma_f32_16x16x32_bf16 v[24:27], v[172:175], v[216:219], v[24:27]
	v_mfma_f32_16x16x32_bf16 v[28:31], v[172:175], v[248:251], v[28:31]
	s_waitcnt lgkmcnt(2)
	v_mfma_f32_16x16x32_bf16 v[32:35], v[176:179], v[244:247], v[32:35]
	ds_read_b128 v[172:175], v155 offset:10240
	v_mfma_f32_16x16x32_bf16 v[36:39], v[176:179], v[212:215], v[36:39]
	v_mfma_f32_16x16x32_bf16 v[40:43], v[176:179], v[216:219], v[40:43]
	v_mfma_f32_16x16x32_bf16 v[44:47], v[176:179], v[248:251], v[44:47]
	s_waitcnt lgkmcnt(2)
	v_mfma_f32_16x16x32_bf16 v[48:51], v[180:183], v[244:247], v[48:51]
	ds_read_b128 v[176:179], v155 offset:12288
	v_mfma_f32_16x16x32_bf16 v[52:55], v[180:183], v[212:215], v[52:55]
	v_mfma_f32_16x16x32_bf16 v[56:59], v[180:183], v[216:219], v[56:59]
	v_mfma_f32_16x16x32_bf16 v[60:63], v[180:183], v[248:251], v[60:63]
	s_waitcnt lgkmcnt(2)
	v_mfma_f32_16x16x32_bf16 v[64:67], v[168:171], v[244:247], v[64:67]
	ds_read_b128 v[180:183], v155 offset:14336
	v_mfma_f32_16x16x32_bf16 v[68:71], v[168:171], v[212:215], v[68:71]
	v_mfma_f32_16x16x32_bf16 v[72:75], v[168:171], v[216:219], v[72:75]
	v_mfma_f32_16x16x32_bf16 v[76:79], v[168:171], v[248:251], v[76:79]
	s_waitcnt lgkmcnt(2)
	v_mfma_f32_16x16x32_bf16 v[80:83], v[172:175], v[244:247], v[80:83]
	v_mfma_f32_16x16x32_bf16 v[84:87], v[172:175], v[212:215], v[84:87]
	v_mfma_f32_16x16x32_bf16 v[88:91], v[172:175], v[216:219], v[88:91]
	v_mfma_f32_16x16x32_bf16 v[92:95], v[172:175], v[248:251], v[92:95]
	s_waitcnt lgkmcnt(0)
	s_waitcnt vmcnt(0)
	s_barrier
	v_xor_b32_e32 v154, 0x10000, v154
	v_xor_b32_e32 v155, 0x10000, v155
	v_xor_b32_e32 v167, 0x10000, v167
	v_xor_b32_e32 v192, 0x10000, v192
	v_mfma_f32_16x16x32_bf16 v[96:99], v[176:179], v[244:247], v[96:99]
	ds_read_b128 v[168:171], v154
	ds_read_b128 v[172:175], v154 offset:2048
	s_mov_b32 m0, s68
	v_mfma_f32_16x16x32_bf16 v[100:103], v[176:179], v[212:215], v[100:103]
	global_load_lds_dwordx4 v150, s[62:63]
	v_mfma_f32_16x16x32_bf16 v[104:107], v[176:179], v[216:219], v[104:107]
	ds_read_b128 v[184:187], v167 offset:32768
	ds_read_b128 v[196:199], v167 offset:34816
	s_add_u32 m0, s68, 0x8000
	v_mfma_f32_16x16x32_bf16 v[108:111], v[176:179], v[248:251], v[108:111]
	global_load_lds_dwordx4 v134, s[64:65]
	v_mfma_f32_16x16x32_bf16 v[112:115], v[180:183], v[244:247], v[112:115]
	ds_read_b128 v[176:179], v154 offset:4096
	s_add_u32 m0, s68, 0x2000
	v_mfma_f32_16x16x32_bf16 v[116:119], v[180:183], v[212:215], v[116:119]
	global_load_lds_dwordx4 v148, s[62:63]
	ds_read_b128 v[200:203], v167 offset:36864
	ds_read_b128 v[240:243], v167 offset:38912
	v_mfma_f32_16x16x32_bf16 v[120:123], v[180:183], v[216:219], v[120:123]
	s_add_u32 m0, s68, 0xa000
	v_mfma_f32_16x16x32_bf16 v[124:127], v[180:183], v[248:251], v[124:127]
	global_load_lds_dwordx4 v132, s[64:65]
	s_waitcnt lgkmcnt(4)
	v_mfma_f32_16x16x32_bf16 v[0:3], v[168:171], v[184:187], v[0:3]
	ds_read_b128 v[180:183], v154 offset:6144
	s_waitcnt lgkmcnt(4)
	v_mfma_f32_16x16x32_bf16 v[4:7], v[168:171], v[196:199], v[4:7]
	ds_read_b128 v[244:247], v192 offset:32768
	s_waitcnt lgkmcnt(3)
	v_mfma_f32_16x16x32_bf16 v[8:11], v[168:171], v[200:203], v[8:11]
	s_waitcnt lgkmcnt(2)
	v_mfma_f32_16x16x32_bf16 v[12:15], v[168:171], v[240:243], v[12:15]
	v_mfma_f32_16x16x32_bf16 v[16:19], v[172:175], v[184:187], v[16:19]
	ds_read_b128 v[168:171], v154 offset:8192
	v_mfma_f32_16x16x32_bf16 v[20:23], v[172:175], v[196:199], v[20:23]
	ds_read_b128 v[212:215], v192 offset:34816
	v_mfma_f32_16x16x32_bf16 v[24:27], v[172:175], v[200:203], v[24:27]
	v_mfma_f32_16x16x32_bf16 v[28:31], v[172:175], v[240:243], v[28:31]
	v_mfma_f32_16x16x32_bf16 v[32:35], v[176:179], v[184:187], v[32:35]
	ds_read_b128 v[172:175], v154 offset:10240
	v_mfma_f32_16x16x32_bf16 v[36:39], v[176:179], v[196:199], v[36:39]
	ds_read_b128 v[216:219], v192 offset:36864
	v_mfma_f32_16x16x32_bf16 v[40:43], v[176:179], v[200:203], v[40:43]
	s_add_u32 m0, s68, 0x4000
	v_mfma_f32_16x16x32_bf16 v[44:47], v[176:179], v[240:243], v[44:47]
	global_load_lds_dwordx4 v146, s[62:63]
	s_waitcnt lgkmcnt(5)
	v_mfma_f32_16x16x32_bf16 v[48:51], v[180:183], v[184:187], v[48:51]
	ds_read_b128 v[176:179], v154 offset:12288
	v_mfma_f32_16x16x32_bf16 v[52:55], v[180:183], v[196:199], v[52:55]
	ds_read_b128 v[248:251], v192 offset:38912
	v_mfma_f32_16x16x32_bf16 v[56:59], v[180:183], v[200:203], v[56:59]
	s_add_u32 m0, s68, 0xc000
	v_mfma_f32_16x16x32_bf16 v[60:63], v[180:183], v[240:243], v[60:63]
	global_load_lds_dwordx4 v130, s[64:65]
	s_waitcnt lgkmcnt(5)
	v_mfma_f32_16x16x32_bf16 v[64:67], v[168:171], v[184:187], v[64:67]
	ds_read_b128 v[180:183], v154 offset:14336
	v_mfma_f32_16x16x32_bf16 v[68:71], v[168:171], v[196:199], v[68:71]
	v_mfma_f32_16x16x32_bf16 v[72:75], v[168:171], v[200:203], v[72:75]
	s_add_u32 m0, s68, 0x6000
	v_mfma_f32_16x16x32_bf16 v[76:79], v[168:171], v[240:243], v[76:79]
	global_load_lds_dwordx4 v144, s[62:63]
	s_waitcnt lgkmcnt(4)
	v_mfma_f32_16x16x32_bf16 v[80:83], v[172:175], v[184:187], v[80:83]
	ds_read_b128 v[168:171], v155
	v_mfma_f32_16x16x32_bf16 v[84:87], v[172:175], v[196:199], v[84:87]
	v_mfma_f32_16x16x32_bf16 v[88:91], v[172:175], v[200:203], v[88:91]
	s_add_u32 m0, s68, 0xe000
	v_mfma_f32_16x16x32_bf16 v[92:95], v[172:175], v[240:243], v[92:95]
	global_load_lds_dwordx4 v152, s[64:65]
	s_add_u32 s62, s62, 0x80
	s_addc_u32 s63, s63, 0
	s_add_u32 s64, s64, 0x80
	s_addc_u32 s65, s65, 0
	s_waitcnt lgkmcnt(3)
	v_mfma_f32_16x16x32_bf16 v[96:99], v[176:179], v[184:187], v[96:99]
	ds_read_b128 v[172:175], v155 offset:2048
	v_mfma_f32_16x16x32_bf16 v[100:103], v[176:179], v[196:199], v[100:103]
	v_mfma_f32_16x16x32_bf16 v[104:107], v[176:179], v[200:203], v[104:107]
	v_mfma_f32_16x16x32_bf16 v[108:111], v[176:179], v[240:243], v[108:111]
	s_waitcnt lgkmcnt(2)
	v_mfma_f32_16x16x32_bf16 v[112:115], v[180:183], v[184:187], v[112:115]
	ds_read_b128 v[176:179], v155 offset:4096
	v_mfma_f32_16x16x32_bf16 v[116:119], v[180:183], v[196:199], v[116:119]
	v_mfma_f32_16x16x32_bf16 v[120:123], v[180:183], v[200:203], v[120:123]
	v_mfma_f32_16x16x32_bf16 v[124:127], v[180:183], v[240:243], v[124:127]
	s_waitcnt lgkmcnt(2)
	v_mfma_f32_16x16x32_bf16 v[0:3], v[168:171], v[244:247], v[0:3]
	ds_read_b128 v[180:183], v155 offset:6144
	v_mfma_f32_16x16x32_bf16 v[4:7], v[168:171], v[212:215], v[4:7]
	v_mfma_f32_16x16x32_bf16 v[8:11], v[168:171], v[216:219], v[8:11]
	v_mfma_f32_16x16x32_bf16 v[12:15], v[168:171], v[248:251], v[12:15]
	s_waitcnt lgkmcnt(2)
	v_mfma_f32_16x16x32_bf16 v[16:19], v[172:175], v[244:247], v[16:19]
	ds_read_b128 v[168:171], v155 offset:8192
	v_mfma_f32_16x16x32_bf16 v[20:23], v[172:175], v[212:215], v[20:23]
	v_mfma_f32_16x16x32_bf16 v[24:27], v[172:175], v[216:219], v[24:27]
	v_mfma_f32_16x16x32_bf16 v[28:31], v[172:175], v[248:251], v[28:31]
	s_waitcnt lgkmcnt(2)
	v_mfma_f32_16x16x32_bf16 v[32:35], v[176:179], v[244:247], v[32:35]
	ds_read_b128 v[172:175], v155 offset:10240
	v_mfma_f32_16x16x32_bf16 v[36:39], v[176:179], v[212:215], v[36:39]
	v_mfma_f32_16x16x32_bf16 v[40:43], v[176:179], v[216:219], v[40:43]
	v_mfma_f32_16x16x32_bf16 v[44:47], v[176:179], v[248:251], v[44:47]
	s_waitcnt lgkmcnt(2)
	v_mfma_f32_16x16x32_bf16 v[48:51], v[180:183], v[244:247], v[48:51]
	ds_read_b128 v[176:179], v155 offset:12288
	v_mfma_f32_16x16x32_bf16 v[52:55], v[180:183], v[212:215], v[52:55]
	v_mfma_f32_16x16x32_bf16 v[56:59], v[180:183], v[216:219], v[56:59]
	v_mfma_f32_16x16x32_bf16 v[60:63], v[180:183], v[248:251], v[60:63]
	s_waitcnt lgkmcnt(2)
	v_mfma_f32_16x16x32_bf16 v[64:67], v[168:171], v[244:247], v[64:67]
	ds_read_b128 v[180:183], v155 offset:14336
	v_mfma_f32_16x16x32_bf16 v[68:71], v[168:171], v[212:215], v[68:71]
	v_mfma_f32_16x16x32_bf16 v[72:75], v[168:171], v[216:219], v[72:75]
	v_mfma_f32_16x16x32_bf16 v[76:79], v[168:171], v[248:251], v[76:79]
	s_waitcnt lgkmcnt(2)
	v_mfma_f32_16x16x32_bf16 v[80:83], v[172:175], v[244:247], v[80:83]
	v_mfma_f32_16x16x32_bf16 v[84:87], v[172:175], v[212:215], v[84:87]
	v_mfma_f32_16x16x32_bf16 v[88:91], v[172:175], v[216:219], v[88:91]
	v_mfma_f32_16x16x32_bf16 v[92:95], v[172:175], v[248:251], v[92:95]
	s_waitcnt lgkmcnt(0)
	s_waitcnt vmcnt(0)
	s_barrier
	v_xor_b32_e32 v154, 0x10000, v154
	v_xor_b32_e32 v155, 0x10000, v155
	v_xor_b32_e32 v167, 0x10000, v167
	v_xor_b32_e32 v192, 0x10000, v192
	v_mfma_f32_16x16x32_bf16 v[96:99], v[176:179], v[244:247], v[96:99]
	ds_read_b128 v[168:171], v154
	ds_read_b128 v[172:175], v154 offset:2048
	s_add_u32 m0, s68, 0x10000
	v_mfma_f32_16x16x32_bf16 v[100:103], v[176:179], v[212:215], v[100:103]
	global_load_lds_dwordx4 v150, s[62:63]
	v_mfma_f32_16x16x32_bf16 v[104:107], v[176:179], v[216:219], v[104:107]
	ds_read_b128 v[184:187], v167 offset:32768
	ds_read_b128 v[196:199], v167 offset:34816
	s_add_u32 m0, s68, 0x18000
	v_mfma_f32_16x16x32_bf16 v[108:111], v[176:179], v[248:251], v[108:111]
	global_load_lds_dwordx4 v134, s[64:65]
	v_mfma_f32_16x16x32_bf16 v[112:115], v[180:183], v[244:247], v[112:115]
	ds_read_b128 v[176:179], v154 offset:4096
	s_add_u32 m0, s68, 0x12000
	v_mfma_f32_16x16x32_bf16 v[116:119], v[180:183], v[212:215], v[116:119]
	global_load_lds_dwordx4 v148, s[62:63]
	ds_read_b128 v[200:203], v167 offset:36864
	ds_read_b128 v[240:243], v167 offset:38912
	v_mfma_f32_16x16x32_bf16 v[120:123], v[180:183], v[216:219], v[120:123]
	s_add_u32 m0, s68, 0x1a000
	v_mfma_f32_16x16x32_bf16 v[124:127], v[180:183], v[248:251], v[124:127]
	global_load_lds_dwordx4 v132, s[64:65]
	s_waitcnt lgkmcnt(4)
	v_mfma_f32_16x16x32_bf16 v[0:3], v[168:171], v[184:187], v[0:3]
	ds_read_b128 v[180:183], v154 offset:6144
	s_waitcnt lgkmcnt(4)
	v_mfma_f32_16x16x32_bf16 v[4:7], v[168:171], v[196:199], v[4:7]
	ds_read_b128 v[244:247], v192 offset:32768
	s_waitcnt lgkmcnt(3)
	v_mfma_f32_16x16x32_bf16 v[8:11], v[168:171], v[200:203], v[8:11]
	s_waitcnt lgkmcnt(2)
	v_mfma_f32_16x16x32_bf16 v[12:15], v[168:171], v[240:243], v[12:15]
	v_mfma_f32_16x16x32_bf16 v[16:19], v[172:175], v[184:187], v[16:19]
	ds_read_b128 v[168:171], v154 offset:8192
	v_mfma_f32_16x16x32_bf16 v[20:23], v[172:175], v[196:199], v[20:23]
	ds_read_b128 v[212:215], v192 offset:34816
	v_mfma_f32_16x16x32_bf16 v[24:27], v[172:175], v[200:203], v[24:27]
	v_mfma_f32_16x16x32_bf16 v[28:31], v[172:175], v[240:243], v[28:31]
	v_mfma_f32_16x16x32_bf16 v[32:35], v[176:179], v[184:187], v[32:35]
	ds_read_b128 v[172:175], v154 offset:10240
	v_mfma_f32_16x16x32_bf16 v[36:39], v[176:179], v[196:199], v[36:39]
	ds_read_b128 v[216:219], v192 offset:36864
	v_mfma_f32_16x16x32_bf16 v[40:43], v[176:179], v[200:203], v[40:43]
	s_add_u32 m0, s68, 0x14000
	v_mfma_f32_16x16x32_bf16 v[44:47], v[176:179], v[240:243], v[44:47]
	global_load_lds_dwordx4 v146, s[62:63]
	s_waitcnt lgkmcnt(5)
	v_mfma_f32_16x16x32_bf16 v[48:51], v[180:183], v[184:187], v[48:51]
	ds_read_b128 v[176:179], v154 offset:12288
	v_mfma_f32_16x16x32_bf16 v[52:55], v[180:183], v[196:199], v[52:55]
	ds_read_b128 v[248:251], v192 offset:38912
	v_mfma_f32_16x16x32_bf16 v[56:59], v[180:183], v[200:203], v[56:59]
	s_add_u32 m0, s68, 0x1c000
	v_mfma_f32_16x16x32_bf16 v[60:63], v[180:183], v[240:243], v[60:63]
	global_load_lds_dwordx4 v130, s[64:65]
	s_waitcnt lgkmcnt(5)
	v_mfma_f32_16x16x32_bf16 v[64:67], v[168:171], v[184:187], v[64:67]
	ds_read_b128 v[180:183], v154 offset:14336
	v_mfma_f32_16x16x32_bf16 v[68:71], v[168:171], v[196:199], v[68:71]
	v_mfma_f32_16x16x32_bf16 v[72:75], v[168:171], v[200:203], v[72:75]
	s_add_u32 m0, s68, 0x16000
	v_mfma_f32_16x16x32_bf16 v[76:79], v[168:171], v[240:243], v[76:79]
	global_load_lds_dwordx4 v144, s[62:63]
	s_waitcnt lgkmcnt(4)
	v_mfma_f32_16x16x32_bf16 v[80:83], v[172:175], v[184:187], v[80:83]
	ds_read_b128 v[168:171], v155
	v_mfma_f32_16x16x32_bf16 v[84:87], v[172:175], v[196:199], v[84:87]
	v_mfma_f32_16x16x32_bf16 v[88:91], v[172:175], v[200:203], v[88:91]
	s_add_u32 m0, s68, 0x1e000
	v_mfma_f32_16x16x32_bf16 v[92:95], v[172:175], v[240:243], v[92:95]
	global_load_lds_dwordx4 v152, s[64:65]
	s_add_u32 s62, s62, 0x80
	s_addc_u32 s63, s63, 0
	s_add_u32 s64, s64, 0x80
	s_addc_u32 s65, s65, 0
	s_waitcnt lgkmcnt(3)
	v_mfma_f32_16x16x32_bf16 v[96:99], v[176:179], v[184:187], v[96:99]
	ds_read_b128 v[172:175], v155 offset:2048
	v_mfma_f32_16x16x32_bf16 v[100:103], v[176:179], v[196:199], v[100:103]
	v_mfma_f32_16x16x32_bf16 v[104:107], v[176:179], v[200:203], v[104:107]
	v_mfma_f32_16x16x32_bf16 v[108:111], v[176:179], v[240:243], v[108:111]
	s_waitcnt lgkmcnt(2)
	v_mfma_f32_16x16x32_bf16 v[112:115], v[180:183], v[184:187], v[112:115]
	ds_read_b128 v[176:179], v155 offset:4096
	v_mfma_f32_16x16x32_bf16 v[116:119], v[180:183], v[196:199], v[116:119]
	v_mfma_f32_16x16x32_bf16 v[120:123], v[180:183], v[200:203], v[120:123]
	v_mfma_f32_16x16x32_bf16 v[124:127], v[180:183], v[240:243], v[124:127]
	s_waitcnt lgkmcnt(2)
	v_mfma_f32_16x16x32_bf16 v[0:3], v[168:171], v[244:247], v[0:3]
	ds_read_b128 v[180:183], v155 offset:6144
	v_mfma_f32_16x16x32_bf16 v[4:7], v[168:171], v[212:215], v[4:7]
	v_mfma_f32_16x16x32_bf16 v[8:11], v[168:171], v[216:219], v[8:11]
	v_mfma_f32_16x16x32_bf16 v[12:15], v[168:171], v[248:251], v[12:15]
	s_waitcnt lgkmcnt(2)
	v_mfma_f32_16x16x32_bf16 v[16:19], v[172:175], v[244:247], v[16:19]
	ds_read_b128 v[168:171], v155 offset:8192
	v_mfma_f32_16x16x32_bf16 v[20:23], v[172:175], v[212:215], v[20:23]
	v_mfma_f32_16x16x32_bf16 v[24:27], v[172:175], v[216:219], v[24:27]
	v_mfma_f32_16x16x32_bf16 v[28:31], v[172:175], v[248:251], v[28:31]
	s_waitcnt lgkmcnt(2)
	v_mfma_f32_16x16x32_bf16 v[32:35], v[176:179], v[244:247], v[32:35]
	ds_read_b128 v[172:175], v155 offset:10240
	v_mfma_f32_16x16x32_bf16 v[36:39], v[176:179], v[212:215], v[36:39]
	v_mfma_f32_16x16x32_bf16 v[40:43], v[176:179], v[216:219], v[40:43]
	v_mfma_f32_16x16x32_bf16 v[44:47], v[176:179], v[248:251], v[44:47]
	s_waitcnt lgkmcnt(2)
	v_mfma_f32_16x16x32_bf16 v[48:51], v[180:183], v[244:247], v[48:51]
	ds_read_b128 v[176:179], v155 offset:12288
	v_mfma_f32_16x16x32_bf16 v[52:55], v[180:183], v[212:215], v[52:55]
	v_mfma_f32_16x16x32_bf16 v[56:59], v[180:183], v[216:219], v[56:59]
	v_mfma_f32_16x16x32_bf16 v[60:63], v[180:183], v[248:251], v[60:63]
	s_waitcnt lgkmcnt(2)
	v_mfma_f32_16x16x32_bf16 v[64:67], v[168:171], v[244:247], v[64:67]
	ds_read_b128 v[180:183], v155 offset:14336
	v_mfma_f32_16x16x32_bf16 v[68:71], v[168:171], v[212:215], v[68:71]
	v_mfma_f32_16x16x32_bf16 v[72:75], v[168:171], v[216:219], v[72:75]
	v_mfma_f32_16x16x32_bf16 v[76:79], v[168:171], v[248:251], v[76:79]
	s_waitcnt lgkmcnt(2)
	v_mfma_f32_16x16x32_bf16 v[80:83], v[172:175], v[244:247], v[80:83]
	v_mfma_f32_16x16x32_bf16 v[84:87], v[172:175], v[212:215], v[84:87]
	v_mfma_f32_16x16x32_bf16 v[88:91], v[172:175], v[216:219], v[88:91]
	v_mfma_f32_16x16x32_bf16 v[92:95], v[172:175], v[248:251], v[92:95]
	s_waitcnt lgkmcnt(0)
	s_waitcnt vmcnt(0)
	s_barrier
	v_xor_b32_e32 v154, 0x10000, v154
	v_xor_b32_e32 v155, 0x10000, v155
	v_xor_b32_e32 v167, 0x10000, v167
	v_xor_b32_e32 v192, 0x10000, v192
	v_mfma_f32_16x16x32_bf16 v[96:99], v[176:179], v[244:247], v[96:99]
	ds_read_b128 v[168:171], v154
	ds_read_b128 v[172:175], v154 offset:2048
	s_mov_b32 m0, s68
	v_mfma_f32_16x16x32_bf16 v[100:103], v[176:179], v[212:215], v[100:103]
	global_load_lds_dwordx4 v150, s[62:63]
	v_mfma_f32_16x16x32_bf16 v[104:107], v[176:179], v[216:219], v[104:107]
	ds_read_b128 v[184:187], v167 offset:32768
	ds_read_b128 v[196:199], v167 offset:34816
	s_add_u32 m0, s68, 0x8000
	v_mfma_f32_16x16x32_bf16 v[108:111], v[176:179], v[248:251], v[108:111]
	global_load_lds_dwordx4 v134, s[64:65]
	v_mfma_f32_16x16x32_bf16 v[112:115], v[180:183], v[244:247], v[112:115]
	ds_read_b128 v[176:179], v154 offset:4096
	s_add_u32 m0, s68, 0x2000
	v_mfma_f32_16x16x32_bf16 v[116:119], v[180:183], v[212:215], v[116:119]
	global_load_lds_dwordx4 v148, s[62:63]
	ds_read_b128 v[200:203], v167 offset:36864
	ds_read_b128 v[240:243], v167 offset:38912
	v_mfma_f32_16x16x32_bf16 v[120:123], v[180:183], v[216:219], v[120:123]
	s_add_u32 m0, s68, 0xa000
	v_mfma_f32_16x16x32_bf16 v[124:127], v[180:183], v[248:251], v[124:127]
	global_load_lds_dwordx4 v132, s[64:65]
	s_waitcnt lgkmcnt(4)
	v_mfma_f32_16x16x32_bf16 v[0:3], v[168:171], v[184:187], v[0:3]
	ds_read_b128 v[180:183], v154 offset:6144
	s_waitcnt lgkmcnt(4)
	v_mfma_f32_16x16x32_bf16 v[4:7], v[168:171], v[196:199], v[4:7]
	ds_read_b128 v[244:247], v192 offset:32768
	s_waitcnt lgkmcnt(3)
	v_mfma_f32_16x16x32_bf16 v[8:11], v[168:171], v[200:203], v[8:11]
	s_waitcnt lgkmcnt(2)
	v_mfma_f32_16x16x32_bf16 v[12:15], v[168:171], v[240:243], v[12:15]
	v_mfma_f32_16x16x32_bf16 v[16:19], v[172:175], v[184:187], v[16:19]
	ds_read_b128 v[168:171], v154 offset:8192
	v_mfma_f32_16x16x32_bf16 v[20:23], v[172:175], v[196:199], v[20:23]
	ds_read_b128 v[212:215], v192 offset:34816
	v_mfma_f32_16x16x32_bf16 v[24:27], v[172:175], v[200:203], v[24:27]
	v_mfma_f32_16x16x32_bf16 v[28:31], v[172:175], v[240:243], v[28:31]
	v_mfma_f32_16x16x32_bf16 v[32:35], v[176:179], v[184:187], v[32:35]
	ds_read_b128 v[172:175], v154 offset:10240
	v_mfma_f32_16x16x32_bf16 v[36:39], v[176:179], v[196:199], v[36:39]
	ds_read_b128 v[216:219], v192 offset:36864
	v_mfma_f32_16x16x32_bf16 v[40:43], v[176:179], v[200:203], v[40:43]
	s_add_u32 m0, s68, 0x4000
	v_mfma_f32_16x16x32_bf16 v[44:47], v[176:179], v[240:243], v[44:47]
	global_load_lds_dwordx4 v146, s[62:63]
	s_waitcnt lgkmcnt(5)
	v_mfma_f32_16x16x32_bf16 v[48:51], v[180:183], v[184:187], v[48:51]
	ds_read_b128 v[176:179], v154 offset:12288
	v_mfma_f32_16x16x32_bf16 v[52:55], v[180:183], v[196:199], v[52:55]
	ds_read_b128 v[248:251], v192 offset:38912
	v_mfma_f32_16x16x32_bf16 v[56:59], v[180:183], v[200:203], v[56:59]
	s_add_u32 m0, s68, 0xc000
	v_mfma_f32_16x16x32_bf16 v[60:63], v[180:183], v[240:243], v[60:63]
	global_load_lds_dwordx4 v130, s[64:65]
	s_waitcnt lgkmcnt(5)
	v_mfma_f32_16x16x32_bf16 v[64:67], v[168:171], v[184:187], v[64:67]
	ds_read_b128 v[180:183], v154 offset:14336
	v_mfma_f32_16x16x32_bf16 v[68:71], v[168:171], v[196:199], v[68:71]
	v_mfma_f32_16x16x32_bf16 v[72:75], v[168:171], v[200:203], v[72:75]
	s_add_u32 m0, s68, 0x6000
	v_mfma_f32_16x16x32_bf16 v[76:79], v[168:171], v[240:243], v[76:79]
	global_load_lds_dwordx4 v144, s[62:63]
	s_waitcnt lgkmcnt(4)
	v_mfma_f32_16x16x32_bf16 v[80:83], v[172:175], v[184:187], v[80:83]
	ds_read_b128 v[168:171], v155
	v_mfma_f32_16x16x32_bf16 v[84:87], v[172:175], v[196:199], v[84:87]
	v_mfma_f32_16x16x32_bf16 v[88:91], v[172:175], v[200:203], v[88:91]
	s_add_u32 m0, s68, 0xe000
	v_mfma_f32_16x16x32_bf16 v[92:95], v[172:175], v[240:243], v[92:95]
	global_load_lds_dwordx4 v152, s[64:65]
	s_add_u32 s62, s62, 0x80
	s_addc_u32 s63, s63, 0
	s_add_u32 s64, s64, 0x80
	s_addc_u32 s65, s65, 0
	s_waitcnt lgkmcnt(3)
	v_mfma_f32_16x16x32_bf16 v[96:99], v[176:179], v[184:187], v[96:99]
	ds_read_b128 v[172:175], v155 offset:2048
	v_mfma_f32_16x16x32_bf16 v[100:103], v[176:179], v[196:199], v[100:103]
	v_mfma_f32_16x16x32_bf16 v[104:107], v[176:179], v[200:203], v[104:107]
	v_mfma_f32_16x16x32_bf16 v[108:111], v[176:179], v[240:243], v[108:111]
	s_waitcnt lgkmcnt(2)
	v_mfma_f32_16x16x32_bf16 v[112:115], v[180:183], v[184:187], v[112:115]
	ds_read_b128 v[176:179], v155 offset:4096
	v_mfma_f32_16x16x32_bf16 v[116:119], v[180:183], v[196:199], v[116:119]
	v_mfma_f32_16x16x32_bf16 v[120:123], v[180:183], v[200:203], v[120:123]
	v_mfma_f32_16x16x32_bf16 v[124:127], v[180:183], v[240:243], v[124:127]
	s_waitcnt lgkmcnt(2)
	v_mfma_f32_16x16x32_bf16 v[0:3], v[168:171], v[244:247], v[0:3]
	ds_read_b128 v[180:183], v155 offset:6144
	v_mfma_f32_16x16x32_bf16 v[4:7], v[168:171], v[212:215], v[4:7]
	v_mfma_f32_16x16x32_bf16 v[8:11], v[168:171], v[216:219], v[8:11]
	v_mfma_f32_16x16x32_bf16 v[12:15], v[168:171], v[248:251], v[12:15]
	s_waitcnt lgkmcnt(2)
	v_mfma_f32_16x16x32_bf16 v[16:19], v[172:175], v[244:247], v[16:19]
	ds_read_b128 v[168:171], v155 offset:8192
	v_mfma_f32_16x16x32_bf16 v[20:23], v[172:175], v[212:215], v[20:23]
	v_mfma_f32_16x16x32_bf16 v[24:27], v[172:175], v[216:219], v[24:27]
	v_mfma_f32_16x16x32_bf16 v[28:31], v[172:175], v[248:251], v[28:31]
	s_waitcnt lgkmcnt(2)
	v_mfma_f32_16x16x32_bf16 v[32:35], v[176:179], v[244:247], v[32:35]
	ds_read_b128 v[172:175], v155 offset:10240
	v_mfma_f32_16x16x32_bf16 v[36:39], v[176:179], v[212:215], v[36:39]
	v_mfma_f32_16x16x32_bf16 v[40:43], v[176:179], v[216:219], v[40:43]
	v_mfma_f32_16x16x32_bf16 v[44:47], v[176:179], v[248:251], v[44:47]
	s_waitcnt lgkmcnt(2)
	v_mfma_f32_16x16x32_bf16 v[48:51], v[180:183], v[244:247], v[48:51]
	ds_read_b128 v[176:179], v155 offset:12288
	v_mfma_f32_16x16x32_bf16 v[52:55], v[180:183], v[212:215], v[52:55]
	v_mfma_f32_16x16x32_bf16 v[56:59], v[180:183], v[216:219], v[56:59]
	v_mfma_f32_16x16x32_bf16 v[60:63], v[180:183], v[248:251], v[60:63]
	s_waitcnt lgkmcnt(2)
	v_mfma_f32_16x16x32_bf16 v[64:67], v[168:171], v[244:247], v[64:67]
	ds_read_b128 v[180:183], v155 offset:14336
	v_mfma_f32_16x16x32_bf16 v[68:71], v[168:171], v[212:215], v[68:71]
	v_mfma_f32_16x16x32_bf16 v[72:75], v[168:171], v[216:219], v[72:75]
	v_mfma_f32_16x16x32_bf16 v[76:79], v[168:171], v[248:251], v[76:79]
	s_waitcnt lgkmcnt(2)
	v_mfma_f32_16x16x32_bf16 v[80:83], v[172:175], v[244:247], v[80:83]
	v_mfma_f32_16x16x32_bf16 v[84:87], v[172:175], v[212:215], v[84:87]
	v_mfma_f32_16x16x32_bf16 v[88:91], v[172:175], v[216:219], v[88:91]
	v_mfma_f32_16x16x32_bf16 v[92:95], v[172:175], v[248:251], v[92:95]
	s_waitcnt lgkmcnt(0)
	s_waitcnt vmcnt(0)
	s_barrier
	v_xor_b32_e32 v154, 0x10000, v154
	v_xor_b32_e32 v155, 0x10000, v155
	v_xor_b32_e32 v167, 0x10000, v167
	v_xor_b32_e32 v192, 0x10000, v192
	v_mfma_f32_16x16x32_bf16 v[96:99], v[176:179], v[244:247], v[96:99]
	ds_read_b128 v[168:171], v154
	ds_read_b128 v[172:175], v154 offset:2048
	s_add_u32 m0, s68, 0x10000
	v_mfma_f32_16x16x32_bf16 v[100:103], v[176:179], v[212:215], v[100:103]
	global_load_lds_dwordx4 v150, s[62:63]
	v_mfma_f32_16x16x32_bf16 v[104:107], v[176:179], v[216:219], v[104:107]
	ds_read_b128 v[184:187], v167 offset:32768
	ds_read_b128 v[196:199], v167 offset:34816
	s_add_u32 m0, s68, 0x18000
	v_mfma_f32_16x16x32_bf16 v[108:111], v[176:179], v[248:251], v[108:111]
	global_load_lds_dwordx4 v134, s[64:65]
	v_mfma_f32_16x16x32_bf16 v[112:115], v[180:183], v[244:247], v[112:115]
	ds_read_b128 v[176:179], v154 offset:4096
	s_add_u32 m0, s68, 0x12000
	v_mfma_f32_16x16x32_bf16 v[116:119], v[180:183], v[212:215], v[116:119]
	global_load_lds_dwordx4 v148, s[62:63]
	ds_read_b128 v[200:203], v167 offset:36864
	ds_read_b128 v[240:243], v167 offset:38912
	v_mfma_f32_16x16x32_bf16 v[120:123], v[180:183], v[216:219], v[120:123]
	s_add_u32 m0, s68, 0x1a000
	v_mfma_f32_16x16x32_bf16 v[124:127], v[180:183], v[248:251], v[124:127]
	global_load_lds_dwordx4 v132, s[64:65]
	s_waitcnt lgkmcnt(4)
	v_mfma_f32_16x16x32_bf16 v[0:3], v[168:171], v[184:187], v[0:3]
	ds_read_b128 v[180:183], v154 offset:6144
	s_waitcnt lgkmcnt(4)
	v_mfma_f32_16x16x32_bf16 v[4:7], v[168:171], v[196:199], v[4:7]
	ds_read_b128 v[244:247], v192 offset:32768
	s_waitcnt lgkmcnt(3)
	v_mfma_f32_16x16x32_bf16 v[8:11], v[168:171], v[200:203], v[8:11]
	s_waitcnt lgkmcnt(2)
	v_mfma_f32_16x16x32_bf16 v[12:15], v[168:171], v[240:243], v[12:15]
	v_mfma_f32_16x16x32_bf16 v[16:19], v[172:175], v[184:187], v[16:19]
	ds_read_b128 v[168:171], v154 offset:8192
	v_mfma_f32_16x16x32_bf16 v[20:23], v[172:175], v[196:199], v[20:23]
	ds_read_b128 v[212:215], v192 offset:34816
	v_mfma_f32_16x16x32_bf16 v[24:27], v[172:175], v[200:203], v[24:27]
	v_mfma_f32_16x16x32_bf16 v[28:31], v[172:175], v[240:243], v[28:31]
	v_mfma_f32_16x16x32_bf16 v[32:35], v[176:179], v[184:187], v[32:35]
	ds_read_b128 v[172:175], v154 offset:10240
	v_mfma_f32_16x16x32_bf16 v[36:39], v[176:179], v[196:199], v[36:39]
	ds_read_b128 v[216:219], v192 offset:36864
	v_mfma_f32_16x16x32_bf16 v[40:43], v[176:179], v[200:203], v[40:43]
	s_add_u32 m0, s68, 0x14000
	v_mfma_f32_16x16x32_bf16 v[44:47], v[176:179], v[240:243], v[44:47]
	global_load_lds_dwordx4 v146, s[62:63]
	s_waitcnt lgkmcnt(5)
	v_mfma_f32_16x16x32_bf16 v[48:51], v[180:183], v[184:187], v[48:51]
	ds_read_b128 v[176:179], v154 offset:12288
	v_mfma_f32_16x16x32_bf16 v[52:55], v[180:183], v[196:199], v[52:55]
	ds_read_b128 v[248:251], v192 offset:38912
	v_mfma_f32_16x16x32_bf16 v[56:59], v[180:183], v[200:203], v[56:59]
	s_add_u32 m0, s68, 0x1c000
	v_mfma_f32_16x16x32_bf16 v[60:63], v[180:183], v[240:243], v[60:63]
	global_load_lds_dwordx4 v130, s[64:65]
	s_waitcnt lgkmcnt(5)
	v_mfma_f32_16x16x32_bf16 v[64:67], v[168:171], v[184:187], v[64:67]
	ds_read_b128 v[180:183], v154 offset:14336
	v_mfma_f32_16x16x32_bf16 v[68:71], v[168:171], v[196:199], v[68:71]
	v_mfma_f32_16x16x32_bf16 v[72:75], v[168:171], v[200:203], v[72:75]
	s_add_u32 m0, s68, 0x16000
	v_mfma_f32_16x16x32_bf16 v[76:79], v[168:171], v[240:243], v[76:79]
	global_load_lds_dwordx4 v144, s[62:63]
	s_waitcnt lgkmcnt(4)
	v_mfma_f32_16x16x32_bf16 v[80:83], v[172:175], v[184:187], v[80:83]
	ds_read_b128 v[168:171], v155
	v_mfma_f32_16x16x32_bf16 v[84:87], v[172:175], v[196:199], v[84:87]
	v_mfma_f32_16x16x32_bf16 v[88:91], v[172:175], v[200:203], v[88:91]
	s_add_u32 m0, s68, 0x1e000
	v_mfma_f32_16x16x32_bf16 v[92:95], v[172:175], v[240:243], v[92:95]
	global_load_lds_dwordx4 v152, s[64:65]
	s_add_u32 s62, s62, 0x80
	s_addc_u32 s63, s63, 0
	s_add_u32 s64, s64, 0x80
	s_addc_u32 s65, s65, 0
	s_waitcnt lgkmcnt(3)
	v_mfma_f32_16x16x32_bf16 v[96:99], v[176:179], v[184:187], v[96:99]
	ds_read_b128 v[172:175], v155 offset:2048
	v_mfma_f32_16x16x32_bf16 v[100:103], v[176:179], v[196:199], v[100:103]
	v_mfma_f32_16x16x32_bf16 v[104:107], v[176:179], v[200:203], v[104:107]
	v_mfma_f32_16x16x32_bf16 v[108:111], v[176:179], v[240:243], v[108:111]
	s_waitcnt lgkmcnt(2)
	v_mfma_f32_16x16x32_bf16 v[112:115], v[180:183], v[184:187], v[112:115]
	ds_read_b128 v[176:179], v155 offset:4096
	v_mfma_f32_16x16x32_bf16 v[116:119], v[180:183], v[196:199], v[116:119]
	v_mfma_f32_16x16x32_bf16 v[120:123], v[180:183], v[200:203], v[120:123]
	v_mfma_f32_16x16x32_bf16 v[124:127], v[180:183], v[240:243], v[124:127]
	s_waitcnt lgkmcnt(2)
	v_mfma_f32_16x16x32_bf16 v[0:3], v[168:171], v[244:247], v[0:3]
	ds_read_b128 v[180:183], v155 offset:6144
	v_mfma_f32_16x16x32_bf16 v[4:7], v[168:171], v[212:215], v[4:7]
	v_mfma_f32_16x16x32_bf16 v[8:11], v[168:171], v[216:219], v[8:11]
	v_mfma_f32_16x16x32_bf16 v[12:15], v[168:171], v[248:251], v[12:15]
	s_waitcnt lgkmcnt(2)
	v_mfma_f32_16x16x32_bf16 v[16:19], v[172:175], v[244:247], v[16:19]
	ds_read_b128 v[168:171], v155 offset:8192
	v_mfma_f32_16x16x32_bf16 v[20:23], v[172:175], v[212:215], v[20:23]
	v_mfma_f32_16x16x32_bf16 v[24:27], v[172:175], v[216:219], v[24:27]
	v_mfma_f32_16x16x32_bf16 v[28:31], v[172:175], v[248:251], v[28:31]
	s_waitcnt lgkmcnt(2)
	v_mfma_f32_16x16x32_bf16 v[32:35], v[176:179], v[244:247], v[32:35]
	ds_read_b128 v[172:175], v155 offset:10240
	v_mfma_f32_16x16x32_bf16 v[36:39], v[176:179], v[212:215], v[36:39]
	v_mfma_f32_16x16x32_bf16 v[40:43], v[176:179], v[216:219], v[40:43]
	v_mfma_f32_16x16x32_bf16 v[44:47], v[176:179], v[248:251], v[44:47]
	s_waitcnt lgkmcnt(2)
	v_mfma_f32_16x16x32_bf16 v[48:51], v[180:183], v[244:247], v[48:51]
	ds_read_b128 v[176:179], v155 offset:12288
	v_mfma_f32_16x16x32_bf16 v[52:55], v[180:183], v[212:215], v[52:55]
	v_mfma_f32_16x16x32_bf16 v[56:59], v[180:183], v[216:219], v[56:59]
	v_mfma_f32_16x16x32_bf16 v[60:63], v[180:183], v[248:251], v[60:63]
	s_waitcnt lgkmcnt(2)
	v_mfma_f32_16x16x32_bf16 v[64:67], v[168:171], v[244:247], v[64:67]
	ds_read_b128 v[180:183], v155 offset:14336
	v_mfma_f32_16x16x32_bf16 v[68:71], v[168:171], v[212:215], v[68:71]
	v_mfma_f32_16x16x32_bf16 v[72:75], v[168:171], v[216:219], v[72:75]
	v_mfma_f32_16x16x32_bf16 v[76:79], v[168:171], v[248:251], v[76:79]
	s_waitcnt lgkmcnt(2)
	v_mfma_f32_16x16x32_bf16 v[80:83], v[172:175], v[244:247], v[80:83]
	v_mfma_f32_16x16x32_bf16 v[84:87], v[172:175], v[212:215], v[84:87]
	v_mfma_f32_16x16x32_bf16 v[88:91], v[172:175], v[216:219], v[88:91]
	v_mfma_f32_16x16x32_bf16 v[92:95], v[172:175], v[248:251], v[92:95]
	s_waitcnt lgkmcnt(0)
	s_waitcnt vmcnt(0)
	s_barrier
	v_xor_b32_e32 v154, 0x10000, v154
	v_xor_b32_e32 v155, 0x10000, v155
	v_xor_b32_e32 v167, 0x10000, v167
	v_xor_b32_e32 v192, 0x10000, v192
	v_mfma_f32_16x16x32_bf16 v[96:99], v[176:179], v[244:247], v[96:99]
	ds_read_b128 v[168:171], v154
	ds_read_b128 v[172:175], v154 offset:2048
	s_mov_b32 m0, s68
	v_mfma_f32_16x16x32_bf16 v[100:103], v[176:179], v[212:215], v[100:103]
	global_load_lds_dwordx4 v150, s[62:63]
	v_mfma_f32_16x16x32_bf16 v[104:107], v[176:179], v[216:219], v[104:107]
	ds_read_b128 v[184:187], v167 offset:32768
	ds_read_b128 v[196:199], v167 offset:34816
	s_add_u32 m0, s68, 0x8000
	v_mfma_f32_16x16x32_bf16 v[108:111], v[176:179], v[248:251], v[108:111]
	global_load_lds_dwordx4 v134, s[64:65]
	v_mfma_f32_16x16x32_bf16 v[112:115], v[180:183], v[244:247], v[112:115]
	ds_read_b128 v[176:179], v154 offset:4096
	s_add_u32 m0, s68, 0x2000
	v_mfma_f32_16x16x32_bf16 v[116:119], v[180:183], v[212:215], v[116:119]
	global_load_lds_dwordx4 v148, s[62:63]
	ds_read_b128 v[200:203], v167 offset:36864
	ds_read_b128 v[240:243], v167 offset:38912
	v_mfma_f32_16x16x32_bf16 v[120:123], v[180:183], v[216:219], v[120:123]
	s_add_u32 m0, s68, 0xa000
	v_mfma_f32_16x16x32_bf16 v[124:127], v[180:183], v[248:251], v[124:127]
	global_load_lds_dwordx4 v132, s[64:65]
	s_waitcnt lgkmcnt(4)
	v_mfma_f32_16x16x32_bf16 v[0:3], v[168:171], v[184:187], v[0:3]
	ds_read_b128 v[180:183], v154 offset:6144
	s_waitcnt lgkmcnt(4)
	v_mfma_f32_16x16x32_bf16 v[4:7], v[168:171], v[196:199], v[4:7]
	ds_read_b128 v[244:247], v192 offset:32768
	s_waitcnt lgkmcnt(3)
	v_mfma_f32_16x16x32_bf16 v[8:11], v[168:171], v[200:203], v[8:11]
	s_waitcnt lgkmcnt(2)
	v_mfma_f32_16x16x32_bf16 v[12:15], v[168:171], v[240:243], v[12:15]
	v_mfma_f32_16x16x32_bf16 v[16:19], v[172:175], v[184:187], v[16:19]
	ds_read_b128 v[168:171], v154 offset:8192
	v_mfma_f32_16x16x32_bf16 v[20:23], v[172:175], v[196:199], v[20:23]
	ds_read_b128 v[212:215], v192 offset:34816
	v_mfma_f32_16x16x32_bf16 v[24:27], v[172:175], v[200:203], v[24:27]
	v_mfma_f32_16x16x32_bf16 v[28:31], v[172:175], v[240:243], v[28:31]
	v_mfma_f32_16x16x32_bf16 v[32:35], v[176:179], v[184:187], v[32:35]
	ds_read_b128 v[172:175], v154 offset:10240
	v_mfma_f32_16x16x32_bf16 v[36:39], v[176:179], v[196:199], v[36:39]
	ds_read_b128 v[216:219], v192 offset:36864
	v_mfma_f32_16x16x32_bf16 v[40:43], v[176:179], v[200:203], v[40:43]
	s_add_u32 m0, s68, 0x4000
	v_mfma_f32_16x16x32_bf16 v[44:47], v[176:179], v[240:243], v[44:47]
	global_load_lds_dwordx4 v146, s[62:63]
	s_waitcnt lgkmcnt(5)
	v_mfma_f32_16x16x32_bf16 v[48:51], v[180:183], v[184:187], v[48:51]
	ds_read_b128 v[176:179], v154 offset:12288
	v_mfma_f32_16x16x32_bf16 v[52:55], v[180:183], v[196:199], v[52:55]
	ds_read_b128 v[248:251], v192 offset:38912
	v_mfma_f32_16x16x32_bf16 v[56:59], v[180:183], v[200:203], v[56:59]
	s_add_u32 m0, s68, 0xc000
	v_mfma_f32_16x16x32_bf16 v[60:63], v[180:183], v[240:243], v[60:63]
	global_load_lds_dwordx4 v130, s[64:65]
	s_waitcnt lgkmcnt(5)
	v_mfma_f32_16x16x32_bf16 v[64:67], v[168:171], v[184:187], v[64:67]
	ds_read_b128 v[180:183], v154 offset:14336
	v_mfma_f32_16x16x32_bf16 v[68:71], v[168:171], v[196:199], v[68:71]
	v_mfma_f32_16x16x32_bf16 v[72:75], v[168:171], v[200:203], v[72:75]
	s_add_u32 m0, s68, 0x6000
	v_mfma_f32_16x16x32_bf16 v[76:79], v[168:171], v[240:243], v[76:79]
	global_load_lds_dwordx4 v144, s[62:63]
	s_waitcnt lgkmcnt(4)
	v_mfma_f32_16x16x32_bf16 v[80:83], v[172:175], v[184:187], v[80:83]
	ds_read_b128 v[168:171], v155
	v_mfma_f32_16x16x32_bf16 v[84:87], v[172:175], v[196:199], v[84:87]
	v_mfma_f32_16x16x32_bf16 v[88:91], v[172:175], v[200:203], v[88:91]
	s_add_u32 m0, s68, 0xe000
	v_mfma_f32_16x16x32_bf16 v[92:95], v[172:175], v[240:243], v[92:95]
	global_load_lds_dwordx4 v152, s[64:65]
	s_add_u32 s62, s62, 0x80
	s_addc_u32 s63, s63, 0
	s_add_u32 s64, s64, 0x80
	s_addc_u32 s65, s65, 0
	s_waitcnt lgkmcnt(3)
	v_mfma_f32_16x16x32_bf16 v[96:99], v[176:179], v[184:187], v[96:99]
	ds_read_b128 v[172:175], v155 offset:2048
	v_mfma_f32_16x16x32_bf16 v[100:103], v[176:179], v[196:199], v[100:103]
	v_mfma_f32_16x16x32_bf16 v[104:107], v[176:179], v[200:203], v[104:107]
	v_mfma_f32_16x16x32_bf16 v[108:111], v[176:179], v[240:243], v[108:111]
	s_waitcnt lgkmcnt(2)
	v_mfma_f32_16x16x32_bf16 v[112:115], v[180:183], v[184:187], v[112:115]
	ds_read_b128 v[176:179], v155 offset:4096
	v_mfma_f32_16x16x32_bf16 v[116:119], v[180:183], v[196:199], v[116:119]
	v_mfma_f32_16x16x32_bf16 v[120:123], v[180:183], v[200:203], v[120:123]
	v_mfma_f32_16x16x32_bf16 v[124:127], v[180:183], v[240:243], v[124:127]
	s_waitcnt lgkmcnt(2)
	v_mfma_f32_16x16x32_bf16 v[0:3], v[168:171], v[244:247], v[0:3]
	ds_read_b128 v[180:183], v155 offset:6144
	v_mfma_f32_16x16x32_bf16 v[4:7], v[168:171], v[212:215], v[4:7]
	v_mfma_f32_16x16x32_bf16 v[8:11], v[168:171], v[216:219], v[8:11]
	v_mfma_f32_16x16x32_bf16 v[12:15], v[168:171], v[248:251], v[12:15]
	s_waitcnt lgkmcnt(2)
	v_mfma_f32_16x16x32_bf16 v[16:19], v[172:175], v[244:247], v[16:19]
	ds_read_b128 v[168:171], v155 offset:8192
	v_mfma_f32_16x16x32_bf16 v[20:23], v[172:175], v[212:215], v[20:23]
	v_mfma_f32_16x16x32_bf16 v[24:27], v[172:175], v[216:219], v[24:27]
	v_mfma_f32_16x16x32_bf16 v[28:31], v[172:175], v[248:251], v[28:31]
	s_waitcnt lgkmcnt(2)
	v_mfma_f32_16x16x32_bf16 v[32:35], v[176:179], v[244:247], v[32:35]
	ds_read_b128 v[172:175], v155 offset:10240
	v_mfma_f32_16x16x32_bf16 v[36:39], v[176:179], v[212:215], v[36:39]
	v_mfma_f32_16x16x32_bf16 v[40:43], v[176:179], v[216:219], v[40:43]
	v_mfma_f32_16x16x32_bf16 v[44:47], v[176:179], v[248:251], v[44:47]
	s_waitcnt lgkmcnt(2)
	v_mfma_f32_16x16x32_bf16 v[48:51], v[180:183], v[244:247], v[48:51]
	ds_read_b128 v[176:179], v155 offset:12288
	v_mfma_f32_16x16x32_bf16 v[52:55], v[180:183], v[212:215], v[52:55]
	v_mfma_f32_16x16x32_bf16 v[56:59], v[180:183], v[216:219], v[56:59]
	v_mfma_f32_16x16x32_bf16 v[60:63], v[180:183], v[248:251], v[60:63]
	s_waitcnt lgkmcnt(2)
	v_mfma_f32_16x16x32_bf16 v[64:67], v[168:171], v[244:247], v[64:67]
	ds_read_b128 v[180:183], v155 offset:14336
	v_mfma_f32_16x16x32_bf16 v[68:71], v[168:171], v[212:215], v[68:71]
	v_mfma_f32_16x16x32_bf16 v[72:75], v[168:171], v[216:219], v[72:75]
	v_mfma_f32_16x16x32_bf16 v[76:79], v[168:171], v[248:251], v[76:79]
	s_waitcnt lgkmcnt(2)
	v_mfma_f32_16x16x32_bf16 v[80:83], v[172:175], v[244:247], v[80:83]
	v_mfma_f32_16x16x32_bf16 v[84:87], v[172:175], v[212:215], v[84:87]
	v_mfma_f32_16x16x32_bf16 v[88:91], v[172:175], v[216:219], v[88:91]
	v_mfma_f32_16x16x32_bf16 v[92:95], v[172:175], v[248:251], v[92:95]
	s_waitcnt lgkmcnt(0)
	s_waitcnt vmcnt(0)
	s_barrier
	v_xor_b32_e32 v154, 0x10000, v154
	v_xor_b32_e32 v155, 0x10000, v155
	v_xor_b32_e32 v167, 0x10000, v167
	v_xor_b32_e32 v192, 0x10000, v192
	v_mfma_f32_16x16x32_bf16 v[96:99], v[176:179], v[244:247], v[96:99]
	ds_read_b128 v[168:171], v154
	ds_read_b128 v[172:175], v154 offset:2048
	s_add_u32 m0, s68, 0x10000
	v_mfma_f32_16x16x32_bf16 v[100:103], v[176:179], v[212:215], v[100:103]
	global_load_lds_dwordx4 v150, s[62:63]
	v_mfma_f32_16x16x32_bf16 v[104:107], v[176:179], v[216:219], v[104:107]
	ds_read_b128 v[184:187], v167 offset:32768
	ds_read_b128 v[196:199], v167 offset:34816
	s_add_u32 m0, s68, 0x18000
	v_mfma_f32_16x16x32_bf16 v[108:111], v[176:179], v[248:251], v[108:111]
	global_load_lds_dwordx4 v134, s[64:65]
	v_mfma_f32_16x16x32_bf16 v[112:115], v[180:183], v[244:247], v[112:115]
	ds_read_b128 v[176:179], v154 offset:4096
	s_add_u32 m0, s68, 0x12000
	v_mfma_f32_16x16x32_bf16 v[116:119], v[180:183], v[212:215], v[116:119]
	global_load_lds_dwordx4 v148, s[62:63]
	ds_read_b128 v[200:203], v167 offset:36864
	ds_read_b128 v[240:243], v167 offset:38912
	v_mfma_f32_16x16x32_bf16 v[120:123], v[180:183], v[216:219], v[120:123]
	s_add_u32 m0, s68, 0x1a000
	v_mfma_f32_16x16x32_bf16 v[124:127], v[180:183], v[248:251], v[124:127]
	global_load_lds_dwordx4 v132, s[64:65]
	s_waitcnt lgkmcnt(4)
	v_mfma_f32_16x16x32_bf16 v[0:3], v[168:171], v[184:187], v[0:3]
	ds_read_b128 v[180:183], v154 offset:6144
	s_waitcnt lgkmcnt(4)
	v_mfma_f32_16x16x32_bf16 v[4:7], v[168:171], v[196:199], v[4:7]
	ds_read_b128 v[244:247], v192 offset:32768
	s_waitcnt lgkmcnt(3)
	v_mfma_f32_16x16x32_bf16 v[8:11], v[168:171], v[200:203], v[8:11]
	s_waitcnt lgkmcnt(2)
	v_mfma_f32_16x16x32_bf16 v[12:15], v[168:171], v[240:243], v[12:15]
	v_mfma_f32_16x16x32_bf16 v[16:19], v[172:175], v[184:187], v[16:19]
	ds_read_b128 v[168:171], v154 offset:8192
	v_mfma_f32_16x16x32_bf16 v[20:23], v[172:175], v[196:199], v[20:23]
	ds_read_b128 v[212:215], v192 offset:34816
	v_mfma_f32_16x16x32_bf16 v[24:27], v[172:175], v[200:203], v[24:27]
	v_mfma_f32_16x16x32_bf16 v[28:31], v[172:175], v[240:243], v[28:31]
	v_mfma_f32_16x16x32_bf16 v[32:35], v[176:179], v[184:187], v[32:35]
	ds_read_b128 v[172:175], v154 offset:10240
	v_mfma_f32_16x16x32_bf16 v[36:39], v[176:179], v[196:199], v[36:39]
	ds_read_b128 v[216:219], v192 offset:36864
	v_mfma_f32_16x16x32_bf16 v[40:43], v[176:179], v[200:203], v[40:43]
	s_add_u32 m0, s68, 0x14000
	v_mfma_f32_16x16x32_bf16 v[44:47], v[176:179], v[240:243], v[44:47]
	global_load_lds_dwordx4 v146, s[62:63]
	s_waitcnt lgkmcnt(5)
	v_mfma_f32_16x16x32_bf16 v[48:51], v[180:183], v[184:187], v[48:51]
	ds_read_b128 v[176:179], v154 offset:12288
	v_mfma_f32_16x16x32_bf16 v[52:55], v[180:183], v[196:199], v[52:55]
	ds_read_b128 v[248:251], v192 offset:38912
	v_mfma_f32_16x16x32_bf16 v[56:59], v[180:183], v[200:203], v[56:59]
	s_add_u32 m0, s68, 0x1c000
	v_mfma_f32_16x16x32_bf16 v[60:63], v[180:183], v[240:243], v[60:63]
	global_load_lds_dwordx4 v130, s[64:65]
	s_waitcnt lgkmcnt(5)
	v_mfma_f32_16x16x32_bf16 v[64:67], v[168:171], v[184:187], v[64:67]
	ds_read_b128 v[180:183], v154 offset:14336
	v_mfma_f32_16x16x32_bf16 v[68:71], v[168:171], v[196:199], v[68:71]
	v_mfma_f32_16x16x32_bf16 v[72:75], v[168:171], v[200:203], v[72:75]
	s_add_u32 m0, s68, 0x16000
	v_mfma_f32_16x16x32_bf16 v[76:79], v[168:171], v[240:243], v[76:79]
	global_load_lds_dwordx4 v144, s[62:63]
	s_waitcnt lgkmcnt(4)
	v_mfma_f32_16x16x32_bf16 v[80:83], v[172:175], v[184:187], v[80:83]
	ds_read_b128 v[168:171], v155
	v_mfma_f32_16x16x32_bf16 v[84:87], v[172:175], v[196:199], v[84:87]
	v_mfma_f32_16x16x32_bf16 v[88:91], v[172:175], v[200:203], v[88:91]
	s_add_u32 m0, s68, 0x1e000
	v_mfma_f32_16x16x32_bf16 v[92:95], v[172:175], v[240:243], v[92:95]
	global_load_lds_dwordx4 v152, s[64:65]
	s_add_u32 s62, s62, 0x80
	s_addc_u32 s63, s63, 0
	s_add_u32 s64, s64, 0x80
	s_addc_u32 s65, s65, 0
	s_waitcnt lgkmcnt(3)
	v_mfma_f32_16x16x32_bf16 v[96:99], v[176:179], v[184:187], v[96:99]
	ds_read_b128 v[172:175], v155 offset:2048
	v_mfma_f32_16x16x32_bf16 v[100:103], v[176:179], v[196:199], v[100:103]
	v_mfma_f32_16x16x32_bf16 v[104:107], v[176:179], v[200:203], v[104:107]
	v_mfma_f32_16x16x32_bf16 v[108:111], v[176:179], v[240:243], v[108:111]
	s_waitcnt lgkmcnt(2)
	v_mfma_f32_16x16x32_bf16 v[112:115], v[180:183], v[184:187], v[112:115]
	ds_read_b128 v[176:179], v155 offset:4096
	v_mfma_f32_16x16x32_bf16 v[116:119], v[180:183], v[196:199], v[116:119]
	v_mfma_f32_16x16x32_bf16 v[120:123], v[180:183], v[200:203], v[120:123]
	v_mfma_f32_16x16x32_bf16 v[124:127], v[180:183], v[240:243], v[124:127]
	s_waitcnt lgkmcnt(2)
	v_mfma_f32_16x16x32_bf16 v[0:3], v[168:171], v[244:247], v[0:3]
	ds_read_b128 v[180:183], v155 offset:6144
	v_mfma_f32_16x16x32_bf16 v[4:7], v[168:171], v[212:215], v[4:7]
	v_mfma_f32_16x16x32_bf16 v[8:11], v[168:171], v[216:219], v[8:11]
	v_mfma_f32_16x16x32_bf16 v[12:15], v[168:171], v[248:251], v[12:15]
	s_waitcnt lgkmcnt(2)
	v_mfma_f32_16x16x32_bf16 v[16:19], v[172:175], v[244:247], v[16:19]
	ds_read_b128 v[168:171], v155 offset:8192
	v_mfma_f32_16x16x32_bf16 v[20:23], v[172:175], v[212:215], v[20:23]
	v_mfma_f32_16x16x32_bf16 v[24:27], v[172:175], v[216:219], v[24:27]
	v_mfma_f32_16x16x32_bf16 v[28:31], v[172:175], v[248:251], v[28:31]
	s_waitcnt lgkmcnt(2)
	v_mfma_f32_16x16x32_bf16 v[32:35], v[176:179], v[244:247], v[32:35]
	ds_read_b128 v[172:175], v155 offset:10240
	v_mfma_f32_16x16x32_bf16 v[36:39], v[176:179], v[212:215], v[36:39]
	v_mfma_f32_16x16x32_bf16 v[40:43], v[176:179], v[216:219], v[40:43]
	v_mfma_f32_16x16x32_bf16 v[44:47], v[176:179], v[248:251], v[44:47]
	s_waitcnt lgkmcnt(2)
	v_mfma_f32_16x16x32_bf16 v[48:51], v[180:183], v[244:247], v[48:51]
	ds_read_b128 v[176:179], v155 offset:12288
	v_mfma_f32_16x16x32_bf16 v[52:55], v[180:183], v[212:215], v[52:55]
	v_mfma_f32_16x16x32_bf16 v[56:59], v[180:183], v[216:219], v[56:59]
	v_mfma_f32_16x16x32_bf16 v[60:63], v[180:183], v[248:251], v[60:63]
	s_waitcnt lgkmcnt(2)
	v_mfma_f32_16x16x32_bf16 v[64:67], v[168:171], v[244:247], v[64:67]
	ds_read_b128 v[180:183], v155 offset:14336
	v_mfma_f32_16x16x32_bf16 v[68:71], v[168:171], v[212:215], v[68:71]
	v_mfma_f32_16x16x32_bf16 v[72:75], v[168:171], v[216:219], v[72:75]
	v_mfma_f32_16x16x32_bf16 v[76:79], v[168:171], v[248:251], v[76:79]
	s_waitcnt lgkmcnt(2)
	v_mfma_f32_16x16x32_bf16 v[80:83], v[172:175], v[244:247], v[80:83]
	v_mfma_f32_16x16x32_bf16 v[84:87], v[172:175], v[212:215], v[84:87]
	v_mfma_f32_16x16x32_bf16 v[88:91], v[172:175], v[216:219], v[88:91]
	v_mfma_f32_16x16x32_bf16 v[92:95], v[172:175], v[248:251], v[92:95]
	s_waitcnt lgkmcnt(0)
	s_waitcnt vmcnt(0)
	s_barrier
	v_xor_b32_e32 v154, 0x10000, v154
	v_xor_b32_e32 v155, 0x10000, v155
	v_xor_b32_e32 v167, 0x10000, v167
	v_xor_b32_e32 v192, 0x10000, v192
	v_mfma_f32_16x16x32_bf16 v[96:99], v[176:179], v[244:247], v[96:99]
	ds_read_b128 v[168:171], v154
	ds_read_b128 v[172:175], v154 offset:2048
	s_mov_b32 m0, s68
	v_mfma_f32_16x16x32_bf16 v[100:103], v[176:179], v[212:215], v[100:103]
	global_load_lds_dwordx4 v150, s[62:63]
	v_mfma_f32_16x16x32_bf16 v[104:107], v[176:179], v[216:219], v[104:107]
	ds_read_b128 v[184:187], v167 offset:32768
	ds_read_b128 v[196:199], v167 offset:34816
	s_add_u32 m0, s68, 0x8000
	v_mfma_f32_16x16x32_bf16 v[108:111], v[176:179], v[248:251], v[108:111]
	global_load_lds_dwordx4 v134, s[64:65]
	v_mfma_f32_16x16x32_bf16 v[112:115], v[180:183], v[244:247], v[112:115]
	ds_read_b128 v[176:179], v154 offset:4096
	s_add_u32 m0, s68, 0x2000
	v_mfma_f32_16x16x32_bf16 v[116:119], v[180:183], v[212:215], v[116:119]
	global_load_lds_dwordx4 v148, s[62:63]
	ds_read_b128 v[200:203], v167 offset:36864
	ds_read_b128 v[240:243], v167 offset:38912
	v_mfma_f32_16x16x32_bf16 v[120:123], v[180:183], v[216:219], v[120:123]
	s_add_u32 m0, s68, 0xa000
	v_mfma_f32_16x16x32_bf16 v[124:127], v[180:183], v[248:251], v[124:127]
	global_load_lds_dwordx4 v132, s[64:65]
	s_waitcnt lgkmcnt(4)
	v_mfma_f32_16x16x32_bf16 v[0:3], v[168:171], v[184:187], v[0:3]
	ds_read_b128 v[180:183], v154 offset:6144
	s_waitcnt lgkmcnt(4)
	v_mfma_f32_16x16x32_bf16 v[4:7], v[168:171], v[196:199], v[4:7]
	ds_read_b128 v[244:247], v192 offset:32768
	s_waitcnt lgkmcnt(3)
	v_mfma_f32_16x16x32_bf16 v[8:11], v[168:171], v[200:203], v[8:11]
	s_waitcnt lgkmcnt(2)
	v_mfma_f32_16x16x32_bf16 v[12:15], v[168:171], v[240:243], v[12:15]
	v_mfma_f32_16x16x32_bf16 v[16:19], v[172:175], v[184:187], v[16:19]
	ds_read_b128 v[168:171], v154 offset:8192
	v_mfma_f32_16x16x32_bf16 v[20:23], v[172:175], v[196:199], v[20:23]
	ds_read_b128 v[212:215], v192 offset:34816
	v_mfma_f32_16x16x32_bf16 v[24:27], v[172:175], v[200:203], v[24:27]
	v_mfma_f32_16x16x32_bf16 v[28:31], v[172:175], v[240:243], v[28:31]
	v_mfma_f32_16x16x32_bf16 v[32:35], v[176:179], v[184:187], v[32:35]
	ds_read_b128 v[172:175], v154 offset:10240
	v_mfma_f32_16x16x32_bf16 v[36:39], v[176:179], v[196:199], v[36:39]
	ds_read_b128 v[216:219], v192 offset:36864
	v_mfma_f32_16x16x32_bf16 v[40:43], v[176:179], v[200:203], v[40:43]
	s_add_u32 m0, s68, 0x4000
	v_mfma_f32_16x16x32_bf16 v[44:47], v[176:179], v[240:243], v[44:47]
	global_load_lds_dwordx4 v146, s[62:63]
	s_waitcnt lgkmcnt(5)
	v_mfma_f32_16x16x32_bf16 v[48:51], v[180:183], v[184:187], v[48:51]
	ds_read_b128 v[176:179], v154 offset:12288
	v_mfma_f32_16x16x32_bf16 v[52:55], v[180:183], v[196:199], v[52:55]
	ds_read_b128 v[248:251], v192 offset:38912
	v_mfma_f32_16x16x32_bf16 v[56:59], v[180:183], v[200:203], v[56:59]
	s_add_u32 m0, s68, 0xc000
	v_mfma_f32_16x16x32_bf16 v[60:63], v[180:183], v[240:243], v[60:63]
	global_load_lds_dwordx4 v130, s[64:65]
	s_waitcnt lgkmcnt(5)
	v_mfma_f32_16x16x32_bf16 v[64:67], v[168:171], v[184:187], v[64:67]
	ds_read_b128 v[180:183], v154 offset:14336
	v_mfma_f32_16x16x32_bf16 v[68:71], v[168:171], v[196:199], v[68:71]
	v_mfma_f32_16x16x32_bf16 v[72:75], v[168:171], v[200:203], v[72:75]
	s_add_u32 m0, s68, 0x6000
	v_mfma_f32_16x16x32_bf16 v[76:79], v[168:171], v[240:243], v[76:79]
	global_load_lds_dwordx4 v144, s[62:63]
	s_waitcnt lgkmcnt(4)
	v_mfma_f32_16x16x32_bf16 v[80:83], v[172:175], v[184:187], v[80:83]
	ds_read_b128 v[168:171], v155
	v_mfma_f32_16x16x32_bf16 v[84:87], v[172:175], v[196:199], v[84:87]
	v_mfma_f32_16x16x32_bf16 v[88:91], v[172:175], v[200:203], v[88:91]
	s_add_u32 m0, s68, 0xe000
	v_mfma_f32_16x16x32_bf16 v[92:95], v[172:175], v[240:243], v[92:95]
	global_load_lds_dwordx4 v152, s[64:65]
	s_add_u32 s62, s62, 0x80
	s_addc_u32 s63, s63, 0
	s_add_u32 s64, s64, 0x80
	s_addc_u32 s65, s65, 0
	s_waitcnt lgkmcnt(3)
	v_mfma_f32_16x16x32_bf16 v[96:99], v[176:179], v[184:187], v[96:99]
	ds_read_b128 v[172:175], v155 offset:2048
	v_mfma_f32_16x16x32_bf16 v[100:103], v[176:179], v[196:199], v[100:103]
	v_mfma_f32_16x16x32_bf16 v[104:107], v[176:179], v[200:203], v[104:107]
	v_mfma_f32_16x16x32_bf16 v[108:111], v[176:179], v[240:243], v[108:111]
	s_waitcnt lgkmcnt(2)
	v_mfma_f32_16x16x32_bf16 v[112:115], v[180:183], v[184:187], v[112:115]
	ds_read_b128 v[176:179], v155 offset:4096
	v_mfma_f32_16x16x32_bf16 v[116:119], v[180:183], v[196:199], v[116:119]
	v_mfma_f32_16x16x32_bf16 v[120:123], v[180:183], v[200:203], v[120:123]
	v_mfma_f32_16x16x32_bf16 v[124:127], v[180:183], v[240:243], v[124:127]
	s_waitcnt lgkmcnt(2)
	v_mfma_f32_16x16x32_bf16 v[0:3], v[168:171], v[244:247], v[0:3]
	ds_read_b128 v[180:183], v155 offset:6144
	v_mfma_f32_16x16x32_bf16 v[4:7], v[168:171], v[212:215], v[4:7]
	v_mfma_f32_16x16x32_bf16 v[8:11], v[168:171], v[216:219], v[8:11]
	v_mfma_f32_16x16x32_bf16 v[12:15], v[168:171], v[248:251], v[12:15]
	s_waitcnt lgkmcnt(2)
	v_mfma_f32_16x16x32_bf16 v[16:19], v[172:175], v[244:247], v[16:19]
	ds_read_b128 v[168:171], v155 offset:8192
	v_mfma_f32_16x16x32_bf16 v[20:23], v[172:175], v[212:215], v[20:23]
	v_mfma_f32_16x16x32_bf16 v[24:27], v[172:175], v[216:219], v[24:27]
	v_mfma_f32_16x16x32_bf16 v[28:31], v[172:175], v[248:251], v[28:31]
	s_waitcnt lgkmcnt(2)
	v_mfma_f32_16x16x32_bf16 v[32:35], v[176:179], v[244:247], v[32:35]
	ds_read_b128 v[172:175], v155 offset:10240
	v_mfma_f32_16x16x32_bf16 v[36:39], v[176:179], v[212:215], v[36:39]
	v_mfma_f32_16x16x32_bf16 v[40:43], v[176:179], v[216:219], v[40:43]
	v_mfma_f32_16x16x32_bf16 v[44:47], v[176:179], v[248:251], v[44:47]
	s_waitcnt lgkmcnt(2)
	v_mfma_f32_16x16x32_bf16 v[48:51], v[180:183], v[244:247], v[48:51]
	ds_read_b128 v[176:179], v155 offset:12288
	v_mfma_f32_16x16x32_bf16 v[52:55], v[180:183], v[212:215], v[52:55]
	v_mfma_f32_16x16x32_bf16 v[56:59], v[180:183], v[216:219], v[56:59]
	v_mfma_f32_16x16x32_bf16 v[60:63], v[180:183], v[248:251], v[60:63]
	s_waitcnt lgkmcnt(2)
	v_mfma_f32_16x16x32_bf16 v[64:67], v[168:171], v[244:247], v[64:67]
	ds_read_b128 v[180:183], v155 offset:14336
	v_mfma_f32_16x16x32_bf16 v[68:71], v[168:171], v[212:215], v[68:71]
	v_mfma_f32_16x16x32_bf16 v[72:75], v[168:171], v[216:219], v[72:75]
	v_mfma_f32_16x16x32_bf16 v[76:79], v[168:171], v[248:251], v[76:79]
	s_waitcnt lgkmcnt(2)
	v_mfma_f32_16x16x32_bf16 v[80:83], v[172:175], v[244:247], v[80:83]
	v_mfma_f32_16x16x32_bf16 v[84:87], v[172:175], v[212:215], v[84:87]
	v_mfma_f32_16x16x32_bf16 v[88:91], v[172:175], v[216:219], v[88:91]
	v_mfma_f32_16x16x32_bf16 v[92:95], v[172:175], v[248:251], v[92:95]
	s_waitcnt lgkmcnt(0)
	s_waitcnt vmcnt(0)
	s_barrier
	v_xor_b32_e32 v154, 0x10000, v154
	v_xor_b32_e32 v155, 0x10000, v155
	v_xor_b32_e32 v167, 0x10000, v167
	v_xor_b32_e32 v192, 0x10000, v192
	v_mfma_f32_16x16x32_bf16 v[96:99], v[176:179], v[244:247], v[96:99]
	ds_read_b128 v[168:171], v154
	ds_read_b128 v[172:175], v154 offset:2048
	s_add_u32 m0, s68, 0x10000
	v_mfma_f32_16x16x32_bf16 v[100:103], v[176:179], v[212:215], v[100:103]
	global_load_lds_dwordx4 v150, s[62:63]
	v_mfma_f32_16x16x32_bf16 v[104:107], v[176:179], v[216:219], v[104:107]
	ds_read_b128 v[184:187], v167 offset:32768
	ds_read_b128 v[196:199], v167 offset:34816
	s_add_u32 m0, s68, 0x18000
	v_mfma_f32_16x16x32_bf16 v[108:111], v[176:179], v[248:251], v[108:111]
	global_load_lds_dwordx4 v134, s[64:65]
	v_mfma_f32_16x16x32_bf16 v[112:115], v[180:183], v[244:247], v[112:115]
	ds_read_b128 v[176:179], v154 offset:4096
	s_add_u32 m0, s68, 0x12000
	v_mfma_f32_16x16x32_bf16 v[116:119], v[180:183], v[212:215], v[116:119]
	global_load_lds_dwordx4 v148, s[62:63]
	ds_read_b128 v[200:203], v167 offset:36864
	ds_read_b128 v[240:243], v167 offset:38912
	v_mfma_f32_16x16x32_bf16 v[120:123], v[180:183], v[216:219], v[120:123]
	s_add_u32 m0, s68, 0x1a000
	v_mfma_f32_16x16x32_bf16 v[124:127], v[180:183], v[248:251], v[124:127]
	global_load_lds_dwordx4 v132, s[64:65]
	s_waitcnt lgkmcnt(4)
	v_mfma_f32_16x16x32_bf16 v[0:3], v[168:171], v[184:187], v[0:3]
	ds_read_b128 v[180:183], v154 offset:6144
	s_waitcnt lgkmcnt(4)
	v_mfma_f32_16x16x32_bf16 v[4:7], v[168:171], v[196:199], v[4:7]
	ds_read_b128 v[244:247], v192 offset:32768
	s_waitcnt lgkmcnt(3)
	v_mfma_f32_16x16x32_bf16 v[8:11], v[168:171], v[200:203], v[8:11]
	s_waitcnt lgkmcnt(2)
	v_mfma_f32_16x16x32_bf16 v[12:15], v[168:171], v[240:243], v[12:15]
	v_mfma_f32_16x16x32_bf16 v[16:19], v[172:175], v[184:187], v[16:19]
	ds_read_b128 v[168:171], v154 offset:8192
	v_mfma_f32_16x16x32_bf16 v[20:23], v[172:175], v[196:199], v[20:23]
	ds_read_b128 v[212:215], v192 offset:34816
	v_mfma_f32_16x16x32_bf16 v[24:27], v[172:175], v[200:203], v[24:27]
	v_mfma_f32_16x16x32_bf16 v[28:31], v[172:175], v[240:243], v[28:31]
	v_mfma_f32_16x16x32_bf16 v[32:35], v[176:179], v[184:187], v[32:35]
	ds_read_b128 v[172:175], v154 offset:10240
	v_mfma_f32_16x16x32_bf16 v[36:39], v[176:179], v[196:199], v[36:39]
	ds_read_b128 v[216:219], v192 offset:36864
	v_mfma_f32_16x16x32_bf16 v[40:43], v[176:179], v[200:203], v[40:43]
	s_add_u32 m0, s68, 0x14000
	v_mfma_f32_16x16x32_bf16 v[44:47], v[176:179], v[240:243], v[44:47]
	global_load_lds_dwordx4 v146, s[62:63]
	s_waitcnt lgkmcnt(5)
	v_mfma_f32_16x16x32_bf16 v[48:51], v[180:183], v[184:187], v[48:51]
	ds_read_b128 v[176:179], v154 offset:12288
	v_mfma_f32_16x16x32_bf16 v[52:55], v[180:183], v[196:199], v[52:55]
	ds_read_b128 v[248:251], v192 offset:38912
	v_mfma_f32_16x16x32_bf16 v[56:59], v[180:183], v[200:203], v[56:59]
	s_add_u32 m0, s68, 0x1c000
	v_mfma_f32_16x16x32_bf16 v[60:63], v[180:183], v[240:243], v[60:63]
	global_load_lds_dwordx4 v130, s[64:65]
	s_waitcnt lgkmcnt(5)
	v_mfma_f32_16x16x32_bf16 v[64:67], v[168:171], v[184:187], v[64:67]
	ds_read_b128 v[180:183], v154 offset:14336
	v_mfma_f32_16x16x32_bf16 v[68:71], v[168:171], v[196:199], v[68:71]
	v_mfma_f32_16x16x32_bf16 v[72:75], v[168:171], v[200:203], v[72:75]
	s_add_u32 m0, s68, 0x16000
	v_mfma_f32_16x16x32_bf16 v[76:79], v[168:171], v[240:243], v[76:79]
	global_load_lds_dwordx4 v144, s[62:63]
	s_waitcnt lgkmcnt(4)
	v_mfma_f32_16x16x32_bf16 v[80:83], v[172:175], v[184:187], v[80:83]
	ds_read_b128 v[168:171], v155
	v_mfma_f32_16x16x32_bf16 v[84:87], v[172:175], v[196:199], v[84:87]
	v_mfma_f32_16x16x32_bf16 v[88:91], v[172:175], v[200:203], v[88:91]
	s_add_u32 m0, s68, 0x1e000
	v_mfma_f32_16x16x32_bf16 v[92:95], v[172:175], v[240:243], v[92:95]
	global_load_lds_dwordx4 v152, s[64:65]
	s_add_u32 s62, s62, 0x80
	s_addc_u32 s63, s63, 0
	s_add_u32 s64, s64, 0x80
	s_addc_u32 s65, s65, 0
	s_waitcnt lgkmcnt(3)
	v_mfma_f32_16x16x32_bf16 v[96:99], v[176:179], v[184:187], v[96:99]
	ds_read_b128 v[172:175], v155 offset:2048
	v_mfma_f32_16x16x32_bf16 v[100:103], v[176:179], v[196:199], v[100:103]
	v_mfma_f32_16x16x32_bf16 v[104:107], v[176:179], v[200:203], v[104:107]
	v_mfma_f32_16x16x32_bf16 v[108:111], v[176:179], v[240:243], v[108:111]
	s_waitcnt lgkmcnt(2)
	v_mfma_f32_16x16x32_bf16 v[112:115], v[180:183], v[184:187], v[112:115]
	ds_read_b128 v[176:179], v155 offset:4096
	v_mfma_f32_16x16x32_bf16 v[116:119], v[180:183], v[196:199], v[116:119]
	v_mfma_f32_16x16x32_bf16 v[120:123], v[180:183], v[200:203], v[120:123]
	v_mfma_f32_16x16x32_bf16 v[124:127], v[180:183], v[240:243], v[124:127]
	s_waitcnt lgkmcnt(2)
	v_mfma_f32_16x16x32_bf16 v[0:3], v[168:171], v[244:247], v[0:3]
	ds_read_b128 v[180:183], v155 offset:6144
	v_mfma_f32_16x16x32_bf16 v[4:7], v[168:171], v[212:215], v[4:7]
	v_mfma_f32_16x16x32_bf16 v[8:11], v[168:171], v[216:219], v[8:11]
	v_mfma_f32_16x16x32_bf16 v[12:15], v[168:171], v[248:251], v[12:15]
	s_waitcnt lgkmcnt(2)
	v_mfma_f32_16x16x32_bf16 v[16:19], v[172:175], v[244:247], v[16:19]
	ds_read_b128 v[168:171], v155 offset:8192
	v_mfma_f32_16x16x32_bf16 v[20:23], v[172:175], v[212:215], v[20:23]
	v_mfma_f32_16x16x32_bf16 v[24:27], v[172:175], v[216:219], v[24:27]
	v_mfma_f32_16x16x32_bf16 v[28:31], v[172:175], v[248:251], v[28:31]
	s_waitcnt lgkmcnt(2)
	v_mfma_f32_16x16x32_bf16 v[32:35], v[176:179], v[244:247], v[32:35]
	ds_read_b128 v[172:175], v155 offset:10240
	v_mfma_f32_16x16x32_bf16 v[36:39], v[176:179], v[212:215], v[36:39]
	v_mfma_f32_16x16x32_bf16 v[40:43], v[176:179], v[216:219], v[40:43]
	v_mfma_f32_16x16x32_bf16 v[44:47], v[176:179], v[248:251], v[44:47]
	s_waitcnt lgkmcnt(2)
	v_mfma_f32_16x16x32_bf16 v[48:51], v[180:183], v[244:247], v[48:51]
	ds_read_b128 v[176:179], v155 offset:12288
	v_mfma_f32_16x16x32_bf16 v[52:55], v[180:183], v[212:215], v[52:55]
	v_mfma_f32_16x16x32_bf16 v[56:59], v[180:183], v[216:219], v[56:59]
	v_mfma_f32_16x16x32_bf16 v[60:63], v[180:183], v[248:251], v[60:63]
	s_waitcnt lgkmcnt(2)
	v_mfma_f32_16x16x32_bf16 v[64:67], v[168:171], v[244:247], v[64:67]
	ds_read_b128 v[180:183], v155 offset:14336
	v_mfma_f32_16x16x32_bf16 v[68:71], v[168:171], v[212:215], v[68:71]
	v_mfma_f32_16x16x32_bf16 v[72:75], v[168:171], v[216:219], v[72:75]
	v_mfma_f32_16x16x32_bf16 v[76:79], v[168:171], v[248:251], v[76:79]
	s_waitcnt lgkmcnt(2)
	v_mfma_f32_16x16x32_bf16 v[80:83], v[172:175], v[244:247], v[80:83]
	v_mfma_f32_16x16x32_bf16 v[84:87], v[172:175], v[212:215], v[84:87]
	v_mfma_f32_16x16x32_bf16 v[88:91], v[172:175], v[216:219], v[88:91]
	v_mfma_f32_16x16x32_bf16 v[92:95], v[172:175], v[248:251], v[92:95]
	s_waitcnt lgkmcnt(0)
	s_waitcnt vmcnt(0)
	s_barrier
	v_xor_b32_e32 v154, 0x10000, v154
	v_xor_b32_e32 v155, 0x10000, v155
	v_xor_b32_e32 v167, 0x10000, v167
	v_xor_b32_e32 v192, 0x10000, v192
	v_mfma_f32_16x16x32_bf16 v[96:99], v[176:179], v[244:247], v[96:99]
	ds_read_b128 v[168:171], v154
	ds_read_b128 v[172:175], v154 offset:2048
	s_mov_b32 m0, s68
	v_mfma_f32_16x16x32_bf16 v[100:103], v[176:179], v[212:215], v[100:103]
	global_load_lds_dwordx4 v150, s[62:63]
	v_mfma_f32_16x16x32_bf16 v[104:107], v[176:179], v[216:219], v[104:107]
	ds_read_b128 v[184:187], v167 offset:32768
	ds_read_b128 v[196:199], v167 offset:34816
	s_add_u32 m0, s68, 0x8000
	v_mfma_f32_16x16x32_bf16 v[108:111], v[176:179], v[248:251], v[108:111]
	global_load_lds_dwordx4 v134, s[64:65]
	v_mfma_f32_16x16x32_bf16 v[112:115], v[180:183], v[244:247], v[112:115]
	ds_read_b128 v[176:179], v154 offset:4096
	s_add_u32 m0, s68, 0x2000
	v_mfma_f32_16x16x32_bf16 v[116:119], v[180:183], v[212:215], v[116:119]
	global_load_lds_dwordx4 v148, s[62:63]
	ds_read_b128 v[200:203], v167 offset:36864
	ds_read_b128 v[240:243], v167 offset:38912
	v_mfma_f32_16x16x32_bf16 v[120:123], v[180:183], v[216:219], v[120:123]
	s_add_u32 m0, s68, 0xa000
	v_mfma_f32_16x16x32_bf16 v[124:127], v[180:183], v[248:251], v[124:127]
	global_load_lds_dwordx4 v132, s[64:65]
	s_waitcnt lgkmcnt(4)
	v_mfma_f32_16x16x32_bf16 v[0:3], v[168:171], v[184:187], v[0:3]
	ds_read_b128 v[180:183], v154 offset:6144
	s_waitcnt lgkmcnt(4)
	v_mfma_f32_16x16x32_bf16 v[4:7], v[168:171], v[196:199], v[4:7]
	ds_read_b128 v[244:247], v192 offset:32768
	s_waitcnt lgkmcnt(3)
	v_mfma_f32_16x16x32_bf16 v[8:11], v[168:171], v[200:203], v[8:11]
	s_waitcnt lgkmcnt(2)
	v_mfma_f32_16x16x32_bf16 v[12:15], v[168:171], v[240:243], v[12:15]
	v_mfma_f32_16x16x32_bf16 v[16:19], v[172:175], v[184:187], v[16:19]
	ds_read_b128 v[168:171], v154 offset:8192
	v_mfma_f32_16x16x32_bf16 v[20:23], v[172:175], v[196:199], v[20:23]
	ds_read_b128 v[212:215], v192 offset:34816
	v_mfma_f32_16x16x32_bf16 v[24:27], v[172:175], v[200:203], v[24:27]
	v_mfma_f32_16x16x32_bf16 v[28:31], v[172:175], v[240:243], v[28:31]
	v_mfma_f32_16x16x32_bf16 v[32:35], v[176:179], v[184:187], v[32:35]
	ds_read_b128 v[172:175], v154 offset:10240
	v_mfma_f32_16x16x32_bf16 v[36:39], v[176:179], v[196:199], v[36:39]
	ds_read_b128 v[216:219], v192 offset:36864
	v_mfma_f32_16x16x32_bf16 v[40:43], v[176:179], v[200:203], v[40:43]
	s_add_u32 m0, s68, 0x4000
	v_mfma_f32_16x16x32_bf16 v[44:47], v[176:179], v[240:243], v[44:47]
	global_load_lds_dwordx4 v146, s[62:63]
	s_waitcnt lgkmcnt(5)
	v_mfma_f32_16x16x32_bf16 v[48:51], v[180:183], v[184:187], v[48:51]
	ds_read_b128 v[176:179], v154 offset:12288
	v_mfma_f32_16x16x32_bf16 v[52:55], v[180:183], v[196:199], v[52:55]
	ds_read_b128 v[248:251], v192 offset:38912
	v_mfma_f32_16x16x32_bf16 v[56:59], v[180:183], v[200:203], v[56:59]
	s_add_u32 m0, s68, 0xc000
	v_mfma_f32_16x16x32_bf16 v[60:63], v[180:183], v[240:243], v[60:63]
	global_load_lds_dwordx4 v130, s[64:65]
	s_waitcnt lgkmcnt(5)
	v_mfma_f32_16x16x32_bf16 v[64:67], v[168:171], v[184:187], v[64:67]
	ds_read_b128 v[180:183], v154 offset:14336
	v_mfma_f32_16x16x32_bf16 v[68:71], v[168:171], v[196:199], v[68:71]
	v_mfma_f32_16x16x32_bf16 v[72:75], v[168:171], v[200:203], v[72:75]
	s_add_u32 m0, s68, 0x6000
	v_mfma_f32_16x16x32_bf16 v[76:79], v[168:171], v[240:243], v[76:79]
	global_load_lds_dwordx4 v144, s[62:63]
	s_waitcnt lgkmcnt(4)
	v_mfma_f32_16x16x32_bf16 v[80:83], v[172:175], v[184:187], v[80:83]
	ds_read_b128 v[168:171], v155
	v_mfma_f32_16x16x32_bf16 v[84:87], v[172:175], v[196:199], v[84:87]
	v_mfma_f32_16x16x32_bf16 v[88:91], v[172:175], v[200:203], v[88:91]
	s_add_u32 m0, s68, 0xe000
	v_mfma_f32_16x16x32_bf16 v[92:95], v[172:175], v[240:243], v[92:95]
	global_load_lds_dwordx4 v152, s[64:65]
	s_add_u32 s62, s62, 0x80
	s_addc_u32 s63, s63, 0
	s_add_u32 s64, s64, 0x80
	s_addc_u32 s65, s65, 0
	s_waitcnt lgkmcnt(3)
	v_mfma_f32_16x16x32_bf16 v[96:99], v[176:179], v[184:187], v[96:99]
	ds_read_b128 v[172:175], v155 offset:2048
	v_mfma_f32_16x16x32_bf16 v[100:103], v[176:179], v[196:199], v[100:103]
	v_mfma_f32_16x16x32_bf16 v[104:107], v[176:179], v[200:203], v[104:107]
	v_mfma_f32_16x16x32_bf16 v[108:111], v[176:179], v[240:243], v[108:111]
	s_waitcnt lgkmcnt(2)
	v_mfma_f32_16x16x32_bf16 v[112:115], v[180:183], v[184:187], v[112:115]
	ds_read_b128 v[176:179], v155 offset:4096
	v_mfma_f32_16x16x32_bf16 v[116:119], v[180:183], v[196:199], v[116:119]
	v_mfma_f32_16x16x32_bf16 v[120:123], v[180:183], v[200:203], v[120:123]
	v_mfma_f32_16x16x32_bf16 v[124:127], v[180:183], v[240:243], v[124:127]
	s_waitcnt lgkmcnt(2)
	v_mfma_f32_16x16x32_bf16 v[0:3], v[168:171], v[244:247], v[0:3]
	ds_read_b128 v[180:183], v155 offset:6144
	v_mfma_f32_16x16x32_bf16 v[4:7], v[168:171], v[212:215], v[4:7]
	v_mfma_f32_16x16x32_bf16 v[8:11], v[168:171], v[216:219], v[8:11]
	v_mfma_f32_16x16x32_bf16 v[12:15], v[168:171], v[248:251], v[12:15]
	s_waitcnt lgkmcnt(2)
	v_mfma_f32_16x16x32_bf16 v[16:19], v[172:175], v[244:247], v[16:19]
	ds_read_b128 v[168:171], v155 offset:8192
	v_mfma_f32_16x16x32_bf16 v[20:23], v[172:175], v[212:215], v[20:23]
	v_mfma_f32_16x16x32_bf16 v[24:27], v[172:175], v[216:219], v[24:27]
	v_mfma_f32_16x16x32_bf16 v[28:31], v[172:175], v[248:251], v[28:31]
	s_waitcnt lgkmcnt(2)
	v_mfma_f32_16x16x32_bf16 v[32:35], v[176:179], v[244:247], v[32:35]
	ds_read_b128 v[172:175], v155 offset:10240
	v_mfma_f32_16x16x32_bf16 v[36:39], v[176:179], v[212:215], v[36:39]
	v_mfma_f32_16x16x32_bf16 v[40:43], v[176:179], v[216:219], v[40:43]
	v_mfma_f32_16x16x32_bf16 v[44:47], v[176:179], v[248:251], v[44:47]
	s_waitcnt lgkmcnt(2)
	v_mfma_f32_16x16x32_bf16 v[48:51], v[180:183], v[244:247], v[48:51]
	ds_read_b128 v[176:179], v155 offset:12288
	v_mfma_f32_16x16x32_bf16 v[52:55], v[180:183], v[212:215], v[52:55]
	v_mfma_f32_16x16x32_bf16 v[56:59], v[180:183], v[216:219], v[56:59]
	v_mfma_f32_16x16x32_bf16 v[60:63], v[180:183], v[248:251], v[60:63]
	s_waitcnt lgkmcnt(2)
	v_mfma_f32_16x16x32_bf16 v[64:67], v[168:171], v[244:247], v[64:67]
	ds_read_b128 v[180:183], v155 offset:14336
	v_mfma_f32_16x16x32_bf16 v[68:71], v[168:171], v[212:215], v[68:71]
	v_mfma_f32_16x16x32_bf16 v[72:75], v[168:171], v[216:219], v[72:75]
	v_mfma_f32_16x16x32_bf16 v[76:79], v[168:171], v[248:251], v[76:79]
	s_waitcnt lgkmcnt(2)
	v_mfma_f32_16x16x32_bf16 v[80:83], v[172:175], v[244:247], v[80:83]
	v_mfma_f32_16x16x32_bf16 v[84:87], v[172:175], v[212:215], v[84:87]
	v_mfma_f32_16x16x32_bf16 v[88:91], v[172:175], v[216:219], v[88:91]
	v_mfma_f32_16x16x32_bf16 v[92:95], v[172:175], v[248:251], v[92:95]
	s_waitcnt lgkmcnt(0)
	s_waitcnt vmcnt(0)
	s_barrier
	v_xor_b32_e32 v154, 0x10000, v154
	v_xor_b32_e32 v155, 0x10000, v155
	v_xor_b32_e32 v167, 0x10000, v167
	v_xor_b32_e32 v192, 0x10000, v192
	v_mfma_f32_16x16x32_bf16 v[96:99], v[176:179], v[244:247], v[96:99]
	ds_read_b128 v[168:171], v154
	ds_read_b128 v[172:175], v154 offset:2048
	s_add_u32 m0, s68, 0x10000
	v_mfma_f32_16x16x32_bf16 v[100:103], v[176:179], v[212:215], v[100:103]
	global_load_lds_dwordx4 v150, s[62:63]
	v_mfma_f32_16x16x32_bf16 v[104:107], v[176:179], v[216:219], v[104:107]
	ds_read_b128 v[184:187], v167 offset:32768
	ds_read_b128 v[196:199], v167 offset:34816
	s_add_u32 m0, s68, 0x18000
	v_mfma_f32_16x16x32_bf16 v[108:111], v[176:179], v[248:251], v[108:111]
	global_load_lds_dwordx4 v134, s[64:65]
	v_mfma_f32_16x16x32_bf16 v[112:115], v[180:183], v[244:247], v[112:115]
	ds_read_b128 v[176:179], v154 offset:4096
	s_add_u32 m0, s68, 0x12000
	v_mfma_f32_16x16x32_bf16 v[116:119], v[180:183], v[212:215], v[116:119]
	global_load_lds_dwordx4 v148, s[62:63]
	ds_read_b128 v[200:203], v167 offset:36864
	ds_read_b128 v[240:243], v167 offset:38912
	v_mfma_f32_16x16x32_bf16 v[120:123], v[180:183], v[216:219], v[120:123]
	s_add_u32 m0, s68, 0x1a000
	v_mfma_f32_16x16x32_bf16 v[124:127], v[180:183], v[248:251], v[124:127]
	global_load_lds_dwordx4 v132, s[64:65]
	s_waitcnt lgkmcnt(4)
	v_mfma_f32_16x16x32_bf16 v[0:3], v[168:171], v[184:187], v[0:3]
	ds_read_b128 v[180:183], v154 offset:6144
	s_waitcnt lgkmcnt(4)
	v_mfma_f32_16x16x32_bf16 v[4:7], v[168:171], v[196:199], v[4:7]
	ds_read_b128 v[244:247], v192 offset:32768
	s_waitcnt lgkmcnt(3)
	v_mfma_f32_16x16x32_bf16 v[8:11], v[168:171], v[200:203], v[8:11]
	s_waitcnt lgkmcnt(2)
	v_mfma_f32_16x16x32_bf16 v[12:15], v[168:171], v[240:243], v[12:15]
	v_mfma_f32_16x16x32_bf16 v[16:19], v[172:175], v[184:187], v[16:19]
	ds_read_b128 v[168:171], v154 offset:8192
	v_mfma_f32_16x16x32_bf16 v[20:23], v[172:175], v[196:199], v[20:23]
	ds_read_b128 v[212:215], v192 offset:34816
	v_mfma_f32_16x16x32_bf16 v[24:27], v[172:175], v[200:203], v[24:27]
	v_mfma_f32_16x16x32_bf16 v[28:31], v[172:175], v[240:243], v[28:31]
	v_mfma_f32_16x16x32_bf16 v[32:35], v[176:179], v[184:187], v[32:35]
	ds_read_b128 v[172:175], v154 offset:10240
	v_mfma_f32_16x16x32_bf16 v[36:39], v[176:179], v[196:199], v[36:39]
	ds_read_b128 v[216:219], v192 offset:36864
	v_mfma_f32_16x16x32_bf16 v[40:43], v[176:179], v[200:203], v[40:43]
	s_add_u32 m0, s68, 0x14000
	v_mfma_f32_16x16x32_bf16 v[44:47], v[176:179], v[240:243], v[44:47]
	global_load_lds_dwordx4 v146, s[62:63]
	s_waitcnt lgkmcnt(5)
	v_mfma_f32_16x16x32_bf16 v[48:51], v[180:183], v[184:187], v[48:51]
	ds_read_b128 v[176:179], v154 offset:12288
	v_mfma_f32_16x16x32_bf16 v[52:55], v[180:183], v[196:199], v[52:55]
	ds_read_b128 v[248:251], v192 offset:38912
	v_mfma_f32_16x16x32_bf16 v[56:59], v[180:183], v[200:203], v[56:59]
	s_add_u32 m0, s68, 0x1c000
	v_mfma_f32_16x16x32_bf16 v[60:63], v[180:183], v[240:243], v[60:63]
	global_load_lds_dwordx4 v130, s[64:65]
	s_waitcnt lgkmcnt(5)
	v_mfma_f32_16x16x32_bf16 v[64:67], v[168:171], v[184:187], v[64:67]
	ds_read_b128 v[180:183], v154 offset:14336
	v_mfma_f32_16x16x32_bf16 v[68:71], v[168:171], v[196:199], v[68:71]
	v_mfma_f32_16x16x32_bf16 v[72:75], v[168:171], v[200:203], v[72:75]
	s_add_u32 m0, s68, 0x16000
	v_mfma_f32_16x16x32_bf16 v[76:79], v[168:171], v[240:243], v[76:79]
	global_load_lds_dwordx4 v144, s[62:63]
	s_waitcnt lgkmcnt(4)
	v_mfma_f32_16x16x32_bf16 v[80:83], v[172:175], v[184:187], v[80:83]
	ds_read_b128 v[168:171], v155
	v_mfma_f32_16x16x32_bf16 v[84:87], v[172:175], v[196:199], v[84:87]
	v_mfma_f32_16x16x32_bf16 v[88:91], v[172:175], v[200:203], v[88:91]
	s_add_u32 m0, s68, 0x1e000
	v_mfma_f32_16x16x32_bf16 v[92:95], v[172:175], v[240:243], v[92:95]
	global_load_lds_dwordx4 v152, s[64:65]
	s_add_u32 s62, s62, 0x80
	s_addc_u32 s63, s63, 0
	s_add_u32 s64, s64, 0x80
	s_addc_u32 s65, s65, 0
	s_waitcnt lgkmcnt(3)
	v_mfma_f32_16x16x32_bf16 v[96:99], v[176:179], v[184:187], v[96:99]
	ds_read_b128 v[172:175], v155 offset:2048
	v_mfma_f32_16x16x32_bf16 v[100:103], v[176:179], v[196:199], v[100:103]
	v_mfma_f32_16x16x32_bf16 v[104:107], v[176:179], v[200:203], v[104:107]
	v_mfma_f32_16x16x32_bf16 v[108:111], v[176:179], v[240:243], v[108:111]
	s_waitcnt lgkmcnt(2)
	v_mfma_f32_16x16x32_bf16 v[112:115], v[180:183], v[184:187], v[112:115]
	ds_read_b128 v[176:179], v155 offset:4096
	v_mfma_f32_16x16x32_bf16 v[116:119], v[180:183], v[196:199], v[116:119]
	v_mfma_f32_16x16x32_bf16 v[120:123], v[180:183], v[200:203], v[120:123]
	v_mfma_f32_16x16x32_bf16 v[124:127], v[180:183], v[240:243], v[124:127]
	s_waitcnt lgkmcnt(2)
	v_mfma_f32_16x16x32_bf16 v[0:3], v[168:171], v[244:247], v[0:3]
	ds_read_b128 v[180:183], v155 offset:6144
	v_mfma_f32_16x16x32_bf16 v[4:7], v[168:171], v[212:215], v[4:7]
	v_mfma_f32_16x16x32_bf16 v[8:11], v[168:171], v[216:219], v[8:11]
	v_mfma_f32_16x16x32_bf16 v[12:15], v[168:171], v[248:251], v[12:15]
	s_waitcnt lgkmcnt(2)
	v_mfma_f32_16x16x32_bf16 v[16:19], v[172:175], v[244:247], v[16:19]
	ds_read_b128 v[168:171], v155 offset:8192
	v_mfma_f32_16x16x32_bf16 v[20:23], v[172:175], v[212:215], v[20:23]
	v_mfma_f32_16x16x32_bf16 v[24:27], v[172:175], v[216:219], v[24:27]
	v_mfma_f32_16x16x32_bf16 v[28:31], v[172:175], v[248:251], v[28:31]
	s_waitcnt lgkmcnt(2)
	v_mfma_f32_16x16x32_bf16 v[32:35], v[176:179], v[244:247], v[32:35]
	ds_read_b128 v[172:175], v155 offset:10240
	v_mfma_f32_16x16x32_bf16 v[36:39], v[176:179], v[212:215], v[36:39]
	v_mfma_f32_16x16x32_bf16 v[40:43], v[176:179], v[216:219], v[40:43]
	v_mfma_f32_16x16x32_bf16 v[44:47], v[176:179], v[248:251], v[44:47]
	s_waitcnt lgkmcnt(2)
	v_mfma_f32_16x16x32_bf16 v[48:51], v[180:183], v[244:247], v[48:51]
	ds_read_b128 v[176:179], v155 offset:12288
	v_mfma_f32_16x16x32_bf16 v[52:55], v[180:183], v[212:215], v[52:55]
	v_mfma_f32_16x16x32_bf16 v[56:59], v[180:183], v[216:219], v[56:59]
	v_mfma_f32_16x16x32_bf16 v[60:63], v[180:183], v[248:251], v[60:63]
	s_waitcnt lgkmcnt(2)
	v_mfma_f32_16x16x32_bf16 v[64:67], v[168:171], v[244:247], v[64:67]
	ds_read_b128 v[180:183], v155 offset:14336
	v_mfma_f32_16x16x32_bf16 v[68:71], v[168:171], v[212:215], v[68:71]
	v_mfma_f32_16x16x32_bf16 v[72:75], v[168:171], v[216:219], v[72:75]
	v_mfma_f32_16x16x32_bf16 v[76:79], v[168:171], v[248:251], v[76:79]
	s_waitcnt lgkmcnt(2)
	v_mfma_f32_16x16x32_bf16 v[80:83], v[172:175], v[244:247], v[80:83]
	v_mfma_f32_16x16x32_bf16 v[84:87], v[172:175], v[212:215], v[84:87]
	v_mfma_f32_16x16x32_bf16 v[88:91], v[172:175], v[216:219], v[88:91]
	v_mfma_f32_16x16x32_bf16 v[92:95], v[172:175], v[248:251], v[92:95]
	s_waitcnt lgkmcnt(0)
	s_waitcnt vmcnt(0)
	s_barrier
	v_xor_b32_e32 v154, 0x10000, v154
	v_xor_b32_e32 v155, 0x10000, v155
	v_xor_b32_e32 v167, 0x10000, v167
	v_xor_b32_e32 v192, 0x10000, v192
	v_mfma_f32_16x16x32_bf16 v[96:99], v[176:179], v[244:247], v[96:99]
	ds_read_b128 v[168:171], v154
	ds_read_b128 v[172:175], v154 offset:2048
	v_mfma_f32_16x16x32_bf16 v[100:103], v[176:179], v[212:215], v[100:103]
	v_mfma_f32_16x16x32_bf16 v[104:107], v[176:179], v[216:219], v[104:107]
	ds_read_b128 v[184:187], v167 offset:32768
	ds_read_b128 v[196:199], v167 offset:34816
	v_mfma_f32_16x16x32_bf16 v[108:111], v[176:179], v[248:251], v[108:111]
	v_mfma_f32_16x16x32_bf16 v[112:115], v[180:183], v[244:247], v[112:115]
	ds_read_b128 v[176:179], v154 offset:4096
	v_mfma_f32_16x16x32_bf16 v[116:119], v[180:183], v[212:215], v[116:119]
	ds_read_b128 v[200:203], v167 offset:36864
	ds_read_b128 v[240:243], v167 offset:38912
	v_mfma_f32_16x16x32_bf16 v[120:123], v[180:183], v[216:219], v[120:123]
	v_mfma_f32_16x16x32_bf16 v[124:127], v[180:183], v[248:251], v[124:127]
	s_waitcnt lgkmcnt(4)
	v_mfma_f32_16x16x32_bf16 v[0:3], v[168:171], v[184:187], v[0:3]
	ds_read_b128 v[180:183], v154 offset:6144
	s_waitcnt lgkmcnt(4)
	v_mfma_f32_16x16x32_bf16 v[4:7], v[168:171], v[196:199], v[4:7]
	ds_read_b128 v[244:247], v192 offset:32768
	s_waitcnt lgkmcnt(3)
	v_mfma_f32_16x16x32_bf16 v[8:11], v[168:171], v[200:203], v[8:11]
	s_waitcnt lgkmcnt(2)
	v_mfma_f32_16x16x32_bf16 v[12:15], v[168:171], v[240:243], v[12:15]
	v_mfma_f32_16x16x32_bf16 v[16:19], v[172:175], v[184:187], v[16:19]
	ds_read_b128 v[168:171], v154 offset:8192
	v_mfma_f32_16x16x32_bf16 v[20:23], v[172:175], v[196:199], v[20:23]
	ds_read_b128 v[212:215], v192 offset:34816
	v_mfma_f32_16x16x32_bf16 v[24:27], v[172:175], v[200:203], v[24:27]
	v_mfma_f32_16x16x32_bf16 v[28:31], v[172:175], v[240:243], v[28:31]
	v_mfma_f32_16x16x32_bf16 v[32:35], v[176:179], v[184:187], v[32:35]
	ds_read_b128 v[172:175], v154 offset:10240
	v_mfma_f32_16x16x32_bf16 v[36:39], v[176:179], v[196:199], v[36:39]
	ds_read_b128 v[216:219], v192 offset:36864
	v_mfma_f32_16x16x32_bf16 v[40:43], v[176:179], v[200:203], v[40:43]
	v_mfma_f32_16x16x32_bf16 v[44:47], v[176:179], v[240:243], v[44:47]
	s_waitcnt lgkmcnt(5)
	v_mfma_f32_16x16x32_bf16 v[48:51], v[180:183], v[184:187], v[48:51]
	ds_read_b128 v[176:179], v154 offset:12288
	v_mfma_f32_16x16x32_bf16 v[52:55], v[180:183], v[196:199], v[52:55]
	ds_read_b128 v[248:251], v192 offset:38912
	v_mfma_f32_16x16x32_bf16 v[56:59], v[180:183], v[200:203], v[56:59]
	v_mfma_f32_16x16x32_bf16 v[60:63], v[180:183], v[240:243], v[60:63]
	s_waitcnt lgkmcnt(5)
	v_mfma_f32_16x16x32_bf16 v[64:67], v[168:171], v[184:187], v[64:67]
	ds_read_b128 v[180:183], v154 offset:14336
	v_mfma_f32_16x16x32_bf16 v[68:71], v[168:171], v[196:199], v[68:71]
	v_mfma_f32_16x16x32_bf16 v[72:75], v[168:171], v[200:203], v[72:75]
	v_mfma_f32_16x16x32_bf16 v[76:79], v[168:171], v[240:243], v[76:79]
	s_waitcnt lgkmcnt(4)
	v_mfma_f32_16x16x32_bf16 v[80:83], v[172:175], v[184:187], v[80:83]
	ds_read_b128 v[168:171], v155
	v_mfma_f32_16x16x32_bf16 v[84:87], v[172:175], v[196:199], v[84:87]
	v_mfma_f32_16x16x32_bf16 v[88:91], v[172:175], v[200:203], v[88:91]
	v_mfma_f32_16x16x32_bf16 v[92:95], v[172:175], v[240:243], v[92:95]
	s_waitcnt lgkmcnt(3)
	v_mfma_f32_16x16x32_bf16 v[96:99], v[176:179], v[184:187], v[96:99]
	ds_read_b128 v[172:175], v155 offset:2048
	v_mfma_f32_16x16x32_bf16 v[100:103], v[176:179], v[196:199], v[100:103]
	v_mfma_f32_16x16x32_bf16 v[104:107], v[176:179], v[200:203], v[104:107]
	v_mfma_f32_16x16x32_bf16 v[108:111], v[176:179], v[240:243], v[108:111]
	s_waitcnt lgkmcnt(2)
	v_mfma_f32_16x16x32_bf16 v[112:115], v[180:183], v[184:187], v[112:115]
	ds_read_b128 v[176:179], v155 offset:4096
	v_mfma_f32_16x16x32_bf16 v[116:119], v[180:183], v[196:199], v[116:119]
	v_mfma_f32_16x16x32_bf16 v[120:123], v[180:183], v[200:203], v[120:123]
	v_mfma_f32_16x16x32_bf16 v[124:127], v[180:183], v[240:243], v[124:127]
	s_waitcnt lgkmcnt(2)
	v_mfma_f32_16x16x32_bf16 v[0:3], v[168:171], v[244:247], v[0:3]
	ds_read_b128 v[180:183], v155 offset:6144
	v_mfma_f32_16x16x32_bf16 v[4:7], v[168:171], v[212:215], v[4:7]
	v_mfma_f32_16x16x32_bf16 v[8:11], v[168:171], v[216:219], v[8:11]
	v_mfma_f32_16x16x32_bf16 v[12:15], v[168:171], v[248:251], v[12:15]
	s_waitcnt lgkmcnt(2)
	v_mfma_f32_16x16x32_bf16 v[16:19], v[172:175], v[244:247], v[16:19]
	ds_read_b128 v[168:171], v155 offset:8192
	v_mfma_f32_16x16x32_bf16 v[20:23], v[172:175], v[212:215], v[20:23]
	v_mfma_f32_16x16x32_bf16 v[24:27], v[172:175], v[216:219], v[24:27]
	v_mfma_f32_16x16x32_bf16 v[28:31], v[172:175], v[248:251], v[28:31]
	s_waitcnt lgkmcnt(2)
	v_mfma_f32_16x16x32_bf16 v[32:35], v[176:179], v[244:247], v[32:35]
	ds_read_b128 v[172:175], v155 offset:10240
	v_mfma_f32_16x16x32_bf16 v[36:39], v[176:179], v[212:215], v[36:39]
	v_mfma_f32_16x16x32_bf16 v[40:43], v[176:179], v[216:219], v[40:43]
	v_mfma_f32_16x16x32_bf16 v[44:47], v[176:179], v[248:251], v[44:47]
	s_waitcnt lgkmcnt(2)
	v_mfma_f32_16x16x32_bf16 v[48:51], v[180:183], v[244:247], v[48:51]
	ds_read_b128 v[176:179], v155 offset:12288
	v_mfma_f32_16x16x32_bf16 v[52:55], v[180:183], v[212:215], v[52:55]
	v_mfma_f32_16x16x32_bf16 v[56:59], v[180:183], v[216:219], v[56:59]
	v_mfma_f32_16x16x32_bf16 v[60:63], v[180:183], v[248:251], v[60:63]
	s_waitcnt lgkmcnt(2)
	v_mfma_f32_16x16x32_bf16 v[64:67], v[168:171], v[244:247], v[64:67]
	ds_read_b128 v[180:183], v155 offset:14336
	v_mfma_f32_16x16x32_bf16 v[68:71], v[168:171], v[212:215], v[68:71]
	v_mfma_f32_16x16x32_bf16 v[72:75], v[168:171], v[216:219], v[72:75]
	v_mfma_f32_16x16x32_bf16 v[76:79], v[168:171], v[248:251], v[76:79]
	s_waitcnt lgkmcnt(2)
	v_mfma_f32_16x16x32_bf16 v[80:83], v[172:175], v[244:247], v[80:83]
	v_mfma_f32_16x16x32_bf16 v[84:87], v[172:175], v[212:215], v[84:87]
	v_mfma_f32_16x16x32_bf16 v[88:91], v[172:175], v[216:219], v[88:91]
	v_mfma_f32_16x16x32_bf16 v[92:95], v[172:175], v[248:251], v[92:95]
	s_waitcnt lgkmcnt(0)
	s_waitcnt vmcnt(0)
	s_barrier
	v_xor_b32_e32 v154, 0x10000, v154
	v_xor_b32_e32 v155, 0x10000, v155
	v_xor_b32_e32 v167, 0x10000, v167
	v_xor_b32_e32 v192, 0x10000, v192
	v_mfma_f32_16x16x32_bf16 v[96:99], v[176:179], v[244:247], v[96:99]
	v_mfma_f32_16x16x32_bf16 v[100:103], v[176:179], v[212:215], v[100:103]
	v_mfma_f32_16x16x32_bf16 v[104:107], v[176:179], v[216:219], v[104:107]
	v_mfma_f32_16x16x32_bf16 v[108:111], v[176:179], v[248:251], v[108:111]
	v_mfma_f32_16x16x32_bf16 v[112:115], v[180:183], v[244:247], v[112:115]
	v_mfma_f32_16x16x32_bf16 v[116:119], v[180:183], v[212:215], v[116:119]
	v_mfma_f32_16x16x32_bf16 v[120:123], v[180:183], v[216:219], v[120:123]
	v_mfma_f32_16x16x32_bf16 v[124:127], v[180:183], v[248:251], v[124:127]
	v_lshl_add_u64 v[142:143], s[2:3], 0, v[128:129]
	v_lshl_add_u32 v128, s54, 7, v158
	v_ashrrev_i32_e32 v129, 31, v128
	v_lshl_add_u64 v[144:145], v[128:129], 1, v[136:137]
	s_mov_b32 m0, s61
	s_mov_b32 s48, 0
	s_mov_b64 s[44:45], -1
	s_nop 7
	s_nop 3
	s_branch .LBB0_736

.LBB0_736:
	v_mov_b32_e32 v128, v195
	s_nop 0
	v_ashrrev_i32_e32 v129, 8, v128
	v_cmp_eq_u32_e32 vcc, s48, v129
	s_and_saveexec_b64 s[46:47], vcc
	s_cbranch_execz .LBB0_738
	v_bfe_i32 v129, v195, 7, 1
	v_and_b32_e32 v129, 0x10c00, v129
	v_and_b32_e32 v130, 0x4f, v195
	v_lshl_or_b32 v129, v130, 2, v129
	v_bfe_u32 v128, v195, 4, 2
	v_mul_u32_u24_e32 v128, 0x840, v128
	v_add_u32_e32 v128, v128, v129
	v_mov_b32_e32 v129, v128
	v_add_u32_e32 v130, 0x420, v128
	ds_write2_b32 v129, v0, v1 offset1:132
	ds_write2_b32 v130, v2, v3 offset1:132
	ds_write2_b32 v129, v4, v5 offset0:16 offset1:148
	ds_write2_b32 v130, v6, v7 offset0:16 offset1:148
	ds_write2_b32 v129, v8, v9 offset0:32 offset1:164
	ds_write2_b32 v130, v10, v11 offset0:32 offset1:164
	ds_write2_b32 v129, v12, v13 offset0:48 offset1:180
	ds_write2_b32 v130, v14, v15 offset0:48 offset1:180
	v_add_u32_e32 v129, 0x2100, v128
	v_add_u32_e32 v130, 0x2520, v128
	ds_write2_b32 v129, v16, v17 offset1:132
	ds_write2_b32 v130, v18, v19 offset1:132
	ds_write2_b32 v129, v20, v21 offset0:16 offset1:148
	ds_write2_b32 v130, v22, v23 offset0:16 offset1:148
	ds_write2_b32 v129, v24, v25 offset0:32 offset1:164
	ds_write2_b32 v130, v26, v27 offset0:32 offset1:164
	ds_write2_b32 v129, v28, v29 offset0:48 offset1:180
	ds_write2_b32 v130, v30, v31 offset0:48 offset1:180
	v_add_u32_e32 v129, 0x4200, v128
	v_add_u32_e32 v130, 0x4620, v128
	ds_write2_b32 v129, v32, v33 offset1:132
	ds_write2_b32 v130, v34, v35 offset1:132
	ds_write2_b32 v129, v36, v37 offset0:16 offset1:148
	ds_write2_b32 v130, v38, v39 offset0:16 offset1:148
	ds_write2_b32 v129, v40, v41 offset0:32 offset1:164
	ds_write2_b32 v130, v42, v43 offset0:32 offset1:164
	ds_write2_b32 v129, v44, v45 offset0:48 offset1:180
	ds_write2_b32 v130, v46, v47 offset0:48 offset1:180
	v_add_u32_e32 v129, 0x6300, v128
	v_add_u32_e32 v130, 0x6720, v128
	ds_write2_b32 v129, v48, v49 offset1:132
	ds_write2_b32 v130, v50, v51 offset1:132
	ds_write2_b32 v129, v52, v53 offset0:16 offset1:148
	ds_write2_b32 v130, v54, v55 offset0:16 offset1:148
	ds_write2_b32 v129, v56, v57 offset0:32 offset1:164
	ds_write2_b32 v130, v58, v59 offset0:32 offset1:164
	ds_write2_b32 v129, v60, v61 offset0:48 offset1:180
	ds_write2_b32 v130, v62, v63 offset0:48 offset1:180
	v_add_u32_e32 v129, 0x8400, v128
	v_add_u32_e32 v130, 0x8820, v128
	ds_write2_b32 v129, v64, v65 offset1:132
	ds_write2_b32 v130, v66, v67 offset1:132
	ds_write2_b32 v129, v68, v69 offset0:16 offset1:148
	ds_write2_b32 v130, v70, v71 offset0:16 offset1:148
	ds_write2_b32 v129, v72, v73 offset0:32 offset1:164
	ds_write2_b32 v130, v74, v75 offset0:32 offset1:164
	ds_write2_b32 v129, v76, v77 offset0:48 offset1:180
	ds_write2_b32 v130, v78, v79 offset0:48 offset1:180
	v_add_u32_e32 v129, 0xa500, v128
	v_add_u32_e32 v130, 0xa920, v128
	ds_write2_b32 v129, v80, v81 offset1:132
	ds_write2_b32 v130, v82, v83 offset1:132
	ds_write2_b32 v129, v84, v85 offset0:16 offset1:148
	ds_write2_b32 v130, v86, v87 offset0:16 offset1:148
	ds_write2_b32 v129, v88, v89 offset0:32 offset1:164
	ds_write2_b32 v130, v90, v91 offset0:32 offset1:164
	ds_write2_b32 v129, v92, v93 offset0:48 offset1:180
	ds_write2_b32 v130, v94, v95 offset0:48 offset1:180
	v_add_u32_e32 v129, 0xc600, v128
	v_add_u32_e32 v130, 0xca20, v128
	ds_write2_b32 v129, v96, v97 offset1:132
	ds_write2_b32 v130, v98, v99 offset1:132
	ds_write2_b32 v129, v100, v101 offset0:16 offset1:148
	ds_write2_b32 v130, v102, v103 offset0:16 offset1:148
	ds_write2_b32 v129, v104, v105 offset0:32 offset1:164
	ds_write2_b32 v130, v106, v107 offset0:32 offset1:164
	ds_write2_b32 v129, v108, v109 offset0:48 offset1:180
	ds_write2_b32 v130, v110, v111 offset0:48 offset1:180
	v_add_u32_e32 v129, 0xe700, v128
	v_add_u32_e32 v130, 0xeb20, v128
	ds_write2_b32 v129, v112, v113 offset1:132
	ds_write2_b32 v130, v114, v115 offset1:132
	ds_write2_b32 v129, v116, v117 offset0:16 offset1:148
	ds_write2_b32 v130, v118, v119 offset0:16 offset1:148
	ds_write2_b32 v129, v120, v121 offset0:32 offset1:164
	ds_write2_b32 v130, v122, v123 offset0:32 offset1:164
	ds_write2_b32 v129, v124, v125 offset0:48 offset1:180
	ds_write2_b32 v130, v126, v127 offset0:48 offset1:180
